# P4b+P6 epilogue: xor-16 row reduction via v_permlane16_swap instead of ds_bpermute, exposed lgkmcnt waits removed
# speedup vs baseline: 1.0017x; 1.0017x over previous
; __device__ __forceinline__ u16 f2bf(float f) { return (u16)(pack2(f, f) & 0xffffu); }
; __device__ __forceinline__ float sum32(float v) { v = dpp_row_sum16(v); v += __shfl_xor(v, 16); return v; }
; __device__ __forceinline__ int rowmap(int e, int lane) { return (e & 3) + 8 * (e >> 2) + 4 * (lane >> 5); }
; __device__ __forceinline__ void phase4b(const Params& p, char* smem) {
;     ...
; #pragma unroll
;     for (int i = 0; i < 2; i++)
; #pragma unroll
;       for (int e = 0; e < 16; e++) {
;         const int row = m0 + wm * 64 + i * 32 + rowmap(e, lane);
;         const float* xr = xrow(p, row);
;         float sq = 0.f;
; #pragma unroll
;         for (int j = 0; j < 2; j++) {
;           const int col = n0 + wn * 64 + j * 32 + (lane & 31);
;           float v = acc[i][j][e] + xr[col];
;           X1[(size_t)row * 1024 + col] = v;
;           ((u16*)smem)[(row - m0) * 136 + (col - n0)] = f2bf(v);
;           sq += v * v;
;         }
;         sq = sum32(sq);
;         if ((lane & 31) == 0) atomicAdd(&SSQ1[row], sq);
.LBB0_1297:
	s_nop 7
	v_accvgpr_read_b32 v48, a48
	v_accvgpr_read_b32 v49, a49
	v_accvgpr_read_b32 v50, a50
	v_accvgpr_read_b32 v51, a51
	v_accvgpr_read_b32 v52, a52
	v_accvgpr_read_b32 v53, a53
	v_accvgpr_read_b32 v54, a54
	v_accvgpr_read_b32 v55, a55
	v_accvgpr_read_b32 v56, a56
	v_accvgpr_read_b32 v57, a57
	v_accvgpr_read_b32 v58, a58
	v_accvgpr_read_b32 v59, a59
	v_accvgpr_read_b32 v60, a60
	v_accvgpr_read_b32 v61, a61
	v_accvgpr_read_b32 v62, a62
	v_accvgpr_read_b32 v63, a63
	v_accvgpr_read_b32 v32, a32
	v_accvgpr_read_b32 v33, a33
	v_accvgpr_read_b32 v34, a34
	v_accvgpr_read_b32 v35, a35
	v_accvgpr_read_b32 v36, a36
	v_accvgpr_read_b32 v37, a37
	v_accvgpr_read_b32 v38, a38
	v_accvgpr_read_b32 v39, a39
	v_accvgpr_read_b32 v40, a40
	v_accvgpr_read_b32 v41, a41
	v_accvgpr_read_b32 v42, a42
	v_accvgpr_read_b32 v43, a43
	v_accvgpr_read_b32 v44, a44
	v_accvgpr_read_b32 v45, a45
	v_accvgpr_read_b32 v46, a46
	v_accvgpr_read_b32 v47, a47
	v_accvgpr_read_b32 v16, a16
	v_accvgpr_read_b32 v17, a17
	v_accvgpr_read_b32 v18, a18
	v_accvgpr_read_b32 v19, a19
	v_accvgpr_read_b32 v20, a20
	v_accvgpr_read_b32 v21, a21
	v_accvgpr_read_b32 v22, a22
	v_accvgpr_read_b32 v23, a23
	v_accvgpr_read_b32 v24, a24
	v_accvgpr_read_b32 v25, a25
	v_accvgpr_read_b32 v26, a26
	v_accvgpr_read_b32 v27, a27
	v_accvgpr_read_b32 v28, a28
	v_accvgpr_read_b32 v29, a29
	v_accvgpr_read_b32 v30, a30
	v_accvgpr_read_b32 v31, a31
	v_accvgpr_read_b32 v0, a0
	v_accvgpr_read_b32 v1, a1
	v_accvgpr_read_b32 v2, a2
	v_accvgpr_read_b32 v3, a3
	v_accvgpr_read_b32 v4, a4
	v_accvgpr_read_b32 v5, a5
	v_accvgpr_read_b32 v6, a6
	v_accvgpr_read_b32 v7, a7
	v_accvgpr_read_b32 v8, a8
	v_accvgpr_read_b32 v9, a9
	v_accvgpr_read_b32 v10, a10
	v_accvgpr_read_b32 v11, a11
	v_accvgpr_read_b32 v12, a12
	v_accvgpr_read_b32 v13, a13
	v_accvgpr_read_b32 v14, a14
	v_accvgpr_read_b32 v15, a15
	v_add_u32_e32 v135, s6, v105
	v_or_b32_e32 v94, v135, v117
	v_cmp_le_i32_e32 vcc, s14, v94
	v_mov_b32_e32 v64, s42
	v_mov_b32_e32 v137, s40
	v_mov_b32_e32 v95, 0
	v_cndmask_b32_e32 v146, v137, v64, vcc
	v_mov_b32_e32 v64, s43
	v_mov_b32_e32 v137, s41
	v_or_b32_e32 v148, 32, v135
	v_cndmask_b32_e32 v147, v137, v64, vcc
	v_mov_b32_e32 v64, 0xfc000000
	v_cndmask_b32_e32 v92, 0, v64, vcc
	v_cndmask_b32_e64 v93, 0, -1, vcc
	v_lshl_add_u64 v[146:147], v[92:93], 0, v[146:147]
	v_or_b32_e32 v64, s45, v107
	v_lshlrev_b32_e32 v64, 2, v64
	v_lshl_add_u64 v[146:147], v[64:65], 0, v[146:147]
	v_add_lshl_u32 v94, v135, v117, 12
	v_lshl_add_u64 v[92:93], v[94:95], 0, v[146:147]
	global_load_dword a48, v[92:93], off
	global_load_dword a32, v[92:93], off offset:128
	v_add_lshl_u32 v94, v135, v120, 12
	v_lshl_add_u64 v[92:93], v[94:95], 0, v[146:147]
	global_load_dword a49, v[92:93], off
	global_load_dword a33, v[92:93], off offset:128
	v_add_lshl_u32 v94, v135, v121, 12
	v_lshl_add_u64 v[92:93], v[94:95], 0, v[146:147]
	global_load_dword a50, v[92:93], off
	global_load_dword a34, v[92:93], off offset:128
	v_add_lshl_u32 v94, v135, v122, 12
	v_lshl_add_u64 v[92:93], v[94:95], 0, v[146:147]
	global_load_dword a51, v[92:93], off
	global_load_dword a35, v[92:93], off offset:128
	v_add_lshl_u32 v94, v135, v123, 12
	v_lshl_add_u64 v[92:93], v[94:95], 0, v[146:147]
	global_load_dword a52, v[92:93], off
	global_load_dword a36, v[92:93], off offset:128
	v_add_lshl_u32 v94, v135, v124, 12
	v_lshl_add_u64 v[92:93], v[94:95], 0, v[146:147]
	global_load_dword a53, v[92:93], off
	global_load_dword a37, v[92:93], off offset:128
	v_add_lshl_u32 v94, v135, v125, 12
	v_lshl_add_u64 v[92:93], v[94:95], 0, v[146:147]
	global_load_dword a54, v[92:93], off
	global_load_dword a38, v[92:93], off offset:128
	v_add_lshl_u32 v94, v135, v126, 12
	v_lshl_add_u64 v[92:93], v[94:95], 0, v[146:147]
	global_load_dword a55, v[92:93], off
	global_load_dword a39, v[92:93], off offset:128
	v_add_lshl_u32 v94, v135, v127, 12
	v_lshl_add_u64 v[92:93], v[94:95], 0, v[146:147]
	global_load_dword a56, v[92:93], off
	global_load_dword a40, v[92:93], off offset:128
	v_add_lshl_u32 v94, v135, v128, 12
	v_lshl_add_u64 v[92:93], v[94:95], 0, v[146:147]
	global_load_dword a57, v[92:93], off
	global_load_dword a41, v[92:93], off offset:128
	v_add_lshl_u32 v94, v135, v129, 12
	v_lshl_add_u64 v[92:93], v[94:95], 0, v[146:147]
	global_load_dword a58, v[92:93], off
	global_load_dword a42, v[92:93], off offset:128
	v_add_lshl_u32 v94, v135, v130, 12
	v_lshl_add_u64 v[92:93], v[94:95], 0, v[146:147]
	global_load_dword a59, v[92:93], off
	global_load_dword a43, v[92:93], off offset:128
	v_add_lshl_u32 v94, v135, v131, 12
	v_lshl_add_u64 v[92:93], v[94:95], 0, v[146:147]
	global_load_dword a60, v[92:93], off
	global_load_dword a44, v[92:93], off offset:128
	v_add_lshl_u32 v94, v135, v132, 12
	v_lshl_add_u64 v[92:93], v[94:95], 0, v[146:147]
	global_load_dword a61, v[92:93], off
	global_load_dword a45, v[92:93], off offset:128
	v_add_lshl_u32 v94, v135, v133, 12
	v_lshl_add_u64 v[92:93], v[94:95], 0, v[146:147]
	global_load_dword a62, v[92:93], off
	global_load_dword a46, v[92:93], off offset:128
	v_add_lshl_u32 v94, v135, v134, 12
	v_lshl_add_u64 v[92:93], v[94:95], 0, v[146:147]
	global_load_dword a63, v[92:93], off
	global_load_dword a47, v[92:93], off offset:128
	v_add_lshl_u32 v94, v148, v117, 12
	v_lshl_add_u64 v[92:93], v[94:95], 0, v[146:147]
	global_load_dword a16, v[92:93], off
	global_load_dword a0, v[92:93], off offset:128
	v_add_lshl_u32 v94, v148, v120, 12
	v_lshl_add_u64 v[92:93], v[94:95], 0, v[146:147]
	global_load_dword a17, v[92:93], off
	global_load_dword a1, v[92:93], off offset:128
	v_add_lshl_u32 v94, v148, v121, 12
	v_lshl_add_u64 v[92:93], v[94:95], 0, v[146:147]
; __device__ __forceinline__ u16 f2bf(float f) { return (u16)(pack2(f, f) & 0xffffu); }
; __device__ __forceinline__ float sum32(float v) { v = dpp_row_sum16(v); v += __shfl_xor(v, 16); return v; }
; __device__ __forceinline__ int rowmap(int e, int lane) { return (e & 3) + 8 * (e >> 2) + 4 * (lane >> 5); }
; __device__ __forceinline__ void phase4b(const Params& p, char* smem) {
;     ...
; #pragma unroll
;     for (int i = 0; i < 2; i++)
; #pragma unroll
;       for (int e = 0; e < 16; e++) {
;         const int row = m0 + wm * 64 + i * 32 + rowmap(e, lane);
;         const float* xr = xrow(p, row);
;         float sq = 0.f;
; #pragma unroll
;         for (int j = 0; j < 2; j++) {
;           const int col = n0 + wn * 64 + j * 32 + (lane & 31);
;           float v = acc[i][j][e] + xr[col];
;           X1[(size_t)row * 1024 + col] = v;
;           ((u16*)smem)[(row - m0) * 136 + (col - n0)] = f2bf(v);
;           sq += v * v;
;         }
;         sq = sum32(sq);
;         if ((lane & 31) == 0) atomicAdd(&SSQ1[row], sq);
	global_load_dword a18, v[92:93], off
	global_load_dword a2, v[92:93], off offset:128
	v_add_lshl_u32 v94, v148, v122, 12
	v_lshl_add_u64 v[92:93], v[94:95], 0, v[146:147]
	global_load_dword a19, v[92:93], off
	global_load_dword a3, v[92:93], off offset:128
	v_add_lshl_u32 v94, v148, v123, 12
	v_lshl_add_u64 v[92:93], v[94:95], 0, v[146:147]
	global_load_dword a20, v[92:93], off
	global_load_dword a4, v[92:93], off offset:128
	v_add_lshl_u32 v94, v148, v124, 12
	v_lshl_add_u64 v[92:93], v[94:95], 0, v[146:147]
	global_load_dword a21, v[92:93], off
	global_load_dword a5, v[92:93], off offset:128
	v_add_lshl_u32 v94, v148, v125, 12
	v_lshl_add_u64 v[92:93], v[94:95], 0, v[146:147]
	global_load_dword a22, v[92:93], off
	global_load_dword a6, v[92:93], off offset:128
	v_add_lshl_u32 v94, v148, v126, 12
	v_lshl_add_u64 v[92:93], v[94:95], 0, v[146:147]
	global_load_dword a23, v[92:93], off
	global_load_dword a7, v[92:93], off offset:128
	v_add_lshl_u32 v94, v148, v127, 12
	v_lshl_add_u64 v[92:93], v[94:95], 0, v[146:147]
	global_load_dword a24, v[92:93], off
	global_load_dword a8, v[92:93], off offset:128
	v_add_lshl_u32 v94, v148, v128, 12
	v_lshl_add_u64 v[92:93], v[94:95], 0, v[146:147]
	global_load_dword a25, v[92:93], off
	global_load_dword a9, v[92:93], off offset:128
	v_add_lshl_u32 v94, v148, v129, 12
	v_lshl_add_u64 v[92:93], v[94:95], 0, v[146:147]
	global_load_dword a26, v[92:93], off
	global_load_dword a10, v[92:93], off offset:128
	v_add_lshl_u32 v94, v148, v130, 12
	v_lshl_add_u64 v[92:93], v[94:95], 0, v[146:147]
	global_load_dword a27, v[92:93], off
	global_load_dword a11, v[92:93], off offset:128
	v_add_lshl_u32 v94, v148, v131, 12
	v_lshl_add_u64 v[92:93], v[94:95], 0, v[146:147]
	global_load_dword a28, v[92:93], off
	global_load_dword a12, v[92:93], off offset:128
	v_add_lshl_u32 v94, v148, v132, 12
	v_lshl_add_u64 v[92:93], v[94:95], 0, v[146:147]
	global_load_dword a29, v[92:93], off
	global_load_dword a13, v[92:93], off offset:128
	v_add_lshl_u32 v94, v148, v133, 12
	v_lshl_add_u64 v[92:93], v[94:95], 0, v[146:147]
	global_load_dword a30, v[92:93], off
	global_load_dword a14, v[92:93], off offset:128
	v_add_lshl_u32 v94, v148, v134, 12
	v_lshl_add_u64 v[92:93], v[94:95], 0, v[146:147]
	global_load_dword a31, v[92:93], off
	global_load_dword a15, v[92:93], off offset:128
	s_waitcnt vmcnt(0)
	v_add_u32_e32 v135, s6, v105
	v_or_b32_e32 v94, v135, v117
	v_add_u32_e32 v64, 0xffffc000, v94
	v_cmp_gt_i32_e32 vcc, s14, v94
	v_ashrrev_i32_e32 v95, 31, v94
	v_mov_b32_e32 v137, s41
	v_cndmask_b32_e32 v92, v64, v94, vcc
	v_mov_b32_e32 v64, s43
	v_cndmask_b32_e32 v93, 0, v95, vcc
	v_cndmask_b32_e32 v147, v64, v137, vcc
	v_mov_b32_e32 v64, s42
	v_mov_b32_e32 v137, s40
	v_cndmask_b32_e32 v146, v64, v137, vcc
	v_lshlrev_b64 v[92:93], 12, v[92:93]
	v_or_b32_e32 v64, s45, v107
	v_lshl_add_u64 v[146:147], v[146:147], 0, v[92:93]
	v_lshlrev_b32_e32 v64, 2, v64
	v_lshl_add_u64 v[92:93], v[146:147], 0, v[64:65]
	v_accvgpr_read_b32 v137, a48
	v_lshlrev_b64 v[148:149], 12, v[94:95]
	v_add_u32_e32 v92, s45, v107
	v_lshl_add_u64 v[148:149], s[78:79], 0, v[148:149]
	v_mov_b32_e32 v93, v65
	v_lshlrev_b32_e32 v92, 2, v92
	v_lshl_add_u64 v[150:151], v[148:149], 0, v[64:65]
	v_lshl_add_u64 v[146:147], v[146:147], 0, v[92:93]
	v_lshl_add_u64 v[148:149], v[148:149], 0, v[92:93]
	v_add_f32_e32 v48, v48, v137
	global_store_dword v[150:151], v48, off
	v_accvgpr_read_b32 v137, a32
	v_cvt_pk_bf16_f32 v150, v48, s0
	v_subrev_u32_e32 v146, s6, v94
	v_mad_u64_u32 v[146:147], s[8:9], v146, s15, v[68:69]
	ds_write_b16 v146, v150
	v_add_f32_e32 v137, v32, v137
	v_mul_f32_e32 v32, v137, v137
	v_fmac_f32_e32 v32, v48, v48
	global_store_dword v[148:149], v137, off offset:128
	v_cvt_pk_bf16_f32 v137, v137, s0
	v_add_f32_dpp v32, v32, v32 quad_perm:[1,0,3,2] row_mask:0xf bank_mask:0xf bound_ctrl:1
	ds_write_b16 v146, v137 offset:64
	s_nop 0
	v_add_f32_dpp v32, v32, v32 quad_perm:[2,3,0,1] row_mask:0xf bank_mask:0xf bound_ctrl:1
	s_nop 1
	v_add_f32_dpp v32, v32, v32 row_half_mirror row_mask:0xf bank_mask:0xf bound_ctrl:1
	s_nop 1
	v_add_f32_dpp v32, v32, v32 row_mirror row_mask:0xf bank_mask:0xf bound_ctrl:1
	v_mov_b32_e32 v48, v32
	s_nop 1
	v_permlane16_swap_b32_e32 v48, v48
	s_and_saveexec_b64 s[8:9], s[4:5]
	s_cbranch_execz .LBB0_1299
	v_add_f32_e32 v32, v32, v48
	v_lshl_add_u64 v[94:95], v[94:95], 2, s[94:95]
	global_atomic_add_f32 v[94:95], v32, off
.LBB0_1299:
	s_or_b64 exec, exec, s[8:9]
	v_or_b32_e32 v94, v135, v120
	v_add_u32_e32 v32, 0xffffc000, v94
	v_cmp_gt_i32_e32 vcc, s14, v94
	v_ashrrev_i32_e32 v95, 31, v94
	v_mov_b32_e32 v48, s41
	v_cndmask_b32_e32 v146, v32, v94, vcc
	v_mov_b32_e32 v32, s43
	v_cndmask_b32_e32 v147, 0, v95, vcc
	v_cndmask_b32_e32 v149, v32, v48, vcc
	v_mov_b32_e32 v32, s42
	v_mov_b32_e32 v48, s40
	v_cndmask_b32_e32 v148, v32, v48, vcc
	v_lshlrev_b64 v[146:147], 12, v[146:147]
	v_lshl_add_u64 v[146:147], v[148:149], 0, v[146:147]
	v_lshl_add_u64 v[148:149], v[146:147], 0, v[64:65]
	v_accvgpr_read_b32 v32, a49
	v_lshlrev_b64 v[148:149], 12, v[94:95]
	v_lshl_add_u64 v[148:149], s[78:79], 0, v[148:149]
	v_lshl_add_u64 v[150:151], v[148:149], 0, v[64:65]
	v_add_f32_e32 v32, v49, v32
	global_store_dword v[150:151], v32, off
	v_lshl_add_u64 v[48:49], v[146:147], 0, v[92:93]
	v_accvgpr_read_b32 v137, a33
	v_subrev_u32_e32 v48, s6, v94
	v_mad_u64_u32 v[48:49], s[8:9], v48, s15, v[68:69]
	v_cvt_pk_bf16_f32 v146, v32, s0
	ds_write_b16 v48, v146
	v_lshl_add_u64 v[146:147], v[148:149], 0, v[92:93]
	v_add_f32_e32 v49, v33, v137
	v_mul_f32_e32 v33, v49, v49
	v_fmac_f32_e32 v33, v32, v32
	global_store_dword v[146:147], v49, off offset:128
	v_cvt_pk_bf16_f32 v49, v49, s0
	v_add_f32_dpp v32, v33, v33 quad_perm:[1,0,3,2] row_mask:0xf bank_mask:0xf bound_ctrl:1
	ds_write_b16 v48, v49 offset:64
	s_nop 0
	v_add_f32_dpp v32, v32, v32 quad_perm:[2,3,0,1] row_mask:0xf bank_mask:0xf bound_ctrl:1
	s_nop 1
	v_add_f32_dpp v32, v32, v32 row_half_mirror row_mask:0xf bank_mask:0xf bound_ctrl:1
	s_nop 1
	v_add_f32_dpp v32, v32, v32 row_mirror row_mask:0xf bank_mask:0xf bound_ctrl:1
	v_mov_b32_e32 v33, v32
	s_nop 1
	v_permlane16_swap_b32_e32 v33, v33
	s_and_saveexec_b64 s[8:9], s[4:5]
	s_cbranch_execz .LBB0_1301
	v_add_f32_e32 v48, v32, v33
	v_lshl_add_u64 v[32:33], v[94:95], 2, s[94:95]
	global_atomic_add_f32 v[32:33], v48, off
; __device__ __forceinline__ u16 f2bf(float f) { return (u16)(pack2(f, f) & 0xffffu); }
; __device__ __forceinline__ float sum32(float v) { v = dpp_row_sum16(v); v += __shfl_xor(v, 16); return v; }
; __device__ __forceinline__ int rowmap(int e, int lane) { return (e & 3) + 8 * (e >> 2) + 4 * (lane >> 5); }
; __device__ __forceinline__ void phase4b(const Params& p, char* smem) {
;     ...
; #pragma unroll
;     for (int i = 0; i < 2; i++)
; #pragma unroll
;       for (int e = 0; e < 16; e++) {
;         const int row = m0 + wm * 64 + i * 32 + rowmap(e, lane);
;         const float* xr = xrow(p, row);
;         float sq = 0.f;
; #pragma unroll
;         for (int j = 0; j < 2; j++) {
;           const int col = n0 + wn * 64 + j * 32 + (lane & 31);
;           float v = acc[i][j][e] + xr[col];
;           X1[(size_t)row * 1024 + col] = v;
;           ((u16*)smem)[(row - m0) * 136 + (col - n0)] = f2bf(v);
;           sq += v * v;
;         }
;         sq = sum32(sq);
;         if ((lane & 31) == 0) atomicAdd(&SSQ1[row], sq);
.LBB0_1301:
	s_or_b64 exec, exec, s[8:9]
	v_or_b32_e32 v32, v135, v121
	v_add_u32_e32 v48, 0xffffc000, v32
	v_ashrrev_i32_e32 v33, 31, v32
	v_cmp_gt_i32_e32 vcc, s14, v32
	v_mov_b32_e32 v93, s43
	v_mov_b32_e32 v94, s41
	v_cndmask_b32_e32 v49, 0, v33, vcc
	v_cndmask_b32_e32 v48, v48, v32, vcc
	v_cndmask_b32_e32 v95, v93, v94, vcc
	v_mov_b32_e32 v93, s42
	v_mov_b32_e32 v94, s40
	v_cndmask_b32_e32 v94, v93, v94, vcc
	v_lshlrev_b64 v[48:49], 12, v[48:49]
	v_lshl_add_u64 v[48:49], v[94:95], 0, v[48:49]
	v_lshl_add_u64 v[94:95], v[48:49], 0, v[64:65]
	v_accvgpr_read_b32 v137, a50
	v_lshlrev_b64 v[94:95], 12, v[32:33]
	v_lshl_add_u64 v[94:95], s[78:79], 0, v[94:95]
	v_mov_b32_e32 v93, v65
	v_lshl_add_u64 v[146:147], v[94:95], 0, v[64:65]
	v_lshl_add_u64 v[48:49], v[48:49], 0, v[92:93]
	v_lshl_add_u64 v[94:95], v[94:95], 0, v[92:93]
	v_add_f32_e32 v50, v50, v137
	global_store_dword v[146:147], v50, off
	v_accvgpr_read_b32 v48, a34
	v_subrev_u32_e32 v49, s6, v32
	v_mad_u64_u32 v[146:147], s[8:9], v49, s15, v[68:69]
	v_cvt_pk_bf16_f32 v137, v50, s0
	ds_write_b16 v146, v137
	v_add_f32_e32 v49, v34, v48
	v_mul_f32_e32 v34, v49, v49
	v_fmac_f32_e32 v34, v50, v50
	global_store_dword v[94:95], v49, off offset:128
	v_cvt_pk_bf16_f32 v49, v49, s0
	v_add_f32_dpp v34, v34, v34 quad_perm:[1,0,3,2] row_mask:0xf bank_mask:0xf bound_ctrl:1
	ds_write_b16 v146, v49 offset:64
	s_nop 0
	v_add_f32_dpp v34, v34, v34 quad_perm:[2,3,0,1] row_mask:0xf bank_mask:0xf bound_ctrl:1
	s_nop 1
	v_add_f32_dpp v34, v34, v34 row_half_mirror row_mask:0xf bank_mask:0xf bound_ctrl:1
	s_nop 1
	v_add_f32_dpp v34, v34, v34 row_mirror row_mask:0xf bank_mask:0xf bound_ctrl:1
	v_mov_b32_e32 v48, v34
	s_nop 1
	v_permlane16_swap_b32_e32 v48, v48
	s_and_saveexec_b64 s[8:9], s[4:5]
	s_cbranch_execz .LBB0_1303
	v_add_f32_e32 v34, v34, v48
	v_lshl_add_u64 v[32:33], v[32:33], 2, s[94:95]
	global_atomic_add_f32 v[32:33], v34, off
.LBB0_1303:
	s_or_b64 exec, exec, s[8:9]
	v_or_b32_e32 v32, v135, v122
	v_add_u32_e32 v34, 0xffffc000, v32
	v_cmp_gt_i32_e32 vcc, s14, v32
	v_ashrrev_i32_e32 v33, 31, v32
	v_mov_b32_e32 v50, s41
	v_cndmask_b32_e32 v48, v34, v32, vcc
	v_mov_b32_e32 v34, s43
	v_cndmask_b32_e32 v49, 0, v33, vcc
	v_cndmask_b32_e32 v95, v34, v50, vcc
	v_mov_b32_e32 v34, s42
	v_mov_b32_e32 v50, s40
	v_cndmask_b32_e32 v94, v34, v50, vcc
	v_lshlrev_b64 v[48:49], 12, v[48:49]
	v_lshl_add_u64 v[48:49], v[94:95], 0, v[48:49]
	v_lshl_add_u64 v[94:95], v[48:49], 0, v[64:65]
	v_accvgpr_read_b32 v34, a51
	v_lshlrev_b64 v[94:95], 12, v[32:33]
	v_lshl_add_u64 v[94:95], s[78:79], 0, v[94:95]
	v_lshl_add_u64 v[146:147], v[94:95], 0, v[64:65]
	v_lshl_add_u64 v[48:49], v[48:49], 0, v[92:93]
	v_add_f32_e32 v34, v51, v34
	global_store_dword v[146:147], v34, off
	v_accvgpr_read_b32 v50, a35
	v_subrev_u32_e32 v48, s6, v32
	v_mad_u64_u32 v[48:49], s[8:9], v48, s15, v[68:69]
	v_cvt_pk_bf16_f32 v51, v34, s0
	ds_write_b16 v48, v51
	v_add_f32_e32 v49, v35, v50
	v_mul_f32_e32 v35, v49, v49
	v_fmac_f32_e32 v35, v34, v34
	v_lshl_add_u64 v[50:51], v[94:95], 0, v[92:93]
	global_store_dword v[50:51], v49, off offset:128
	v_add_f32_dpp v34, v35, v35 quad_perm:[1,0,3,2] row_mask:0xf bank_mask:0xf bound_ctrl:1
	v_cvt_pk_bf16_f32 v49, v49, s0
	ds_write_b16 v48, v49 offset:64
	v_add_f32_dpp v34, v34, v34 quad_perm:[2,3,0,1] row_mask:0xf bank_mask:0xf bound_ctrl:1
	s_nop 1
	v_add_f32_dpp v34, v34, v34 row_half_mirror row_mask:0xf bank_mask:0xf bound_ctrl:1
	s_nop 1
	v_add_f32_dpp v34, v34, v34 row_mirror row_mask:0xf bank_mask:0xf bound_ctrl:1
	v_mov_b32_e32 v35, v34
	s_nop 1
	v_permlane16_swap_b32_e32 v35, v35
	s_and_saveexec_b64 s[8:9], s[4:5]
	s_cbranch_execz .LBB0_1305
	v_add_f32_e32 v34, v34, v35
	v_lshl_add_u64 v[32:33], v[32:33], 2, s[94:95]
	global_atomic_add_f32 v[32:33], v34, off
.LBB0_1305:
	s_or_b64 exec, exec, s[8:9]
	v_or_b32_e32 v32, v135, v123
	v_add_u32_e32 v34, 0xffffc000, v32
	v_ashrrev_i32_e32 v33, 31, v32
	v_cmp_gt_i32_e32 vcc, s14, v32
	v_mov_b32_e32 v48, s43
	v_mov_b32_e32 v49, s41
	v_cndmask_b32_e32 v35, 0, v33, vcc
	v_cndmask_b32_e32 v34, v34, v32, vcc
	v_cndmask_b32_e32 v49, v48, v49, vcc
	v_mov_b32_e32 v48, s42
	v_mov_b32_e32 v50, s40
	v_cndmask_b32_e32 v48, v48, v50, vcc
	v_lshlrev_b64 v[34:35], 12, v[34:35]
	v_lshl_add_u64 v[34:35], v[48:49], 0, v[34:35]
	v_lshl_add_u64 v[48:49], v[34:35], 0, v[64:65]
	v_accvgpr_read_b32 v94, a52
	v_lshlrev_b64 v[48:49], 12, v[32:33]
	v_lshl_add_u64 v[48:49], s[78:79], 0, v[48:49]
	v_mov_b32_e32 v93, v65
	v_lshl_add_u64 v[50:51], v[48:49], 0, v[64:65]
	v_lshl_add_u64 v[34:35], v[34:35], 0, v[92:93]
	v_lshl_add_u64 v[48:49], v[48:49], 0, v[92:93]
	v_add_f32_e32 v52, v52, v94
	global_store_dword v[50:51], v52, off
	v_accvgpr_read_b32 v34, a36
	v_subrev_u32_e32 v35, s6, v32
	v_mad_u64_u32 v[50:51], s[8:9], v35, s15, v[68:69]
	v_cvt_pk_bf16_f32 v94, v52, s0
	ds_write_b16 v50, v94
	v_add_f32_e32 v36, v36, v34
	v_mul_f32_e32 v34, v36, v36
	v_fmac_f32_e32 v34, v52, v52
	global_store_dword v[48:49], v36, off offset:128
	v_cvt_pk_bf16_f32 v36, v36, s0
	v_add_f32_dpp v34, v34, v34 quad_perm:[1,0,3,2] row_mask:0xf bank_mask:0xf bound_ctrl:1
	ds_write_b16 v50, v36 offset:64
	s_nop 0
	v_add_f32_dpp v34, v34, v34 quad_perm:[2,3,0,1] row_mask:0xf bank_mask:0xf bound_ctrl:1
	s_nop 1
	v_add_f32_dpp v34, v34, v34 row_half_mirror row_mask:0xf bank_mask:0xf bound_ctrl:1
	s_nop 1
	v_add_f32_dpp v34, v34, v34 row_mirror row_mask:0xf bank_mask:0xf bound_ctrl:1
	v_mov_b32_e32 v35, v34
	s_nop 1
	v_permlane16_swap_b32_e32 v35, v35
	s_and_saveexec_b64 s[8:9], s[4:5]
	s_cbranch_execz .LBB0_1307
	v_add_f32_e32 v34, v34, v35
	v_lshl_add_u64 v[32:33], v[32:33], 2, s[94:95]
	global_atomic_add_f32 v[32:33], v34, off
; __device__ __forceinline__ u16 f2bf(float f) { return (u16)(pack2(f, f) & 0xffffu); }
; __device__ __forceinline__ float sum32(float v) { v = dpp_row_sum16(v); v += __shfl_xor(v, 16); return v; }
; __device__ __forceinline__ int rowmap(int e, int lane) { return (e & 3) + 8 * (e >> 2) + 4 * (lane >> 5); }
; __device__ __forceinline__ void phase4b(const Params& p, char* smem) {
;     ...
; #pragma unroll
;     for (int i = 0; i < 2; i++)
; #pragma unroll
;       for (int e = 0; e < 16; e++) {
;         const int row = m0 + wm * 64 + i * 32 + rowmap(e, lane);
;         const float* xr = xrow(p, row);
;         float sq = 0.f;
; #pragma unroll
;         for (int j = 0; j < 2; j++) {
;           const int col = n0 + wn * 64 + j * 32 + (lane & 31);
;           float v = acc[i][j][e] + xr[col];
;           X1[(size_t)row * 1024 + col] = v;
;           ((u16*)smem)[(row - m0) * 136 + (col - n0)] = f2bf(v);
;           sq += v * v;
;         }
;         sq = sum32(sq);
;         if ((lane & 31) == 0) atomicAdd(&SSQ1[row], sq);
.LBB0_1307:
	s_or_b64 exec, exec, s[8:9]
	v_or_b32_e32 v32, v135, v124
	v_add_u32_e32 v34, 0xffffc000, v32
	v_ashrrev_i32_e32 v33, 31, v32
	v_cmp_gt_i32_e32 vcc, s14, v32
	v_mov_b32_e32 v36, s43
	v_mov_b32_e32 v48, s41
	v_cndmask_b32_e32 v35, 0, v33, vcc
	v_cndmask_b32_e32 v34, v34, v32, vcc
	v_cndmask_b32_e32 v49, v36, v48, vcc
	v_mov_b32_e32 v36, s42
	v_mov_b32_e32 v48, s40
	v_cndmask_b32_e32 v48, v36, v48, vcc
	v_lshlrev_b64 v[34:35], 12, v[34:35]
	v_lshl_add_u64 v[34:35], v[48:49], 0, v[34:35]
	v_lshl_add_u64 v[48:49], v[34:35], 0, v[64:65]
	v_accvgpr_read_b32 v36, a53
	v_lshlrev_b64 v[48:49], 12, v[32:33]
	v_lshl_add_u64 v[48:49], s[78:79], 0, v[48:49]
	v_lshl_add_u64 v[50:51], v[48:49], 0, v[64:65]
	v_lshl_add_u64 v[34:35], v[34:35], 0, v[92:93]
	v_add_f32_e32 v36, v53, v36
	global_store_dword v[50:51], v36, off
	v_accvgpr_read_b32 v34, a37
	v_subrev_u32_e32 v35, s6, v32
	v_mad_u64_u32 v[50:51], s[8:9], v35, s15, v[68:69]
	v_cvt_pk_bf16_f32 v52, v36, s0
	ds_write_b16 v50, v52
	v_add_f32_e32 v51, v37, v34
	v_mul_f32_e32 v34, v51, v51
	v_fmac_f32_e32 v34, v36, v36
	v_lshl_add_u64 v[36:37], v[48:49], 0, v[92:93]
	global_store_dword v[36:37], v51, off offset:128
	v_add_f32_dpp v34, v34, v34 quad_perm:[1,0,3,2] row_mask:0xf bank_mask:0xf bound_ctrl:1
	v_cvt_pk_bf16_f32 v36, v51, s0
	ds_write_b16 v50, v36 offset:64
	v_add_f32_dpp v34, v34, v34 quad_perm:[2,3,0,1] row_mask:0xf bank_mask:0xf bound_ctrl:1
	s_nop 1
	v_add_f32_dpp v34, v34, v34 row_half_mirror row_mask:0xf bank_mask:0xf bound_ctrl:1
	s_nop 1
	v_add_f32_dpp v34, v34, v34 row_mirror row_mask:0xf bank_mask:0xf bound_ctrl:1
	v_mov_b32_e32 v35, v34
	s_nop 1
	v_permlane16_swap_b32_e32 v35, v35
	s_and_saveexec_b64 s[8:9], s[4:5]
	s_cbranch_execz .LBB0_1309
	v_add_f32_e32 v34, v34, v35
	v_lshl_add_u64 v[32:33], v[32:33], 2, s[94:95]
	global_atomic_add_f32 v[32:33], v34, off
.LBB0_1309:
	s_or_b64 exec, exec, s[8:9]
	v_or_b32_e32 v32, v135, v125
	v_add_u32_e32 v34, 0xffffc000, v32
	v_ashrrev_i32_e32 v33, 31, v32
	v_cmp_gt_i32_e32 vcc, s14, v32
	v_mov_b32_e32 v36, s43
	v_mov_b32_e32 v37, s41
	v_cndmask_b32_e32 v35, 0, v33, vcc
	v_cndmask_b32_e32 v34, v34, v32, vcc
	v_cndmask_b32_e32 v37, v36, v37, vcc
	v_mov_b32_e32 v36, s42
	v_mov_b32_e32 v48, s40
	v_cndmask_b32_e32 v36, v36, v48, vcc
	v_lshlrev_b64 v[34:35], 12, v[34:35]
	v_lshl_add_u64 v[34:35], v[36:37], 0, v[34:35]
	v_lshl_add_u64 v[36:37], v[34:35], 0, v[64:65]
	v_accvgpr_read_b32 v50, a54
	v_lshlrev_b64 v[36:37], 12, v[32:33]
	v_lshl_add_u64 v[36:37], s[78:79], 0, v[36:37]
	v_mov_b32_e32 v93, v65
	v_lshl_add_u64 v[48:49], v[36:37], 0, v[64:65]
	v_lshl_add_u64 v[34:35], v[34:35], 0, v[92:93]
	v_lshl_add_u64 v[36:37], v[36:37], 0, v[92:93]
	v_add_f32_e32 v50, v54, v50
	global_store_dword v[48:49], v50, off
	v_accvgpr_read_b32 v34, a38
	v_subrev_u32_e32 v35, s6, v32
	v_mad_u64_u32 v[48:49], s[8:9], v35, s15, v[68:69]
	v_cvt_pk_bf16_f32 v51, v50, s0
	ds_write_b16 v48, v51
	v_add_f32_e32 v38, v38, v34
	v_mul_f32_e32 v34, v38, v38
	v_fmac_f32_e32 v34, v50, v50
	global_store_dword v[36:37], v38, off offset:128
	v_cvt_pk_bf16_f32 v36, v38, s0
	v_add_f32_dpp v34, v34, v34 quad_perm:[1,0,3,2] row_mask:0xf bank_mask:0xf bound_ctrl:1
	ds_write_b16 v48, v36 offset:64
	s_nop 0
	v_add_f32_dpp v34, v34, v34 quad_perm:[2,3,0,1] row_mask:0xf bank_mask:0xf bound_ctrl:1
	s_nop 1
	v_add_f32_dpp v34, v34, v34 row_half_mirror row_mask:0xf bank_mask:0xf bound_ctrl:1
	s_nop 1
	v_add_f32_dpp v34, v34, v34 row_mirror row_mask:0xf bank_mask:0xf bound_ctrl:1
	v_mov_b32_e32 v35, v34
	s_nop 1
	v_permlane16_swap_b32_e32 v35, v35
	s_and_saveexec_b64 s[8:9], s[4:5]
	s_cbranch_execz .LBB0_1311
	v_add_f32_e32 v34, v34, v35
	v_lshl_add_u64 v[32:33], v[32:33], 2, s[94:95]
	global_atomic_add_f32 v[32:33], v34, off
.LBB0_1311:
	s_or_b64 exec, exec, s[8:9]
	v_or_b32_e32 v32, v135, v126
	v_add_u32_e32 v34, 0xffffc000, v32
	v_ashrrev_i32_e32 v33, 31, v32
	v_cmp_gt_i32_e32 vcc, s14, v32
	v_mov_b32_e32 v36, s43
	v_mov_b32_e32 v37, s41
	v_cndmask_b32_e32 v35, 0, v33, vcc
	v_cndmask_b32_e32 v34, v34, v32, vcc
	v_cndmask_b32_e32 v37, v36, v37, vcc
	v_mov_b32_e32 v36, s42
	v_mov_b32_e32 v38, s40
	v_cndmask_b32_e32 v36, v36, v38, vcc
	v_lshlrev_b64 v[34:35], 12, v[34:35]
	v_lshl_add_u64 v[34:35], v[36:37], 0, v[34:35]
	v_lshl_add_u64 v[36:37], v[34:35], 0, v[64:65]
	v_accvgpr_read_b32 v38, a55
	v_lshlrev_b64 v[36:37], 12, v[32:33]
	v_lshl_add_u64 v[36:37], s[78:79], 0, v[36:37]
	v_lshl_add_u64 v[48:49], v[36:37], 0, v[64:65]
	v_lshl_add_u64 v[34:35], v[34:35], 0, v[92:93]
	v_lshl_add_u64 v[36:37], v[36:37], 0, v[92:93]
	v_add_f32_e32 v38, v55, v38
	global_store_dword v[48:49], v38, off
	v_accvgpr_read_b32 v34, a39
	v_subrev_u32_e32 v35, s6, v32
	v_mad_u64_u32 v[48:49], s[8:9], v35, s15, v[68:69]
	v_cvt_pk_bf16_f32 v50, v38, s0
	ds_write_b16 v48, v50
	v_add_f32_e32 v39, v39, v34
	v_mul_f32_e32 v34, v39, v39
	v_fmac_f32_e32 v34, v38, v38
	global_store_dword v[36:37], v39, off offset:128
	v_cvt_pk_bf16_f32 v36, v39, s0
	v_add_f32_dpp v34, v34, v34 quad_perm:[1,0,3,2] row_mask:0xf bank_mask:0xf bound_ctrl:1
	ds_write_b16 v48, v36 offset:64
	s_nop 0
	v_add_f32_dpp v34, v34, v34 quad_perm:[2,3,0,1] row_mask:0xf bank_mask:0xf bound_ctrl:1
	s_nop 1
	v_add_f32_dpp v34, v34, v34 row_half_mirror row_mask:0xf bank_mask:0xf bound_ctrl:1
	s_nop 1
	v_add_f32_dpp v34, v34, v34 row_mirror row_mask:0xf bank_mask:0xf bound_ctrl:1
	v_mov_b32_e32 v35, v34
	s_nop 1
	v_permlane16_swap_b32_e32 v35, v35
	s_and_saveexec_b64 s[8:9], s[4:5]
	s_cbranch_execz .LBB0_1313
	v_add_f32_e32 v34, v34, v35
	v_lshl_add_u64 v[32:33], v[32:33], 2, s[94:95]
	global_atomic_add_f32 v[32:33], v34, off
; __device__ __forceinline__ u16 f2bf(float f) { return (u16)(pack2(f, f) & 0xffffu); }
; __device__ __forceinline__ float sum32(float v) { v = dpp_row_sum16(v); v += __shfl_xor(v, 16); return v; }
; __device__ __forceinline__ int rowmap(int e, int lane) { return (e & 3) + 8 * (e >> 2) + 4 * (lane >> 5); }
; __device__ __forceinline__ void phase4b(const Params& p, char* smem) {
;     ...
; #pragma unroll
;     for (int i = 0; i < 2; i++)
; #pragma unroll
;       for (int e = 0; e < 16; e++) {
;         const int row = m0 + wm * 64 + i * 32 + rowmap(e, lane);
;         const float* xr = xrow(p, row);
;         float sq = 0.f;
; #pragma unroll
;         for (int j = 0; j < 2; j++) {
;           const int col = n0 + wn * 64 + j * 32 + (lane & 31);
;           float v = acc[i][j][e] + xr[col];
;           X1[(size_t)row * 1024 + col] = v;
;           ((u16*)smem)[(row - m0) * 136 + (col - n0)] = f2bf(v);
;           sq += v * v;
;         }
;         sq = sum32(sq);
;         if ((lane & 31) == 0) atomicAdd(&SSQ1[row], sq);
.LBB0_1313:
	s_or_b64 exec, exec, s[8:9]
	v_or_b32_e32 v32, v135, v127
	v_add_u32_e32 v34, 0xffffc000, v32
	v_ashrrev_i32_e32 v33, 31, v32
	v_cmp_gt_i32_e32 vcc, s14, v32
	v_mov_b32_e32 v36, s43
	v_mov_b32_e32 v37, s41
	v_cndmask_b32_e32 v35, 0, v33, vcc
	v_cndmask_b32_e32 v34, v34, v32, vcc
	v_cndmask_b32_e32 v37, v36, v37, vcc
	v_mov_b32_e32 v36, s42
	v_mov_b32_e32 v38, s40
	v_cndmask_b32_e32 v36, v36, v38, vcc
	v_lshlrev_b64 v[34:35], 12, v[34:35]
	v_lshl_add_u64 v[34:35], v[36:37], 0, v[34:35]
	v_lshl_add_u64 v[36:37], v[34:35], 0, v[64:65]
	v_accvgpr_read_b32 v48, a56
	v_lshlrev_b64 v[36:37], 12, v[32:33]
	v_lshl_add_u64 v[36:37], s[78:79], 0, v[36:37]
	v_mov_b32_e32 v93, v65
	v_lshl_add_u64 v[38:39], v[36:37], 0, v[64:65]
	v_lshl_add_u64 v[34:35], v[34:35], 0, v[92:93]
	v_lshl_add_u64 v[36:37], v[36:37], 0, v[92:93]
	v_add_f32_e32 v48, v56, v48
	global_store_dword v[38:39], v48, off
	v_accvgpr_read_b32 v34, a40
	v_subrev_u32_e32 v35, s6, v32
	v_mad_u64_u32 v[38:39], s[8:9], v35, s15, v[68:69]
	v_cvt_pk_bf16_f32 v49, v48, s0
	ds_write_b16 v38, v49
	v_add_f32_e32 v39, v40, v34
	v_mul_f32_e32 v34, v39, v39
	v_fmac_f32_e32 v34, v48, v48
	global_store_dword v[36:37], v39, off offset:128
	v_cvt_pk_bf16_f32 v36, v39, s0
	v_add_f32_dpp v34, v34, v34 quad_perm:[1,0,3,2] row_mask:0xf bank_mask:0xf bound_ctrl:1
	ds_write_b16 v38, v36 offset:64
	s_nop 0
	v_add_f32_dpp v34, v34, v34 quad_perm:[2,3,0,1] row_mask:0xf bank_mask:0xf bound_ctrl:1
	s_nop 1
	v_add_f32_dpp v34, v34, v34 row_half_mirror row_mask:0xf bank_mask:0xf bound_ctrl:1
	s_nop 1
	v_add_f32_dpp v34, v34, v34 row_mirror row_mask:0xf bank_mask:0xf bound_ctrl:1
	v_mov_b32_e32 v35, v34
	s_nop 1
	v_permlane16_swap_b32_e32 v35, v35
	s_and_saveexec_b64 s[8:9], s[4:5]
	s_cbranch_execz .LBB0_1315
	v_add_f32_e32 v34, v34, v35
	v_lshl_add_u64 v[32:33], v[32:33], 2, s[94:95]
	global_atomic_add_f32 v[32:33], v34, off
.LBB0_1315:
	s_or_b64 exec, exec, s[8:9]
	v_or_b32_e32 v32, v135, v128
	v_add_u32_e32 v34, 0xffffc000, v32
	v_ashrrev_i32_e32 v33, 31, v32
	v_cmp_gt_i32_e32 vcc, s14, v32
	v_mov_b32_e32 v36, s43
	v_mov_b32_e32 v37, s41
	v_cndmask_b32_e32 v35, 0, v33, vcc
	v_cndmask_b32_e32 v34, v34, v32, vcc
	v_cndmask_b32_e32 v37, v36, v37, vcc
	v_mov_b32_e32 v36, s42
	v_mov_b32_e32 v38, s40
	v_cndmask_b32_e32 v36, v36, v38, vcc
	v_lshlrev_b64 v[34:35], 12, v[34:35]
	v_lshl_add_u64 v[34:35], v[36:37], 0, v[34:35]
	v_lshl_add_u64 v[36:37], v[34:35], 0, v[64:65]
	v_accvgpr_read_b32 v40, a57
	v_lshlrev_b64 v[36:37], 12, v[32:33]
	v_lshl_add_u64 v[36:37], s[78:79], 0, v[36:37]
	v_lshl_add_u64 v[38:39], v[36:37], 0, v[64:65]
	v_lshl_add_u64 v[34:35], v[34:35], 0, v[92:93]
	v_lshl_add_u64 v[36:37], v[36:37], 0, v[92:93]
	v_add_f32_e32 v40, v57, v40
	global_store_dword v[38:39], v40, off
	v_accvgpr_read_b32 v34, a41
	v_subrev_u32_e32 v35, s6, v32
	v_mad_u64_u32 v[38:39], s[8:9], v35, s15, v[68:69]
	v_cvt_pk_bf16_f32 v48, v40, s0
	ds_write_b16 v38, v48
	v_add_f32_e32 v39, v41, v34
	v_mul_f32_e32 v34, v39, v39
	v_fmac_f32_e32 v34, v40, v40
	global_store_dword v[36:37], v39, off offset:128
	v_cvt_pk_bf16_f32 v36, v39, s0
	v_add_f32_dpp v34, v34, v34 quad_perm:[1,0,3,2] row_mask:0xf bank_mask:0xf bound_ctrl:1
	ds_write_b16 v38, v36 offset:64
	s_nop 0
	v_add_f32_dpp v34, v34, v34 quad_perm:[2,3,0,1] row_mask:0xf bank_mask:0xf bound_ctrl:1
	s_nop 1
	v_add_f32_dpp v34, v34, v34 row_half_mirror row_mask:0xf bank_mask:0xf bound_ctrl:1
	s_nop 1
	v_add_f32_dpp v34, v34, v34 row_mirror row_mask:0xf bank_mask:0xf bound_ctrl:1
	v_mov_b32_e32 v35, v34
	s_nop 1
	v_permlane16_swap_b32_e32 v35, v35
	s_and_saveexec_b64 s[8:9], s[4:5]
	s_cbranch_execz .LBB0_1317
	v_add_f32_e32 v34, v34, v35
	v_lshl_add_u64 v[32:33], v[32:33], 2, s[94:95]
	global_atomic_add_f32 v[32:33], v34, off
.LBB0_1317:
	s_or_b64 exec, exec, s[8:9]
	v_or_b32_e32 v32, v135, v129
	v_add_u32_e32 v34, 0xffffc000, v32
	v_ashrrev_i32_e32 v33, 31, v32
	v_cmp_gt_i32_e32 vcc, s14, v32
	v_mov_b32_e32 v36, s43
	v_mov_b32_e32 v37, s41
	v_cndmask_b32_e32 v35, 0, v33, vcc
	v_cndmask_b32_e32 v34, v34, v32, vcc
	v_cndmask_b32_e32 v37, v36, v37, vcc
	v_mov_b32_e32 v36, s42
	v_mov_b32_e32 v38, s40
	v_cndmask_b32_e32 v36, v36, v38, vcc
	v_lshlrev_b64 v[34:35], 12, v[34:35]
	v_lshl_add_u64 v[34:35], v[36:37], 0, v[34:35]
	v_lshl_add_u64 v[36:37], v[34:35], 0, v[64:65]
	v_accvgpr_read_b32 v40, a58
	v_lshlrev_b64 v[36:37], 12, v[32:33]
	v_lshl_add_u64 v[36:37], s[78:79], 0, v[36:37]
	v_mov_b32_e32 v93, v65
	v_lshl_add_u64 v[38:39], v[36:37], 0, v[64:65]
	v_lshl_add_u64 v[34:35], v[34:35], 0, v[92:93]
	v_lshl_add_u64 v[36:37], v[36:37], 0, v[92:93]
	v_add_f32_e32 v40, v58, v40
	global_store_dword v[38:39], v40, off
	v_accvgpr_read_b32 v34, a42
	v_subrev_u32_e32 v35, s6, v32
	v_mad_u64_u32 v[38:39], s[8:9], v35, s15, v[68:69]
	v_cvt_pk_bf16_f32 v41, v40, s0
	ds_write_b16 v38, v41
	v_add_f32_e32 v39, v42, v34
	v_mul_f32_e32 v34, v39, v39
	v_fmac_f32_e32 v34, v40, v40
	global_store_dword v[36:37], v39, off offset:128
	v_cvt_pk_bf16_f32 v36, v39, s0
	v_add_f32_dpp v34, v34, v34 quad_perm:[1,0,3,2] row_mask:0xf bank_mask:0xf bound_ctrl:1
	ds_write_b16 v38, v36 offset:64
	s_nop 0
	v_add_f32_dpp v34, v34, v34 quad_perm:[2,3,0,1] row_mask:0xf bank_mask:0xf bound_ctrl:1
	s_nop 1
	v_add_f32_dpp v34, v34, v34 row_half_mirror row_mask:0xf bank_mask:0xf bound_ctrl:1
	s_nop 1
	v_add_f32_dpp v34, v34, v34 row_mirror row_mask:0xf bank_mask:0xf bound_ctrl:1
	v_mov_b32_e32 v35, v34
	s_nop 1
	v_permlane16_swap_b32_e32 v35, v35
	s_and_saveexec_b64 s[8:9], s[4:5]
	s_cbranch_execz .LBB0_1319
	v_add_f32_e32 v34, v34, v35
	v_lshl_add_u64 v[32:33], v[32:33], 2, s[94:95]
	global_atomic_add_f32 v[32:33], v34, off
; __device__ __forceinline__ u16 f2bf(float f) { return (u16)(pack2(f, f) & 0xffffu); }
; __device__ __forceinline__ float sum32(float v) { v = dpp_row_sum16(v); v += __shfl_xor(v, 16); return v; }
; __device__ __forceinline__ int rowmap(int e, int lane) { return (e & 3) + 8 * (e >> 2) + 4 * (lane >> 5); }
; __device__ __forceinline__ void phase4b(const Params& p, char* smem) {
;     ...
; #pragma unroll
;     for (int i = 0; i < 2; i++)
; #pragma unroll
;       for (int e = 0; e < 16; e++) {
;         const int row = m0 + wm * 64 + i * 32 + rowmap(e, lane);
;         const float* xr = xrow(p, row);
;         float sq = 0.f;
; #pragma unroll
;         for (int j = 0; j < 2; j++) {
;           const int col = n0 + wn * 64 + j * 32 + (lane & 31);
;           float v = acc[i][j][e] + xr[col];
;           X1[(size_t)row * 1024 + col] = v;
;           ((u16*)smem)[(row - m0) * 136 + (col - n0)] = f2bf(v);
;           sq += v * v;
;         }
;         sq = sum32(sq);
;         if ((lane & 31) == 0) atomicAdd(&SSQ1[row], sq);
.LBB0_1319:
	s_or_b64 exec, exec, s[8:9]
	v_or_b32_e32 v32, v135, v130
	v_add_u32_e32 v34, 0xffffc000, v32
	v_ashrrev_i32_e32 v33, 31, v32
	v_cmp_gt_i32_e32 vcc, s14, v32
	v_mov_b32_e32 v36, s43
	v_mov_b32_e32 v37, s41
	v_cndmask_b32_e32 v35, 0, v33, vcc
	v_cndmask_b32_e32 v34, v34, v32, vcc
	v_cndmask_b32_e32 v37, v36, v37, vcc
	v_mov_b32_e32 v36, s42
	v_mov_b32_e32 v38, s40
	v_cndmask_b32_e32 v36, v36, v38, vcc
	v_lshlrev_b64 v[34:35], 12, v[34:35]
	v_lshl_add_u64 v[34:35], v[36:37], 0, v[34:35]
	v_lshl_add_u64 v[36:37], v[34:35], 0, v[64:65]
	v_accvgpr_read_b32 v40, a59
	v_lshlrev_b64 v[36:37], 12, v[32:33]
	v_lshl_add_u64 v[36:37], s[78:79], 0, v[36:37]
	v_lshl_add_u64 v[38:39], v[36:37], 0, v[64:65]
	v_lshl_add_u64 v[34:35], v[34:35], 0, v[92:93]
	v_lshl_add_u64 v[36:37], v[36:37], 0, v[92:93]
	v_add_f32_e32 v40, v59, v40
	global_store_dword v[38:39], v40, off
	v_accvgpr_read_b32 v34, a43
	v_subrev_u32_e32 v35, s6, v32
	v_mad_u64_u32 v[38:39], s[8:9], v35, s15, v[68:69]
	v_cvt_pk_bf16_f32 v41, v40, s0
	ds_write_b16 v38, v41
	v_add_f32_e32 v39, v43, v34
	v_mul_f32_e32 v34, v39, v39
	v_fmac_f32_e32 v34, v40, v40
	global_store_dword v[36:37], v39, off offset:128
	v_cvt_pk_bf16_f32 v36, v39, s0
	v_add_f32_dpp v34, v34, v34 quad_perm:[1,0,3,2] row_mask:0xf bank_mask:0xf bound_ctrl:1
	ds_write_b16 v38, v36 offset:64
	s_nop 0
	v_add_f32_dpp v34, v34, v34 quad_perm:[2,3,0,1] row_mask:0xf bank_mask:0xf bound_ctrl:1
	s_nop 1
	v_add_f32_dpp v34, v34, v34 row_half_mirror row_mask:0xf bank_mask:0xf bound_ctrl:1
	s_nop 1
	v_add_f32_dpp v34, v34, v34 row_mirror row_mask:0xf bank_mask:0xf bound_ctrl:1
	v_mov_b32_e32 v35, v34
	s_nop 1
	v_permlane16_swap_b32_e32 v35, v35
	s_and_saveexec_b64 s[8:9], s[4:5]
	s_cbranch_execz .LBB0_1321
	v_add_f32_e32 v34, v34, v35
	v_lshl_add_u64 v[32:33], v[32:33], 2, s[94:95]
	global_atomic_add_f32 v[32:33], v34, off
.LBB0_1321:
	s_or_b64 exec, exec, s[8:9]
	v_or_b32_e32 v32, v135, v131
	v_add_u32_e32 v34, 0xffffc000, v32
	v_ashrrev_i32_e32 v33, 31, v32
	v_cmp_gt_i32_e32 vcc, s14, v32
	v_mov_b32_e32 v36, s43
	v_mov_b32_e32 v37, s41
	v_cndmask_b32_e32 v35, 0, v33, vcc
	v_cndmask_b32_e32 v34, v34, v32, vcc
	v_cndmask_b32_e32 v37, v36, v37, vcc
	v_mov_b32_e32 v36, s42
	v_mov_b32_e32 v38, s40
	v_cndmask_b32_e32 v36, v36, v38, vcc
	v_lshlrev_b64 v[34:35], 12, v[34:35]
	v_lshl_add_u64 v[34:35], v[36:37], 0, v[34:35]
	v_lshl_add_u64 v[36:37], v[34:35], 0, v[64:65]
	v_accvgpr_read_b32 v40, a60
	v_lshlrev_b64 v[36:37], 12, v[32:33]
	v_lshl_add_u64 v[36:37], s[78:79], 0, v[36:37]
	v_mov_b32_e32 v93, v65
	v_lshl_add_u64 v[38:39], v[36:37], 0, v[64:65]
	v_lshl_add_u64 v[34:35], v[34:35], 0, v[92:93]
	v_lshl_add_u64 v[36:37], v[36:37], 0, v[92:93]
	v_add_f32_e32 v40, v60, v40
	global_store_dword v[38:39], v40, off
	v_accvgpr_read_b32 v34, a44
	v_subrev_u32_e32 v35, s6, v32
	v_mad_u64_u32 v[38:39], s[8:9], v35, s15, v[68:69]
	v_cvt_pk_bf16_f32 v41, v40, s0
	ds_write_b16 v38, v41
	v_add_f32_e32 v39, v44, v34
	v_mul_f32_e32 v34, v39, v39
	v_fmac_f32_e32 v34, v40, v40
	global_store_dword v[36:37], v39, off offset:128
	v_cvt_pk_bf16_f32 v36, v39, s0
	v_add_f32_dpp v34, v34, v34 quad_perm:[1,0,3,2] row_mask:0xf bank_mask:0xf bound_ctrl:1
	ds_write_b16 v38, v36 offset:64
	s_nop 0
	v_add_f32_dpp v34, v34, v34 quad_perm:[2,3,0,1] row_mask:0xf bank_mask:0xf bound_ctrl:1
	s_nop 1
	v_add_f32_dpp v34, v34, v34 row_half_mirror row_mask:0xf bank_mask:0xf bound_ctrl:1
	s_nop 1
	v_add_f32_dpp v34, v34, v34 row_mirror row_mask:0xf bank_mask:0xf bound_ctrl:1
	v_mov_b32_e32 v35, v34
	s_nop 1
	v_permlane16_swap_b32_e32 v35, v35
	s_and_saveexec_b64 s[8:9], s[4:5]
	s_cbranch_execz .LBB0_1323
	v_add_f32_e32 v34, v34, v35
	v_lshl_add_u64 v[32:33], v[32:33], 2, s[94:95]
	global_atomic_add_f32 v[32:33], v34, off
.LBB0_1323:
	s_or_b64 exec, exec, s[8:9]
	v_or_b32_e32 v32, v135, v132
	v_add_u32_e32 v34, 0xffffc000, v32
	v_ashrrev_i32_e32 v33, 31, v32
	v_cmp_gt_i32_e32 vcc, s14, v32
	v_mov_b32_e32 v36, s43
	v_mov_b32_e32 v37, s41
	v_cndmask_b32_e32 v35, 0, v33, vcc
	v_cndmask_b32_e32 v34, v34, v32, vcc
	v_cndmask_b32_e32 v37, v36, v37, vcc
	v_mov_b32_e32 v36, s42
	v_mov_b32_e32 v38, s40
	v_cndmask_b32_e32 v36, v36, v38, vcc
	v_lshlrev_b64 v[34:35], 12, v[34:35]
	v_lshl_add_u64 v[34:35], v[36:37], 0, v[34:35]
	v_lshl_add_u64 v[36:37], v[34:35], 0, v[64:65]
	v_accvgpr_read_b32 v40, a61
	v_lshlrev_b64 v[36:37], 12, v[32:33]
	v_lshl_add_u64 v[36:37], s[78:79], 0, v[36:37]
	v_lshl_add_u64 v[38:39], v[36:37], 0, v[64:65]
	v_lshl_add_u64 v[34:35], v[34:35], 0, v[92:93]
	v_lshl_add_u64 v[36:37], v[36:37], 0, v[92:93]
	v_add_f32_e32 v40, v61, v40
	global_store_dword v[38:39], v40, off
	v_accvgpr_read_b32 v34, a45
	v_subrev_u32_e32 v35, s6, v32
	v_mad_u64_u32 v[38:39], s[8:9], v35, s15, v[68:69]
	v_cvt_pk_bf16_f32 v41, v40, s0
	ds_write_b16 v38, v41
	v_add_f32_e32 v39, v45, v34
	v_mul_f32_e32 v34, v39, v39
	v_fmac_f32_e32 v34, v40, v40
	global_store_dword v[36:37], v39, off offset:128
	v_cvt_pk_bf16_f32 v36, v39, s0
	v_add_f32_dpp v34, v34, v34 quad_perm:[1,0,3,2] row_mask:0xf bank_mask:0xf bound_ctrl:1
	ds_write_b16 v38, v36 offset:64
	s_nop 0
	v_add_f32_dpp v34, v34, v34 quad_perm:[2,3,0,1] row_mask:0xf bank_mask:0xf bound_ctrl:1
	s_nop 1
	v_add_f32_dpp v34, v34, v34 row_half_mirror row_mask:0xf bank_mask:0xf bound_ctrl:1
	s_nop 1
	v_add_f32_dpp v34, v34, v34 row_mirror row_mask:0xf bank_mask:0xf bound_ctrl:1
	v_mov_b32_e32 v35, v34
	s_nop 1
	v_permlane16_swap_b32_e32 v35, v35
	s_and_saveexec_b64 s[8:9], s[4:5]
	s_cbranch_execz .LBB0_1325
	v_add_f32_e32 v34, v34, v35
	v_lshl_add_u64 v[32:33], v[32:33], 2, s[94:95]
	global_atomic_add_f32 v[32:33], v34, off
; __device__ __forceinline__ u16 f2bf(float f) { return (u16)(pack2(f, f) & 0xffffu); }
; __device__ __forceinline__ float sum32(float v) { v = dpp_row_sum16(v); v += __shfl_xor(v, 16); return v; }
; __device__ __forceinline__ int rowmap(int e, int lane) { return (e & 3) + 8 * (e >> 2) + 4 * (lane >> 5); }
; __device__ __forceinline__ void phase4b(const Params& p, char* smem) {
;     ...
; #pragma unroll
;     for (int i = 0; i < 2; i++)
; #pragma unroll
;       for (int e = 0; e < 16; e++) {
;         const int row = m0 + wm * 64 + i * 32 + rowmap(e, lane);
;         const float* xr = xrow(p, row);
;         float sq = 0.f;
; #pragma unroll
;         for (int j = 0; j < 2; j++) {
;           const int col = n0 + wn * 64 + j * 32 + (lane & 31);
;           float v = acc[i][j][e] + xr[col];
;           X1[(size_t)row * 1024 + col] = v;
;           ((u16*)smem)[(row - m0) * 136 + (col - n0)] = f2bf(v);
;           sq += v * v;
;         }
;         sq = sum32(sq);
;         if ((lane & 31) == 0) atomicAdd(&SSQ1[row], sq);
.LBB0_1325:
	s_or_b64 exec, exec, s[8:9]
	v_or_b32_e32 v32, v135, v133
	v_add_u32_e32 v34, 0xffffc000, v32
	v_ashrrev_i32_e32 v33, 31, v32
	v_cmp_gt_i32_e32 vcc, s14, v32
	v_mov_b32_e32 v36, s43
	v_mov_b32_e32 v37, s41
	v_cndmask_b32_e32 v35, 0, v33, vcc
	v_cndmask_b32_e32 v34, v34, v32, vcc
	v_cndmask_b32_e32 v37, v36, v37, vcc
	v_mov_b32_e32 v36, s42
	v_mov_b32_e32 v38, s40
	v_cndmask_b32_e32 v36, v36, v38, vcc
	v_lshlrev_b64 v[34:35], 12, v[34:35]
	v_lshl_add_u64 v[34:35], v[36:37], 0, v[34:35]
	v_lshl_add_u64 v[36:37], v[34:35], 0, v[64:65]
	v_accvgpr_read_b32 v40, a62
	v_lshlrev_b64 v[36:37], 12, v[32:33]
	v_lshl_add_u64 v[36:37], s[78:79], 0, v[36:37]
	v_mov_b32_e32 v93, v65
	v_lshl_add_u64 v[38:39], v[36:37], 0, v[64:65]
	v_lshl_add_u64 v[34:35], v[34:35], 0, v[92:93]
	v_lshl_add_u64 v[36:37], v[36:37], 0, v[92:93]
	v_add_f32_e32 v40, v62, v40
	global_store_dword v[38:39], v40, off
	v_accvgpr_read_b32 v34, a46
	v_subrev_u32_e32 v35, s6, v32
	v_mad_u64_u32 v[38:39], s[8:9], v35, s15, v[68:69]
	v_cvt_pk_bf16_f32 v41, v40, s0
	ds_write_b16 v38, v41
	v_add_f32_e32 v39, v46, v34
	v_mul_f32_e32 v34, v39, v39
	v_fmac_f32_e32 v34, v40, v40
	global_store_dword v[36:37], v39, off offset:128
	v_cvt_pk_bf16_f32 v36, v39, s0
	v_add_f32_dpp v34, v34, v34 quad_perm:[1,0,3,2] row_mask:0xf bank_mask:0xf bound_ctrl:1
	ds_write_b16 v38, v36 offset:64
	s_nop 0
	v_add_f32_dpp v34, v34, v34 quad_perm:[2,3,0,1] row_mask:0xf bank_mask:0xf bound_ctrl:1
	s_nop 1
	v_add_f32_dpp v34, v34, v34 row_half_mirror row_mask:0xf bank_mask:0xf bound_ctrl:1
	s_nop 1
	v_add_f32_dpp v34, v34, v34 row_mirror row_mask:0xf bank_mask:0xf bound_ctrl:1
	v_mov_b32_e32 v35, v34
	s_nop 1
	v_permlane16_swap_b32_e32 v35, v35
	s_and_saveexec_b64 s[8:9], s[4:5]
	s_cbranch_execz .LBB0_1327
	v_add_f32_e32 v34, v34, v35
	v_lshl_add_u64 v[32:33], v[32:33], 2, s[94:95]
	global_atomic_add_f32 v[32:33], v34, off
.LBB0_1327:
	s_or_b64 exec, exec, s[8:9]
	v_or_b32_e32 v32, v135, v134
	v_add_u32_e32 v34, 0xffffc000, v32
	v_ashrrev_i32_e32 v33, 31, v32
	v_cmp_gt_i32_e32 vcc, s14, v32
	v_mov_b32_e32 v36, s43
	v_mov_b32_e32 v37, s41
	v_cndmask_b32_e32 v35, 0, v33, vcc
	v_cndmask_b32_e32 v34, v34, v32, vcc
	v_cndmask_b32_e32 v37, v36, v37, vcc
	v_mov_b32_e32 v36, s42
	v_mov_b32_e32 v38, s40
	v_cndmask_b32_e32 v36, v36, v38, vcc
	v_lshlrev_b64 v[34:35], 12, v[34:35]
	v_lshl_add_u64 v[34:35], v[36:37], 0, v[34:35]
	v_lshl_add_u64 v[36:37], v[34:35], 0, v[64:65]
	v_accvgpr_read_b32 v40, a63
	v_lshlrev_b64 v[36:37], 12, v[32:33]
	v_lshl_add_u64 v[36:37], s[78:79], 0, v[36:37]
	v_lshl_add_u64 v[38:39], v[36:37], 0, v[64:65]
	v_lshl_add_u64 v[34:35], v[34:35], 0, v[92:93]
	v_lshl_add_u64 v[36:37], v[36:37], 0, v[92:93]
	v_add_f32_e32 v40, v63, v40
	global_store_dword v[38:39], v40, off
	v_accvgpr_read_b32 v34, a47
	v_subrev_u32_e32 v35, s6, v32
	v_mad_u64_u32 v[38:39], s[8:9], v35, s15, v[68:69]
	v_cvt_pk_bf16_f32 v41, v40, s0
	ds_write_b16 v38, v41
	v_add_f32_e32 v39, v47, v34
	v_mul_f32_e32 v34, v39, v39
	v_fmac_f32_e32 v34, v40, v40
	global_store_dword v[36:37], v39, off offset:128
	v_cvt_pk_bf16_f32 v36, v39, s0
	v_add_f32_dpp v34, v34, v34 quad_perm:[1,0,3,2] row_mask:0xf bank_mask:0xf bound_ctrl:1
	ds_write_b16 v38, v36 offset:64
	s_nop 0
	v_add_f32_dpp v34, v34, v34 quad_perm:[2,3,0,1] row_mask:0xf bank_mask:0xf bound_ctrl:1
	s_nop 1
	v_add_f32_dpp v34, v34, v34 row_half_mirror row_mask:0xf bank_mask:0xf bound_ctrl:1
	s_nop 1
	v_add_f32_dpp v34, v34, v34 row_mirror row_mask:0xf bank_mask:0xf bound_ctrl:1
	v_mov_b32_e32 v35, v34
	s_nop 1
	v_permlane16_swap_b32_e32 v35, v35
	s_and_saveexec_b64 s[8:9], s[4:5]
	s_cbranch_execz .LBB0_1329
	v_add_f32_e32 v34, v34, v35
	v_lshl_add_u64 v[32:33], v[32:33], 2, s[94:95]
	global_atomic_add_f32 v[32:33], v34, off
.LBB0_1329:
	s_or_b64 exec, exec, s[8:9]
	v_or_b32_e32 v34, 32, v135
	v_or_b32_e32 v32, v34, v117
	v_add_u32_e32 v35, 0xffffc000, v32
	v_cmp_gt_i32_e32 vcc, s14, v32
	v_ashrrev_i32_e32 v33, 31, v32
	v_mov_b32_e32 v38, s41
	v_cndmask_b32_e32 v36, v35, v32, vcc
	v_mov_b32_e32 v35, s43
	v_cndmask_b32_e32 v37, 0, v33, vcc
	v_cndmask_b32_e32 v39, v35, v38, vcc
	v_mov_b32_e32 v35, s42
	v_mov_b32_e32 v38, s40
	v_cndmask_b32_e32 v38, v35, v38, vcc
	v_lshlrev_b64 v[36:37], 12, v[36:37]
	v_lshl_add_u64 v[36:37], v[38:39], 0, v[36:37]
	v_lshl_add_u64 v[38:39], v[36:37], 0, v[64:65]
	v_accvgpr_read_b32 v35, a16
	v_lshlrev_b64 v[38:39], 12, v[32:33]
	v_lshl_add_u64 v[38:39], s[78:79], 0, v[38:39]
	v_mov_b32_e32 v93, v65
	v_lshl_add_u64 v[40:41], v[38:39], 0, v[64:65]
	v_lshl_add_u64 v[36:37], v[36:37], 0, v[92:93]
	v_lshl_add_u64 v[38:39], v[38:39], 0, v[92:93]
	v_add_f32_e32 v16, v16, v35
	global_store_dword v[40:41], v16, off
	v_accvgpr_read_b32 v35, a0
	v_cvt_pk_bf16_f32 v40, v16, s0
	v_subrev_u32_e32 v36, s6, v32
	v_mad_u64_u32 v[36:37], s[8:9], v36, s15, v[68:69]
	ds_write_b16 v36, v40
	v_add_f32_e32 v35, v0, v35
	v_mul_f32_e32 v0, v35, v35
	v_fmac_f32_e32 v0, v16, v16
	global_store_dword v[38:39], v35, off offset:128
	v_cvt_pk_bf16_f32 v35, v35, s0
	v_add_f32_dpp v0, v0, v0 quad_perm:[1,0,3,2] row_mask:0xf bank_mask:0xf bound_ctrl:1
	ds_write_b16 v36, v35 offset:64
	s_nop 0
	v_add_f32_dpp v0, v0, v0 quad_perm:[2,3,0,1] row_mask:0xf bank_mask:0xf bound_ctrl:1
	s_nop 1
	v_add_f32_dpp v0, v0, v0 row_half_mirror row_mask:0xf bank_mask:0xf bound_ctrl:1
	s_nop 1
	v_add_f32_dpp v0, v0, v0 row_mirror row_mask:0xf bank_mask:0xf bound_ctrl:1
	v_mov_b32_e32 v16, v0
	s_nop 1
	v_permlane16_swap_b32_e32 v16, v16
	s_and_saveexec_b64 s[8:9], s[4:5]
	s_cbranch_execz .LBB0_1331
	v_add_f32_e32 v0, v0, v16
	v_lshl_add_u64 v[32:33], v[32:33], 2, s[94:95]
	global_atomic_add_f32 v[32:33], v0, off
; __device__ __forceinline__ u16 f2bf(float f) { return (u16)(pack2(f, f) & 0xffffu); }
; __device__ __forceinline__ float sum32(float v) { v = dpp_row_sum16(v); v += __shfl_xor(v, 16); return v; }
; __device__ __forceinline__ int rowmap(int e, int lane) { return (e & 3) + 8 * (e >> 2) + 4 * (lane >> 5); }
; __device__ __forceinline__ void phase4b(const Params& p, char* smem) {
;     ...
; #pragma unroll
;     for (int i = 0; i < 2; i++)
; #pragma unroll
;       for (int e = 0; e < 16; e++) {
;         const int row = m0 + wm * 64 + i * 32 + rowmap(e, lane);
;         const float* xr = xrow(p, row);
;         float sq = 0.f;
; #pragma unroll
;         for (int j = 0; j < 2; j++) {
;           const int col = n0 + wn * 64 + j * 32 + (lane & 31);
;           float v = acc[i][j][e] + xr[col];
;           X1[(size_t)row * 1024 + col] = v;
;           ((u16*)smem)[(row - m0) * 136 + (col - n0)] = f2bf(v);
;           sq += v * v;
;         }
;         sq = sum32(sq);
;         if ((lane & 31) == 0) atomicAdd(&SSQ1[row], sq);
.LBB0_1331:
	s_or_b64 exec, exec, s[8:9]
	v_or_b32_e32 v32, v34, v120
	v_add_u32_e32 v0, 0xffffc000, v32
	v_cmp_gt_i32_e32 vcc, s14, v32
	v_ashrrev_i32_e32 v33, 31, v32
	v_mov_b32_e32 v16, s41
	v_cndmask_b32_e32 v36, v0, v32, vcc
	v_mov_b32_e32 v0, s43
	v_cndmask_b32_e32 v37, 0, v33, vcc
	v_cndmask_b32_e32 v39, v0, v16, vcc
	v_mov_b32_e32 v0, s42
	v_mov_b32_e32 v16, s40
	v_cndmask_b32_e32 v38, v0, v16, vcc
	v_lshlrev_b64 v[36:37], 12, v[36:37]
	v_lshl_add_u64 v[36:37], v[38:39], 0, v[36:37]
	v_lshl_add_u64 v[38:39], v[36:37], 0, v[64:65]
	v_accvgpr_read_b32 v0, a17
	v_lshlrev_b64 v[38:39], 12, v[32:33]
	v_lshl_add_u64 v[38:39], s[78:79], 0, v[38:39]
	v_lshl_add_u64 v[40:41], v[38:39], 0, v[64:65]
	v_add_f32_e32 v0, v17, v0
	global_store_dword v[40:41], v0, off
	v_lshl_add_u64 v[16:17], v[36:37], 0, v[92:93]
	v_accvgpr_read_b32 v35, a1
	v_subrev_u32_e32 v16, s6, v32
	v_mad_u64_u32 v[16:17], s[8:9], v16, s15, v[68:69]
	v_cvt_pk_bf16_f32 v36, v0, s0
	ds_write_b16 v16, v36
	v_lshl_add_u64 v[36:37], v[38:39], 0, v[92:93]
	v_add_f32_e32 v17, v1, v35
	v_mul_f32_e32 v1, v17, v17
	v_fmac_f32_e32 v1, v0, v0
	global_store_dword v[36:37], v17, off offset:128
	v_cvt_pk_bf16_f32 v17, v17, s0
	v_add_f32_dpp v0, v1, v1 quad_perm:[1,0,3,2] row_mask:0xf bank_mask:0xf bound_ctrl:1
	ds_write_b16 v16, v17 offset:64
	s_nop 0
	v_add_f32_dpp v0, v0, v0 quad_perm:[2,3,0,1] row_mask:0xf bank_mask:0xf bound_ctrl:1
	s_nop 1
	v_add_f32_dpp v0, v0, v0 row_half_mirror row_mask:0xf bank_mask:0xf bound_ctrl:1
	s_nop 1
	v_add_f32_dpp v0, v0, v0 row_mirror row_mask:0xf bank_mask:0xf bound_ctrl:1
	v_mov_b32_e32 v1, v0
	s_nop 1
	v_permlane16_swap_b32_e32 v1, v1
	s_and_saveexec_b64 s[8:9], s[4:5]
	s_cbranch_execz .LBB0_1333
	v_add_f32_e32 v16, v0, v1
	v_lshl_add_u64 v[0:1], v[32:33], 2, s[94:95]
	global_atomic_add_f32 v[0:1], v16, off
.LBB0_1333:
	s_or_b64 exec, exec, s[8:9]
	v_or_b32_e32 v0, v34, v121
	v_add_u32_e32 v16, 0xffffc000, v0
	v_ashrrev_i32_e32 v1, 31, v0
	v_cmp_gt_i32_e32 vcc, s14, v0
	v_mov_b32_e32 v32, s43
	v_mov_b32_e32 v33, s41
	v_cndmask_b32_e32 v17, 0, v1, vcc
	v_cndmask_b32_e32 v16, v16, v0, vcc
	v_cndmask_b32_e32 v33, v32, v33, vcc
	v_mov_b32_e32 v32, s42
	v_mov_b32_e32 v35, s40
	v_cndmask_b32_e32 v32, v32, v35, vcc
	v_lshlrev_b64 v[16:17], 12, v[16:17]
	v_lshl_add_u64 v[16:17], v[32:33], 0, v[16:17]
	v_lshl_add_u64 v[32:33], v[16:17], 0, v[64:65]
	v_accvgpr_read_b32 v35, a18
	v_lshlrev_b64 v[32:33], 12, v[0:1]
	v_lshl_add_u64 v[32:33], s[78:79], 0, v[32:33]
	v_mov_b32_e32 v93, v65
	v_lshl_add_u64 v[36:37], v[32:33], 0, v[64:65]
	v_lshl_add_u64 v[16:17], v[16:17], 0, v[92:93]
	v_lshl_add_u64 v[32:33], v[32:33], 0, v[92:93]
	v_add_f32_e32 v18, v18, v35
	global_store_dword v[36:37], v18, off
	v_accvgpr_read_b32 v16, a2
	v_subrev_u32_e32 v17, s6, v0
	v_mad_u64_u32 v[36:37], s[8:9], v17, s15, v[68:69]
	v_cvt_pk_bf16_f32 v35, v18, s0
	ds_write_b16 v36, v35
	v_add_f32_e32 v17, v2, v16
	v_mul_f32_e32 v2, v17, v17
	v_fmac_f32_e32 v2, v18, v18
	global_store_dword v[32:33], v17, off offset:128
	v_cvt_pk_bf16_f32 v17, v17, s0
	v_add_f32_dpp v2, v2, v2 quad_perm:[1,0,3,2] row_mask:0xf bank_mask:0xf bound_ctrl:1
	ds_write_b16 v36, v17 offset:64
	s_nop 0
	v_add_f32_dpp v2, v2, v2 quad_perm:[2,3,0,1] row_mask:0xf bank_mask:0xf bound_ctrl:1
	s_nop 1
	v_add_f32_dpp v2, v2, v2 row_half_mirror row_mask:0xf bank_mask:0xf bound_ctrl:1
	s_nop 1
	v_add_f32_dpp v2, v2, v2 row_mirror row_mask:0xf bank_mask:0xf bound_ctrl:1
	v_mov_b32_e32 v16, v2
	s_nop 1
	v_permlane16_swap_b32_e32 v16, v16
	s_and_saveexec_b64 s[8:9], s[4:5]
	s_cbranch_execz .LBB0_1335
	v_add_f32_e32 v2, v2, v16
	v_lshl_add_u64 v[0:1], v[0:1], 2, s[94:95]
	global_atomic_add_f32 v[0:1], v2, off
.LBB0_1335:
	s_or_b64 exec, exec, s[8:9]
	v_or_b32_e32 v0, v34, v122
	v_add_u32_e32 v2, 0xffffc000, v0
	v_cmp_gt_i32_e32 vcc, s14, v0
	v_ashrrev_i32_e32 v1, 31, v0
	v_mov_b32_e32 v18, s41
	v_cndmask_b32_e32 v16, v2, v0, vcc
	v_mov_b32_e32 v2, s43
	v_cndmask_b32_e32 v17, 0, v1, vcc
	v_cndmask_b32_e32 v33, v2, v18, vcc
	v_mov_b32_e32 v2, s42
	v_mov_b32_e32 v18, s40
	v_cndmask_b32_e32 v32, v2, v18, vcc
	v_lshlrev_b64 v[16:17], 12, v[16:17]
	v_lshl_add_u64 v[16:17], v[32:33], 0, v[16:17]
	v_lshl_add_u64 v[32:33], v[16:17], 0, v[64:65]
	v_accvgpr_read_b32 v2, a19
	v_lshlrev_b64 v[32:33], 12, v[0:1]
	v_lshl_add_u64 v[32:33], s[78:79], 0, v[32:33]
	v_lshl_add_u64 v[36:37], v[32:33], 0, v[64:65]
	v_lshl_add_u64 v[16:17], v[16:17], 0, v[92:93]
	v_add_f32_e32 v2, v19, v2
	global_store_dword v[36:37], v2, off
	v_accvgpr_read_b32 v18, a3
	v_subrev_u32_e32 v16, s6, v0
	v_mad_u64_u32 v[16:17], s[8:9], v16, s15, v[68:69]
	v_cvt_pk_bf16_f32 v19, v2, s0
	ds_write_b16 v16, v19
	v_add_f32_e32 v17, v3, v18
	v_mul_f32_e32 v3, v17, v17
	v_fmac_f32_e32 v3, v2, v2
	v_lshl_add_u64 v[18:19], v[32:33], 0, v[92:93]
	global_store_dword v[18:19], v17, off offset:128
	v_add_f32_dpp v2, v3, v3 quad_perm:[1,0,3,2] row_mask:0xf bank_mask:0xf bound_ctrl:1
	v_cvt_pk_bf16_f32 v17, v17, s0
	ds_write_b16 v16, v17 offset:64
	v_add_f32_dpp v2, v2, v2 quad_perm:[2,3,0,1] row_mask:0xf bank_mask:0xf bound_ctrl:1
	s_nop 1
	v_add_f32_dpp v2, v2, v2 row_half_mirror row_mask:0xf bank_mask:0xf bound_ctrl:1
	s_nop 1
	v_add_f32_dpp v2, v2, v2 row_mirror row_mask:0xf bank_mask:0xf bound_ctrl:1
	v_mov_b32_e32 v3, v2
	s_nop 1
	v_permlane16_swap_b32_e32 v3, v3
	s_and_saveexec_b64 s[8:9], s[4:5]
	s_cbranch_execz .LBB0_1337
	v_add_f32_e32 v2, v2, v3
	v_lshl_add_u64 v[0:1], v[0:1], 2, s[94:95]
	global_atomic_add_f32 v[0:1], v2, off
; __device__ __forceinline__ u16 f2bf(float f) { return (u16)(pack2(f, f) & 0xffffu); }
; __device__ __forceinline__ float sum32(float v) { v = dpp_row_sum16(v); v += __shfl_xor(v, 16); return v; }
; __device__ __forceinline__ int rowmap(int e, int lane) { return (e & 3) + 8 * (e >> 2) + 4 * (lane >> 5); }
; __device__ __forceinline__ void phase4b(const Params& p, char* smem) {
;     ...
; #pragma unroll
;     for (int i = 0; i < 2; i++)
; #pragma unroll
;       for (int e = 0; e < 16; e++) {
;         const int row = m0 + wm * 64 + i * 32 + rowmap(e, lane);
;         const float* xr = xrow(p, row);
;         float sq = 0.f;
; #pragma unroll
;         for (int j = 0; j < 2; j++) {
;           const int col = n0 + wn * 64 + j * 32 + (lane & 31);
;           float v = acc[i][j][e] + xr[col];
;           X1[(size_t)row * 1024 + col] = v;
;           ((u16*)smem)[(row - m0) * 136 + (col - n0)] = f2bf(v);
;           sq += v * v;
;         }
;         sq = sum32(sq);
;         if ((lane & 31) == 0) atomicAdd(&SSQ1[row], sq);
.LBB0_1337:
	s_or_b64 exec, exec, s[8:9]
	v_or_b32_e32 v0, v34, v123
	v_add_u32_e32 v2, 0xffffc000, v0
	v_ashrrev_i32_e32 v1, 31, v0
	v_cmp_gt_i32_e32 vcc, s14, v0
	v_mov_b32_e32 v16, s43
	v_mov_b32_e32 v17, s41
	v_cndmask_b32_e32 v3, 0, v1, vcc
	v_cndmask_b32_e32 v2, v2, v0, vcc
	v_cndmask_b32_e32 v17, v16, v17, vcc
	v_mov_b32_e32 v16, s42
	v_mov_b32_e32 v18, s40
	v_cndmask_b32_e32 v16, v16, v18, vcc
	v_lshlrev_b64 v[2:3], 12, v[2:3]
	v_lshl_add_u64 v[2:3], v[16:17], 0, v[2:3]
	v_lshl_add_u64 v[16:17], v[2:3], 0, v[64:65]
	v_accvgpr_read_b32 v32, a20
	v_lshlrev_b64 v[16:17], 12, v[0:1]
	v_lshl_add_u64 v[16:17], s[78:79], 0, v[16:17]
	v_mov_b32_e32 v93, v65
	v_lshl_add_u64 v[18:19], v[16:17], 0, v[64:65]
	v_lshl_add_u64 v[2:3], v[2:3], 0, v[92:93]
	v_lshl_add_u64 v[16:17], v[16:17], 0, v[92:93]
	v_add_f32_e32 v20, v20, v32
	global_store_dword v[18:19], v20, off
	v_accvgpr_read_b32 v2, a4
	v_subrev_u32_e32 v3, s6, v0
	v_mad_u64_u32 v[18:19], s[8:9], v3, s15, v[68:69]
	v_cvt_pk_bf16_f32 v32, v20, s0
	ds_write_b16 v18, v32
	v_add_f32_e32 v4, v4, v2
	v_mul_f32_e32 v2, v4, v4
	v_fmac_f32_e32 v2, v20, v20
	global_store_dword v[16:17], v4, off offset:128
	v_cvt_pk_bf16_f32 v4, v4, s0
	v_add_f32_dpp v2, v2, v2 quad_perm:[1,0,3,2] row_mask:0xf bank_mask:0xf bound_ctrl:1
	ds_write_b16 v18, v4 offset:64
	s_nop 0
	v_add_f32_dpp v2, v2, v2 quad_perm:[2,3,0,1] row_mask:0xf bank_mask:0xf bound_ctrl:1
	s_nop 1
	v_add_f32_dpp v2, v2, v2 row_half_mirror row_mask:0xf bank_mask:0xf bound_ctrl:1
	s_nop 1
	v_add_f32_dpp v2, v2, v2 row_mirror row_mask:0xf bank_mask:0xf bound_ctrl:1
	v_mov_b32_e32 v3, v2
	s_nop 1
	v_permlane16_swap_b32_e32 v3, v3
	s_and_saveexec_b64 s[8:9], s[4:5]
	s_cbranch_execz .LBB0_1339
	v_add_f32_e32 v2, v2, v3
	v_lshl_add_u64 v[0:1], v[0:1], 2, s[94:95]
	global_atomic_add_f32 v[0:1], v2, off
.LBB0_1339:
	s_or_b64 exec, exec, s[8:9]
	v_or_b32_e32 v0, v34, v124
	v_add_u32_e32 v2, 0xffffc000, v0
	v_ashrrev_i32_e32 v1, 31, v0
	v_cmp_gt_i32_e32 vcc, s14, v0
	v_mov_b32_e32 v4, s43
	v_mov_b32_e32 v16, s41
	v_cndmask_b32_e32 v3, 0, v1, vcc
	v_cndmask_b32_e32 v2, v2, v0, vcc
	v_cndmask_b32_e32 v17, v4, v16, vcc
	v_mov_b32_e32 v4, s42
	v_mov_b32_e32 v16, s40
	v_cndmask_b32_e32 v16, v4, v16, vcc
	v_lshlrev_b64 v[2:3], 12, v[2:3]
	v_lshl_add_u64 v[2:3], v[16:17], 0, v[2:3]
	v_lshl_add_u64 v[16:17], v[2:3], 0, v[64:65]
	v_accvgpr_read_b32 v4, a21
	v_lshlrev_b64 v[16:17], 12, v[0:1]
	v_lshl_add_u64 v[16:17], s[78:79], 0, v[16:17]
	v_lshl_add_u64 v[18:19], v[16:17], 0, v[64:65]
	v_lshl_add_u64 v[2:3], v[2:3], 0, v[92:93]
	v_add_f32_e32 v4, v21, v4
	global_store_dword v[18:19], v4, off
	v_accvgpr_read_b32 v2, a5
	v_subrev_u32_e32 v3, s6, v0
	v_mad_u64_u32 v[18:19], s[8:9], v3, s15, v[68:69]
	v_cvt_pk_bf16_f32 v20, v4, s0
	ds_write_b16 v18, v20
	v_add_f32_e32 v19, v5, v2
	v_mul_f32_e32 v2, v19, v19
	v_fmac_f32_e32 v2, v4, v4
	v_lshl_add_u64 v[4:5], v[16:17], 0, v[92:93]
	global_store_dword v[4:5], v19, off offset:128
	v_add_f32_dpp v2, v2, v2 quad_perm:[1,0,3,2] row_mask:0xf bank_mask:0xf bound_ctrl:1
	v_cvt_pk_bf16_f32 v4, v19, s0
	ds_write_b16 v18, v4 offset:64
	v_add_f32_dpp v2, v2, v2 quad_perm:[2,3,0,1] row_mask:0xf bank_mask:0xf bound_ctrl:1
	s_nop 1
	v_add_f32_dpp v2, v2, v2 row_half_mirror row_mask:0xf bank_mask:0xf bound_ctrl:1
	s_nop 1
	v_add_f32_dpp v2, v2, v2 row_mirror row_mask:0xf bank_mask:0xf bound_ctrl:1
	v_mov_b32_e32 v3, v2
	s_nop 1
	v_permlane16_swap_b32_e32 v3, v3
	s_and_saveexec_b64 s[8:9], s[4:5]
	s_cbranch_execz .LBB0_1341
	v_add_f32_e32 v2, v2, v3
	v_lshl_add_u64 v[0:1], v[0:1], 2, s[94:95]
	global_atomic_add_f32 v[0:1], v2, off
.LBB0_1341:
	s_or_b64 exec, exec, s[8:9]
	v_or_b32_e32 v0, v34, v125
	v_add_u32_e32 v2, 0xffffc000, v0
	v_ashrrev_i32_e32 v1, 31, v0
	v_cmp_gt_i32_e32 vcc, s14, v0
	v_mov_b32_e32 v4, s43
	v_mov_b32_e32 v5, s41
	v_cndmask_b32_e32 v3, 0, v1, vcc
	v_cndmask_b32_e32 v2, v2, v0, vcc
	v_cndmask_b32_e32 v5, v4, v5, vcc
	v_mov_b32_e32 v4, s42
	v_mov_b32_e32 v16, s40
	v_cndmask_b32_e32 v4, v4, v16, vcc
	v_lshlrev_b64 v[2:3], 12, v[2:3]
	v_lshl_add_u64 v[2:3], v[4:5], 0, v[2:3]
	v_lshl_add_u64 v[4:5], v[2:3], 0, v[64:65]
	v_accvgpr_read_b32 v18, a22
	v_lshlrev_b64 v[4:5], 12, v[0:1]
	v_lshl_add_u64 v[4:5], s[78:79], 0, v[4:5]
	v_mov_b32_e32 v93, v65
	v_lshl_add_u64 v[16:17], v[4:5], 0, v[64:65]
	v_lshl_add_u64 v[2:3], v[2:3], 0, v[92:93]
	v_lshl_add_u64 v[4:5], v[4:5], 0, v[92:93]
	v_add_f32_e32 v18, v22, v18
	global_store_dword v[16:17], v18, off
	v_accvgpr_read_b32 v2, a6
	v_subrev_u32_e32 v3, s6, v0
	v_mad_u64_u32 v[16:17], s[8:9], v3, s15, v[68:69]
	v_cvt_pk_bf16_f32 v19, v18, s0
	ds_write_b16 v16, v19
	v_add_f32_e32 v6, v6, v2
	v_mul_f32_e32 v2, v6, v6
	v_fmac_f32_e32 v2, v18, v18
	global_store_dword v[4:5], v6, off offset:128
	v_cvt_pk_bf16_f32 v4, v6, s0
	v_add_f32_dpp v2, v2, v2 quad_perm:[1,0,3,2] row_mask:0xf bank_mask:0xf bound_ctrl:1
	ds_write_b16 v16, v4 offset:64
	s_nop 0
	v_add_f32_dpp v2, v2, v2 quad_perm:[2,3,0,1] row_mask:0xf bank_mask:0xf bound_ctrl:1
	s_nop 1
	v_add_f32_dpp v2, v2, v2 row_half_mirror row_mask:0xf bank_mask:0xf bound_ctrl:1
	s_nop 1
	v_add_f32_dpp v2, v2, v2 row_mirror row_mask:0xf bank_mask:0xf bound_ctrl:1
	v_mov_b32_e32 v3, v2
	s_nop 1
	v_permlane16_swap_b32_e32 v3, v3
	s_and_saveexec_b64 s[8:9], s[4:5]
	s_cbranch_execz .LBB0_1343
	v_add_f32_e32 v2, v2, v3
	v_lshl_add_u64 v[0:1], v[0:1], 2, s[94:95]
	global_atomic_add_f32 v[0:1], v2, off
; __device__ __forceinline__ u16 f2bf(float f) { return (u16)(pack2(f, f) & 0xffffu); }
; __device__ __forceinline__ float sum32(float v) { v = dpp_row_sum16(v); v += __shfl_xor(v, 16); return v; }
; __device__ __forceinline__ int rowmap(int e, int lane) { return (e & 3) + 8 * (e >> 2) + 4 * (lane >> 5); }
; __device__ __forceinline__ void phase4b(const Params& p, char* smem) {
;     ...
; #pragma unroll
;     for (int i = 0; i < 2; i++)
; #pragma unroll
;       for (int e = 0; e < 16; e++) {
;         const int row = m0 + wm * 64 + i * 32 + rowmap(e, lane);
;         const float* xr = xrow(p, row);
;         float sq = 0.f;
; #pragma unroll
;         for (int j = 0; j < 2; j++) {
;           const int col = n0 + wn * 64 + j * 32 + (lane & 31);
;           float v = acc[i][j][e] + xr[col];
;           X1[(size_t)row * 1024 + col] = v;
;           ((u16*)smem)[(row - m0) * 136 + (col - n0)] = f2bf(v);
;           sq += v * v;
;         }
;         sq = sum32(sq);
;         if ((lane & 31) == 0) atomicAdd(&SSQ1[row], sq);
.LBB0_1343:
	s_or_b64 exec, exec, s[8:9]
	v_or_b32_e32 v0, v34, v126
	v_add_u32_e32 v2, 0xffffc000, v0
	v_ashrrev_i32_e32 v1, 31, v0
	v_cmp_gt_i32_e32 vcc, s14, v0
	v_mov_b32_e32 v4, s43
	v_mov_b32_e32 v5, s41
	v_cndmask_b32_e32 v3, 0, v1, vcc
	v_cndmask_b32_e32 v2, v2, v0, vcc
	v_cndmask_b32_e32 v5, v4, v5, vcc
	v_mov_b32_e32 v4, s42
	v_mov_b32_e32 v6, s40
	v_cndmask_b32_e32 v4, v4, v6, vcc
	v_lshlrev_b64 v[2:3], 12, v[2:3]
	v_lshl_add_u64 v[2:3], v[4:5], 0, v[2:3]
	v_lshl_add_u64 v[4:5], v[2:3], 0, v[64:65]
	v_accvgpr_read_b32 v6, a23
	v_lshlrev_b64 v[4:5], 12, v[0:1]
	v_lshl_add_u64 v[4:5], s[78:79], 0, v[4:5]
	v_lshl_add_u64 v[16:17], v[4:5], 0, v[64:65]
	v_lshl_add_u64 v[2:3], v[2:3], 0, v[92:93]
	v_lshl_add_u64 v[4:5], v[4:5], 0, v[92:93]
	v_add_f32_e32 v6, v23, v6
	global_store_dword v[16:17], v6, off
	v_accvgpr_read_b32 v2, a7
	v_subrev_u32_e32 v3, s6, v0
	v_mad_u64_u32 v[16:17], s[8:9], v3, s15, v[68:69]
	v_cvt_pk_bf16_f32 v18, v6, s0
	ds_write_b16 v16, v18
	v_add_f32_e32 v7, v7, v2
	v_mul_f32_e32 v2, v7, v7
	v_fmac_f32_e32 v2, v6, v6
	global_store_dword v[4:5], v7, off offset:128
	v_cvt_pk_bf16_f32 v4, v7, s0
	v_add_f32_dpp v2, v2, v2 quad_perm:[1,0,3,2] row_mask:0xf bank_mask:0xf bound_ctrl:1
	ds_write_b16 v16, v4 offset:64
	s_nop 0
	v_add_f32_dpp v2, v2, v2 quad_perm:[2,3,0,1] row_mask:0xf bank_mask:0xf bound_ctrl:1
	s_nop 1
	v_add_f32_dpp v2, v2, v2 row_half_mirror row_mask:0xf bank_mask:0xf bound_ctrl:1
	s_nop 1
	v_add_f32_dpp v2, v2, v2 row_mirror row_mask:0xf bank_mask:0xf bound_ctrl:1
	v_mov_b32_e32 v3, v2
	s_nop 1
	v_permlane16_swap_b32_e32 v3, v3
	s_and_saveexec_b64 s[8:9], s[4:5]
	s_cbranch_execz .LBB0_1345
	v_add_f32_e32 v2, v2, v3
	v_lshl_add_u64 v[0:1], v[0:1], 2, s[94:95]
	global_atomic_add_f32 v[0:1], v2, off
.LBB0_1345:
	s_or_b64 exec, exec, s[8:9]
	v_or_b32_e32 v0, v34, v127
	v_add_u32_e32 v2, 0xffffc000, v0
	v_ashrrev_i32_e32 v1, 31, v0
	v_cmp_gt_i32_e32 vcc, s14, v0
	v_mov_b32_e32 v4, s43
	v_mov_b32_e32 v5, s41
	v_cndmask_b32_e32 v3, 0, v1, vcc
	v_cndmask_b32_e32 v2, v2, v0, vcc
	v_cndmask_b32_e32 v5, v4, v5, vcc
	v_mov_b32_e32 v4, s42
	v_mov_b32_e32 v6, s40
	v_cndmask_b32_e32 v4, v4, v6, vcc
	v_lshlrev_b64 v[2:3], 12, v[2:3]
	v_lshl_add_u64 v[2:3], v[4:5], 0, v[2:3]
	v_lshl_add_u64 v[4:5], v[2:3], 0, v[64:65]
	v_accvgpr_read_b32 v16, a24
	v_lshlrev_b64 v[4:5], 12, v[0:1]
	v_lshl_add_u64 v[4:5], s[78:79], 0, v[4:5]
	v_mov_b32_e32 v93, v65
	v_lshl_add_u64 v[6:7], v[4:5], 0, v[64:65]
	v_lshl_add_u64 v[2:3], v[2:3], 0, v[92:93]
	v_lshl_add_u64 v[4:5], v[4:5], 0, v[92:93]
	v_add_f32_e32 v16, v24, v16
	global_store_dword v[6:7], v16, off
	v_accvgpr_read_b32 v2, a8
	v_subrev_u32_e32 v3, s6, v0
	v_mad_u64_u32 v[6:7], s[8:9], v3, s15, v[68:69]
	v_cvt_pk_bf16_f32 v17, v16, s0
	ds_write_b16 v6, v17
	v_add_f32_e32 v7, v8, v2
	v_mul_f32_e32 v2, v7, v7
	v_fmac_f32_e32 v2, v16, v16
	global_store_dword v[4:5], v7, off offset:128
	v_cvt_pk_bf16_f32 v4, v7, s0
	v_add_f32_dpp v2, v2, v2 quad_perm:[1,0,3,2] row_mask:0xf bank_mask:0xf bound_ctrl:1
	ds_write_b16 v6, v4 offset:64
	s_nop 0
	v_add_f32_dpp v2, v2, v2 quad_perm:[2,3,0,1] row_mask:0xf bank_mask:0xf bound_ctrl:1
	s_nop 1
	v_add_f32_dpp v2, v2, v2 row_half_mirror row_mask:0xf bank_mask:0xf bound_ctrl:1
	s_nop 1
	v_add_f32_dpp v2, v2, v2 row_mirror row_mask:0xf bank_mask:0xf bound_ctrl:1
	v_mov_b32_e32 v3, v2
	s_nop 1
	v_permlane16_swap_b32_e32 v3, v3
	s_and_saveexec_b64 s[8:9], s[4:5]
	s_cbranch_execz .LBB0_1347
	v_add_f32_e32 v2, v2, v3
	v_lshl_add_u64 v[0:1], v[0:1], 2, s[94:95]
	global_atomic_add_f32 v[0:1], v2, off
.LBB0_1347:
	s_or_b64 exec, exec, s[8:9]
	v_or_b32_e32 v0, v34, v128
	v_add_u32_e32 v2, 0xffffc000, v0
	v_ashrrev_i32_e32 v1, 31, v0
	v_cmp_gt_i32_e32 vcc, s14, v0
	v_mov_b32_e32 v4, s43
	v_mov_b32_e32 v5, s41
	v_cndmask_b32_e32 v3, 0, v1, vcc
	v_cndmask_b32_e32 v2, v2, v0, vcc
	v_cndmask_b32_e32 v5, v4, v5, vcc
	v_mov_b32_e32 v4, s42
	v_mov_b32_e32 v6, s40
	v_cndmask_b32_e32 v4, v4, v6, vcc
	v_lshlrev_b64 v[2:3], 12, v[2:3]
	v_lshl_add_u64 v[2:3], v[4:5], 0, v[2:3]
	v_lshl_add_u64 v[4:5], v[2:3], 0, v[64:65]
	v_accvgpr_read_b32 v8, a25
	v_lshlrev_b64 v[4:5], 12, v[0:1]
	v_lshl_add_u64 v[4:5], s[78:79], 0, v[4:5]
	v_lshl_add_u64 v[6:7], v[4:5], 0, v[64:65]
	v_lshl_add_u64 v[2:3], v[2:3], 0, v[92:93]
	v_lshl_add_u64 v[4:5], v[4:5], 0, v[92:93]
	v_add_f32_e32 v8, v25, v8
	global_store_dword v[6:7], v8, off
	v_accvgpr_read_b32 v2, a9
	v_subrev_u32_e32 v3, s6, v0
	v_mad_u64_u32 v[6:7], s[8:9], v3, s15, v[68:69]
	v_cvt_pk_bf16_f32 v16, v8, s0
	ds_write_b16 v6, v16
	v_add_f32_e32 v7, v9, v2
	v_mul_f32_e32 v2, v7, v7
	v_fmac_f32_e32 v2, v8, v8
	global_store_dword v[4:5], v7, off offset:128
	v_cvt_pk_bf16_f32 v4, v7, s0
	v_add_f32_dpp v2, v2, v2 quad_perm:[1,0,3,2] row_mask:0xf bank_mask:0xf bound_ctrl:1
	ds_write_b16 v6, v4 offset:64
	s_nop 0
	v_add_f32_dpp v2, v2, v2 quad_perm:[2,3,0,1] row_mask:0xf bank_mask:0xf bound_ctrl:1
	s_nop 1
	v_add_f32_dpp v2, v2, v2 row_half_mirror row_mask:0xf bank_mask:0xf bound_ctrl:1
	s_nop 1
	v_add_f32_dpp v2, v2, v2 row_mirror row_mask:0xf bank_mask:0xf bound_ctrl:1
	v_mov_b32_e32 v3, v2
	s_nop 1
	v_permlane16_swap_b32_e32 v3, v3
	s_and_saveexec_b64 s[8:9], s[4:5]
	s_cbranch_execz .LBB0_1349
	v_add_f32_e32 v2, v2, v3
	v_lshl_add_u64 v[0:1], v[0:1], 2, s[94:95]
	global_atomic_add_f32 v[0:1], v2, off
; __device__ __forceinline__ u16 f2bf(float f) { return (u16)(pack2(f, f) & 0xffffu); }
; __device__ __forceinline__ float sum32(float v) { v = dpp_row_sum16(v); v += __shfl_xor(v, 16); return v; }
; __device__ __forceinline__ int rowmap(int e, int lane) { return (e & 3) + 8 * (e >> 2) + 4 * (lane >> 5); }
; __device__ __forceinline__ void phase4b(const Params& p, char* smem) {
;     ...
; #pragma unroll
;     for (int i = 0; i < 2; i++)
; #pragma unroll
;       for (int e = 0; e < 16; e++) {
;         const int row = m0 + wm * 64 + i * 32 + rowmap(e, lane);
;         const float* xr = xrow(p, row);
;         float sq = 0.f;
; #pragma unroll
;         for (int j = 0; j < 2; j++) {
;           const int col = n0 + wn * 64 + j * 32 + (lane & 31);
;           float v = acc[i][j][e] + xr[col];
;           X1[(size_t)row * 1024 + col] = v;
;           ((u16*)smem)[(row - m0) * 136 + (col - n0)] = f2bf(v);
;           sq += v * v;
;         }
;         sq = sum32(sq);
;         if ((lane & 31) == 0) atomicAdd(&SSQ1[row], sq);
.LBB0_1349:
	s_or_b64 exec, exec, s[8:9]
	v_or_b32_e32 v0, v34, v129
	v_add_u32_e32 v2, 0xffffc000, v0
	v_ashrrev_i32_e32 v1, 31, v0
	v_cmp_gt_i32_e32 vcc, s14, v0
	v_mov_b32_e32 v4, s43
	v_mov_b32_e32 v5, s41
	v_cndmask_b32_e32 v3, 0, v1, vcc
	v_cndmask_b32_e32 v2, v2, v0, vcc
	v_cndmask_b32_e32 v5, v4, v5, vcc
	v_mov_b32_e32 v4, s42
	v_mov_b32_e32 v6, s40
	v_cndmask_b32_e32 v4, v4, v6, vcc
	v_lshlrev_b64 v[2:3], 12, v[2:3]
	v_lshl_add_u64 v[2:3], v[4:5], 0, v[2:3]
	v_lshl_add_u64 v[4:5], v[2:3], 0, v[64:65]
	v_accvgpr_read_b32 v8, a26
	v_lshlrev_b64 v[4:5], 12, v[0:1]
	v_lshl_add_u64 v[4:5], s[78:79], 0, v[4:5]
	v_mov_b32_e32 v93, v65
	v_lshl_add_u64 v[6:7], v[4:5], 0, v[64:65]
	v_lshl_add_u64 v[2:3], v[2:3], 0, v[92:93]
	v_lshl_add_u64 v[4:5], v[4:5], 0, v[92:93]
	v_add_f32_e32 v8, v26, v8
	global_store_dword v[6:7], v8, off
	v_accvgpr_read_b32 v2, a10
	v_subrev_u32_e32 v3, s6, v0
	v_mad_u64_u32 v[6:7], s[8:9], v3, s15, v[68:69]
	v_cvt_pk_bf16_f32 v9, v8, s0
	ds_write_b16 v6, v9
	v_add_f32_e32 v7, v10, v2
	v_mul_f32_e32 v2, v7, v7
	v_fmac_f32_e32 v2, v8, v8
	global_store_dword v[4:5], v7, off offset:128
	v_cvt_pk_bf16_f32 v4, v7, s0
	v_add_f32_dpp v2, v2, v2 quad_perm:[1,0,3,2] row_mask:0xf bank_mask:0xf bound_ctrl:1
	ds_write_b16 v6, v4 offset:64
	s_nop 0
	v_add_f32_dpp v2, v2, v2 quad_perm:[2,3,0,1] row_mask:0xf bank_mask:0xf bound_ctrl:1
	s_nop 1
	v_add_f32_dpp v2, v2, v2 row_half_mirror row_mask:0xf bank_mask:0xf bound_ctrl:1
	s_nop 1
	v_add_f32_dpp v2, v2, v2 row_mirror row_mask:0xf bank_mask:0xf bound_ctrl:1
	v_mov_b32_e32 v3, v2
	s_nop 1
	v_permlane16_swap_b32_e32 v3, v3
	s_and_saveexec_b64 s[8:9], s[4:5]
	s_cbranch_execz .LBB0_1351
	v_add_f32_e32 v2, v2, v3
	v_lshl_add_u64 v[0:1], v[0:1], 2, s[94:95]
	global_atomic_add_f32 v[0:1], v2, off
.LBB0_1351:
	s_or_b64 exec, exec, s[8:9]
	v_or_b32_e32 v0, v34, v130
	v_add_u32_e32 v2, 0xffffc000, v0
	v_ashrrev_i32_e32 v1, 31, v0
	v_cmp_gt_i32_e32 vcc, s14, v0
	v_mov_b32_e32 v4, s43
	v_mov_b32_e32 v5, s41
	v_cndmask_b32_e32 v3, 0, v1, vcc
	v_cndmask_b32_e32 v2, v2, v0, vcc
	v_cndmask_b32_e32 v5, v4, v5, vcc
	v_mov_b32_e32 v4, s42
	v_mov_b32_e32 v6, s40
	v_cndmask_b32_e32 v4, v4, v6, vcc
	v_lshlrev_b64 v[2:3], 12, v[2:3]
	v_lshl_add_u64 v[2:3], v[4:5], 0, v[2:3]
	v_lshl_add_u64 v[4:5], v[2:3], 0, v[64:65]
	v_accvgpr_read_b32 v8, a27
	v_lshlrev_b64 v[4:5], 12, v[0:1]
	v_lshl_add_u64 v[4:5], s[78:79], 0, v[4:5]
	v_lshl_add_u64 v[6:7], v[4:5], 0, v[64:65]
	v_lshl_add_u64 v[2:3], v[2:3], 0, v[92:93]
	v_lshl_add_u64 v[4:5], v[4:5], 0, v[92:93]
	v_add_f32_e32 v8, v27, v8
	global_store_dword v[6:7], v8, off
	v_accvgpr_read_b32 v2, a11
	v_subrev_u32_e32 v3, s6, v0
	v_mad_u64_u32 v[6:7], s[8:9], v3, s15, v[68:69]
	v_cvt_pk_bf16_f32 v9, v8, s0
	ds_write_b16 v6, v9
	v_add_f32_e32 v7, v11, v2
	v_mul_f32_e32 v2, v7, v7
	v_fmac_f32_e32 v2, v8, v8
	global_store_dword v[4:5], v7, off offset:128
	v_cvt_pk_bf16_f32 v4, v7, s0
	v_add_f32_dpp v2, v2, v2 quad_perm:[1,0,3,2] row_mask:0xf bank_mask:0xf bound_ctrl:1
	ds_write_b16 v6, v4 offset:64
	s_nop 0
	v_add_f32_dpp v2, v2, v2 quad_perm:[2,3,0,1] row_mask:0xf bank_mask:0xf bound_ctrl:1
	s_nop 1
	v_add_f32_dpp v2, v2, v2 row_half_mirror row_mask:0xf bank_mask:0xf bound_ctrl:1
	s_nop 1
	v_add_f32_dpp v2, v2, v2 row_mirror row_mask:0xf bank_mask:0xf bound_ctrl:1
	v_mov_b32_e32 v3, v2
	s_nop 1
	v_permlane16_swap_b32_e32 v3, v3
	s_and_saveexec_b64 s[8:9], s[4:5]
	s_cbranch_execz .LBB0_1353
	v_add_f32_e32 v2, v2, v3
	v_lshl_add_u64 v[0:1], v[0:1], 2, s[94:95]
	global_atomic_add_f32 v[0:1], v2, off
.LBB0_1353:
	s_or_b64 exec, exec, s[8:9]
	v_or_b32_e32 v0, v34, v131
	v_add_u32_e32 v2, 0xffffc000, v0
	v_ashrrev_i32_e32 v1, 31, v0
	v_cmp_gt_i32_e32 vcc, s14, v0
	v_mov_b32_e32 v4, s43
	v_mov_b32_e32 v5, s41
	v_cndmask_b32_e32 v3, 0, v1, vcc
	v_cndmask_b32_e32 v2, v2, v0, vcc
	v_cndmask_b32_e32 v5, v4, v5, vcc
	v_mov_b32_e32 v4, s42
	v_mov_b32_e32 v6, s40
	v_cndmask_b32_e32 v4, v4, v6, vcc
	v_lshlrev_b64 v[2:3], 12, v[2:3]
	v_lshl_add_u64 v[2:3], v[4:5], 0, v[2:3]
	v_lshl_add_u64 v[4:5], v[2:3], 0, v[64:65]
	v_accvgpr_read_b32 v8, a28
	v_lshlrev_b64 v[4:5], 12, v[0:1]
	v_lshl_add_u64 v[4:5], s[78:79], 0, v[4:5]
	v_mov_b32_e32 v93, v65
	v_lshl_add_u64 v[6:7], v[4:5], 0, v[64:65]
	v_lshl_add_u64 v[2:3], v[2:3], 0, v[92:93]
	v_lshl_add_u64 v[4:5], v[4:5], 0, v[92:93]
	v_add_f32_e32 v8, v28, v8
	global_store_dword v[6:7], v8, off
	v_accvgpr_read_b32 v2, a12
	v_subrev_u32_e32 v3, s6, v0
	v_mad_u64_u32 v[6:7], s[8:9], v3, s15, v[68:69]
	v_cvt_pk_bf16_f32 v9, v8, s0
	ds_write_b16 v6, v9
	v_add_f32_e32 v7, v12, v2
	v_mul_f32_e32 v2, v7, v7
	v_fmac_f32_e32 v2, v8, v8
	global_store_dword v[4:5], v7, off offset:128
	v_cvt_pk_bf16_f32 v4, v7, s0
	v_add_f32_dpp v2, v2, v2 quad_perm:[1,0,3,2] row_mask:0xf bank_mask:0xf bound_ctrl:1
	ds_write_b16 v6, v4 offset:64
	s_nop 0
	v_add_f32_dpp v2, v2, v2 quad_perm:[2,3,0,1] row_mask:0xf bank_mask:0xf bound_ctrl:1
	s_nop 1
	v_add_f32_dpp v2, v2, v2 row_half_mirror row_mask:0xf bank_mask:0xf bound_ctrl:1
	s_nop 1
	v_add_f32_dpp v2, v2, v2 row_mirror row_mask:0xf bank_mask:0xf bound_ctrl:1
	v_mov_b32_e32 v3, v2
	s_nop 1
	v_permlane16_swap_b32_e32 v3, v3
	s_and_saveexec_b64 s[8:9], s[4:5]
	s_cbranch_execz .LBB0_1355
	v_add_f32_e32 v2, v2, v3
	v_lshl_add_u64 v[0:1], v[0:1], 2, s[94:95]
	global_atomic_add_f32 v[0:1], v2, off
; __device__ __forceinline__ u16 f2bf(float f) { return (u16)(pack2(f, f) & 0xffffu); }
; __device__ __forceinline__ float sum32(float v) { v = dpp_row_sum16(v); v += __shfl_xor(v, 16); return v; }
; __device__ __forceinline__ int rowmap(int e, int lane) { return (e & 3) + 8 * (e >> 2) + 4 * (lane >> 5); }
; __device__ __forceinline__ void phase4b(const Params& p, char* smem) {
;     ...
;     for (int i = 0; i < 2; i++)
; #pragma unroll
;       for (int e = 0; e < 16; e++) {
;         const int row = m0 + wm * 64 + i * 32 + rowmap(e, lane);
;         const float* xr = xrow(p, row);
;         float sq = 0.f;
; #pragma unroll
;         for (int j = 0; j < 2; j++) {
;           const int col = n0 + wn * 64 + j * 32 + (lane & 31);
;           float v = acc[i][j][e] + xr[col];
;           X1[(size_t)row * 1024 + col] = v;
;           ((u16*)smem)[(row - m0) * 136 + (col - n0)] = f2bf(v);
;           sq += v * v;
;         }
;         sq = sum32(sq);
;         if ((lane & 31) == 0) atomicAdd(&SSQ1[row], sq);
.LBB0_1355:
	s_or_b64 exec, exec, s[8:9]
	v_or_b32_e32 v0, v34, v132
	v_add_u32_e32 v2, 0xffffc000, v0
	v_ashrrev_i32_e32 v1, 31, v0
	v_cmp_gt_i32_e32 vcc, s14, v0
	v_mov_b32_e32 v4, s43
	v_mov_b32_e32 v5, s41
	v_cndmask_b32_e32 v3, 0, v1, vcc
	v_cndmask_b32_e32 v2, v2, v0, vcc
	v_cndmask_b32_e32 v5, v4, v5, vcc
	v_mov_b32_e32 v4, s42
	v_mov_b32_e32 v6, s40
	v_cndmask_b32_e32 v4, v4, v6, vcc
	v_lshlrev_b64 v[2:3], 12, v[2:3]
	v_lshl_add_u64 v[2:3], v[4:5], 0, v[2:3]
	v_lshl_add_u64 v[4:5], v[2:3], 0, v[64:65]
	v_accvgpr_read_b32 v8, a29
	v_lshlrev_b64 v[4:5], 12, v[0:1]
	v_lshl_add_u64 v[4:5], s[78:79], 0, v[4:5]
	v_lshl_add_u64 v[6:7], v[4:5], 0, v[64:65]
	v_lshl_add_u64 v[2:3], v[2:3], 0, v[92:93]
	v_lshl_add_u64 v[4:5], v[4:5], 0, v[92:93]
	v_add_f32_e32 v8, v29, v8
	global_store_dword v[6:7], v8, off
	v_accvgpr_read_b32 v2, a13
	v_subrev_u32_e32 v3, s6, v0
	v_mad_u64_u32 v[6:7], s[8:9], v3, s15, v[68:69]
	v_cvt_pk_bf16_f32 v9, v8, s0
	ds_write_b16 v6, v9
	v_add_f32_e32 v7, v13, v2
	v_mul_f32_e32 v2, v7, v7
	v_fmac_f32_e32 v2, v8, v8
	global_store_dword v[4:5], v7, off offset:128
	v_cvt_pk_bf16_f32 v4, v7, s0
	v_add_f32_dpp v2, v2, v2 quad_perm:[1,0,3,2] row_mask:0xf bank_mask:0xf bound_ctrl:1
	ds_write_b16 v6, v4 offset:64
	s_nop 0
	v_add_f32_dpp v2, v2, v2 quad_perm:[2,3,0,1] row_mask:0xf bank_mask:0xf bound_ctrl:1
	s_nop 1
	v_add_f32_dpp v2, v2, v2 row_half_mirror row_mask:0xf bank_mask:0xf bound_ctrl:1
	s_nop 1
	v_add_f32_dpp v2, v2, v2 row_mirror row_mask:0xf bank_mask:0xf bound_ctrl:1
	v_mov_b32_e32 v3, v2
	s_nop 1
	v_permlane16_swap_b32_e32 v3, v3
	s_and_saveexec_b64 s[8:9], s[4:5]
	s_cbranch_execz .LBB0_1357
	v_add_f32_e32 v2, v2, v3
	v_lshl_add_u64 v[0:1], v[0:1], 2, s[94:95]
	global_atomic_add_f32 v[0:1], v2, off
.LBB0_1357:
	s_or_b64 exec, exec, s[8:9]
	v_or_b32_e32 v0, v34, v133
	v_add_u32_e32 v2, 0xffffc000, v0
	v_ashrrev_i32_e32 v1, 31, v0
	v_cmp_gt_i32_e32 vcc, s14, v0
	v_mov_b32_e32 v4, s43
	v_mov_b32_e32 v5, s41
	v_cndmask_b32_e32 v3, 0, v1, vcc
	v_cndmask_b32_e32 v2, v2, v0, vcc
	v_cndmask_b32_e32 v5, v4, v5, vcc
	v_mov_b32_e32 v4, s42
	v_mov_b32_e32 v6, s40
	v_cndmask_b32_e32 v4, v4, v6, vcc
	v_lshlrev_b64 v[2:3], 12, v[2:3]
	v_lshl_add_u64 v[2:3], v[4:5], 0, v[2:3]
	v_lshl_add_u64 v[4:5], v[2:3], 0, v[64:65]
	v_accvgpr_read_b32 v8, a30
	v_lshlrev_b64 v[4:5], 12, v[0:1]
	v_lshl_add_u64 v[4:5], s[78:79], 0, v[4:5]
	v_mov_b32_e32 v93, v65
	v_lshl_add_u64 v[6:7], v[4:5], 0, v[64:65]
	v_lshl_add_u64 v[2:3], v[2:3], 0, v[92:93]
	v_lshl_add_u64 v[4:5], v[4:5], 0, v[92:93]
	v_add_f32_e32 v8, v30, v8
	global_store_dword v[6:7], v8, off
	v_accvgpr_read_b32 v2, a14
	v_subrev_u32_e32 v3, s6, v0
	v_mad_u64_u32 v[6:7], s[8:9], v3, s15, v[68:69]
	v_cvt_pk_bf16_f32 v9, v8, s0
	ds_write_b16 v6, v9
	v_add_f32_e32 v7, v14, v2
	v_mul_f32_e32 v2, v7, v7
	v_fmac_f32_e32 v2, v8, v8
	global_store_dword v[4:5], v7, off offset:128
	v_cvt_pk_bf16_f32 v4, v7, s0
	v_add_f32_dpp v2, v2, v2 quad_perm:[1,0,3,2] row_mask:0xf bank_mask:0xf bound_ctrl:1
	ds_write_b16 v6, v4 offset:64
	s_nop 0
	v_add_f32_dpp v2, v2, v2 quad_perm:[2,3,0,1] row_mask:0xf bank_mask:0xf bound_ctrl:1
	s_nop 1
	v_add_f32_dpp v2, v2, v2 row_half_mirror row_mask:0xf bank_mask:0xf bound_ctrl:1
	s_nop 1
	v_add_f32_dpp v2, v2, v2 row_mirror row_mask:0xf bank_mask:0xf bound_ctrl:1
	v_mov_b32_e32 v3, v2
	s_nop 1
	v_permlane16_swap_b32_e32 v3, v3
	s_and_saveexec_b64 s[8:9], s[4:5]
	s_cbranch_execz .LBB0_1359
	v_add_f32_e32 v2, v2, v3
	v_lshl_add_u64 v[0:1], v[0:1], 2, s[94:95]
	global_atomic_add_f32 v[0:1], v2, off
.LBB0_1359:
	s_or_b64 exec, exec, s[8:9]
	v_or_b32_e32 v0, v34, v134
	v_add_u32_e32 v2, 0xffffc000, v0
	v_ashrrev_i32_e32 v1, 31, v0
	v_cmp_gt_i32_e32 vcc, s14, v0
	v_mov_b32_e32 v4, s43
	v_mov_b32_e32 v5, s41
	v_cndmask_b32_e32 v3, 0, v1, vcc
	v_cndmask_b32_e32 v2, v2, v0, vcc
	v_cndmask_b32_e32 v5, v4, v5, vcc
	v_mov_b32_e32 v4, s42
	v_mov_b32_e32 v6, s40
	v_cndmask_b32_e32 v4, v4, v6, vcc
	v_lshlrev_b64 v[2:3], 12, v[2:3]
	v_lshl_add_u64 v[2:3], v[4:5], 0, v[2:3]
	v_lshl_add_u64 v[4:5], v[2:3], 0, v[64:65]
	v_accvgpr_read_b32 v8, a31
	v_lshlrev_b64 v[4:5], 12, v[0:1]
	v_lshl_add_u64 v[4:5], s[78:79], 0, v[4:5]
	v_lshl_add_u64 v[6:7], v[4:5], 0, v[64:65]
	v_lshl_add_u64 v[2:3], v[2:3], 0, v[92:93]
	v_lshl_add_u64 v[4:5], v[4:5], 0, v[92:93]
	v_add_f32_e32 v8, v31, v8
	global_store_dword v[6:7], v8, off
	v_accvgpr_read_b32 v2, a15
	v_subrev_u32_e32 v3, s6, v0
	v_mad_u64_u32 v[6:7], s[8:9], v3, s15, v[68:69]
	v_cvt_pk_bf16_f32 v9, v8, s0
	ds_write_b16 v6, v9
	v_add_f32_e32 v7, v15, v2
	v_mul_f32_e32 v2, v7, v7
	v_fmac_f32_e32 v2, v8, v8
	global_store_dword v[4:5], v7, off offset:128
	v_cvt_pk_bf16_f32 v4, v7, s0
	v_add_f32_dpp v2, v2, v2 quad_perm:[1,0,3,2] row_mask:0xf bank_mask:0xf bound_ctrl:1
	ds_write_b16 v6, v4 offset:64
	s_nop 0
	v_add_f32_dpp v2, v2, v2 quad_perm:[2,3,0,1] row_mask:0xf bank_mask:0xf bound_ctrl:1
	s_nop 1
	v_add_f32_dpp v2, v2, v2 row_half_mirror row_mask:0xf bank_mask:0xf bound_ctrl:1
	s_nop 1
	v_add_f32_dpp v2, v2, v2 row_mirror row_mask:0xf bank_mask:0xf bound_ctrl:1
	v_mov_b32_e32 v3, v2
	s_nop 1
	v_permlane16_swap_b32_e32 v3, v3
	s_and_saveexec_b64 s[8:9], s[4:5]
	s_cbranch_execz .LBB0_1290
	v_add_f32_e32 v2, v2, v3
	v_lshl_add_u64 v[0:1], v[0:1], 2, s[94:95]
	global_atomic_add_f32 v[0:1], v2, off
	s_branch .LBB0_1290

; __device__ __forceinline__ float bflo(unsigned u) { return __uint_as_float(u << 16); }
; __device__ __forceinline__ float bfhi(unsigned u) { return __uint_as_float(u & 0xffff0000u); }
; __device__ __forceinline__ float sigmoidf_(float x) { return __builtin_amdgcn_rcpf(1.f + __expf(-x)); }
; __device__ __forceinline__ int rowmap(int e, int lane) { return (e & 3) + 8 * (e >> 2) + 4 * (lane >> 5); }
; __device__ __forceinline__ void phase6(const Params& p, char* smem) {
;     ...
; #pragma unroll
;     for (int i = 0; i < 2; i++)
; #pragma unroll
;       for (int e = 0; e < 16; e++) {
;         const int row = m0 + wm * 64 + i * 32 + rowmap(e, lane);
;         float sq = 0.f;
; #pragma unroll
;         for (int j = 0; j < 2; j++) {
;           const int col = n0 + wn * 64 + j * 32 + (lane & 31);
;           float* xp = X + (size_t)row * 1024 + col;
;           float v = *xp + ((e & 1) ? bfhi(pe[i][j][e >> 1]) : bflo(pe[i][j][e >> 1])) * sigmoidf_(acc1[i][j][e]);
.LBB0_1588:
	s_nop 7
	v_accvgpr_read_b32 v112, a0
	v_accvgpr_read_b32 v113, a1
	v_accvgpr_read_b32 v114, a2
	v_accvgpr_read_b32 v115, a3
	v_accvgpr_read_b32 v116, a4
	v_accvgpr_read_b32 v117, a5
	v_accvgpr_read_b32 v118, a6
	v_accvgpr_read_b32 v119, a7
	v_accvgpr_read_b32 v120, a8
	v_accvgpr_read_b32 v121, a9
	v_accvgpr_read_b32 v122, a10
	v_accvgpr_read_b32 v123, a11
	v_accvgpr_read_b32 v124, a12
	v_accvgpr_read_b32 v125, a13
	v_accvgpr_read_b32 v126, a14
	v_accvgpr_read_b32 v127, a15
	v_accvgpr_read_b32 v96, a32
	v_accvgpr_read_b32 v97, a33
	v_accvgpr_read_b32 v98, a34
	v_accvgpr_read_b32 v99, a35
	v_accvgpr_read_b32 v100, a36
	v_accvgpr_read_b32 v101, a37
	v_accvgpr_read_b32 v102, a38
	v_accvgpr_read_b32 v103, a39
	v_accvgpr_read_b32 v104, a40
	v_accvgpr_read_b32 v105, a41
	v_accvgpr_read_b32 v106, a42
	v_accvgpr_read_b32 v107, a43
	v_accvgpr_read_b32 v108, a44
	v_accvgpr_read_b32 v109, a45
	v_accvgpr_read_b32 v110, a46
	v_accvgpr_read_b32 v111, a47
	v_accvgpr_read_b32 v80, a48
	v_accvgpr_read_b32 v81, a49
	v_accvgpr_read_b32 v82, a50
	v_accvgpr_read_b32 v83, a51
	v_accvgpr_read_b32 v84, a52
	v_accvgpr_read_b32 v85, a53
	v_accvgpr_read_b32 v86, a54
	v_accvgpr_read_b32 v87, a55
	v_accvgpr_read_b32 v88, a56
	v_accvgpr_read_b32 v89, a57
	v_accvgpr_read_b32 v90, a58
	v_accvgpr_read_b32 v91, a59
	v_accvgpr_read_b32 v92, a60
	v_accvgpr_read_b32 v93, a61
	v_accvgpr_read_b32 v94, a62
	v_accvgpr_read_b32 v95, a63
	v_accvgpr_read_b32 v64, a16
	v_accvgpr_read_b32 v65, a17
	v_accvgpr_read_b32 v66, a18
	v_accvgpr_read_b32 v67, a19
	v_accvgpr_read_b32 v68, a20
	v_accvgpr_read_b32 v69, a21
	v_accvgpr_read_b32 v70, a22
	v_accvgpr_read_b32 v71, a23
	v_accvgpr_read_b32 v72, a24
	v_accvgpr_read_b32 v73, a25
	v_accvgpr_read_b32 v74, a26
	v_accvgpr_read_b32 v75, a27
	v_accvgpr_read_b32 v76, a28
	v_accvgpr_read_b32 v77, a29
	v_accvgpr_read_b32 v78, a30
	v_accvgpr_read_b32 v79, a31
	v_add_u32_e32 v206, s8, v215
	v_or_b32_e32 v130, s38, v217
	v_or_b32_e32 v206, v206, v236
	s_add_u32 s98, s80, 0x4cb5000
	s_addc_u32 s99, s81, 0
	v_lshlrev_b32_e32 v154, 2, v206
	global_load_dwordx4 v[238:241], v154, s[98:99]
	global_load_dwordx4 v[242:245], v154, s[98:99] offset:32
	global_load_dwordx4 v[246:249], v154, s[98:99] offset:64
	global_load_dwordx4 v[250:253], v154, s[98:99] offset:96
	global_load_dwordx4 a[224:227], v154, s[98:99] offset:128
	global_load_dwordx4 a[228:231], v154, s[98:99] offset:160
	global_load_dwordx4 a[232:235], v154, s[98:99] offset:192
	global_load_dwordx4 a[236:239], v154, s[98:99] offset:224
	v_lshlrev_b32_e32 v130, 2, v130
	s_nop 0
	v_lshl_add_u64 v[132:133], s[78:79], 0, v[130:131]
	v_add_lshl_u32 v130, v206, 0, 12
	v_lshl_add_u64 v[134:135], v[130:131], 0, v[132:133]
	global_load_dword a0, v[134:135], off
	global_load_dword a1, v[134:135], off offset:128
	v_add_lshl_u32 v130, v206, 1, 12
	v_lshl_add_u64 v[134:135], v[130:131], 0, v[132:133]
	global_load_dword a2, v[134:135], off
	global_load_dword a3, v[134:135], off offset:128
	v_add_lshl_u32 v130, v206, 2, 12
	v_lshl_add_u64 v[134:135], v[130:131], 0, v[132:133]
	global_load_dword a4, v[134:135], off
	global_load_dword a5, v[134:135], off offset:128
	v_add_lshl_u32 v130, v206, 3, 12
	v_lshl_add_u64 v[134:135], v[130:131], 0, v[132:133]
	global_load_dword a6, v[134:135], off
	global_load_dword a7, v[134:135], off offset:128
	v_add_lshl_u32 v130, v206, 8, 12
	v_lshl_add_u64 v[134:135], v[130:131], 0, v[132:133]
	global_load_dword a8, v[134:135], off
	global_load_dword a9, v[134:135], off offset:128
	v_add_lshl_u32 v130, v206, 9, 12
	v_lshl_add_u64 v[134:135], v[130:131], 0, v[132:133]
	global_load_dword a10, v[134:135], off
	global_load_dword a11, v[134:135], off offset:128
	v_add_lshl_u32 v130, v206, 10, 12
	v_lshl_add_u64 v[134:135], v[130:131], 0, v[132:133]
	global_load_dword a12, v[134:135], off
	global_load_dword a13, v[134:135], off offset:128
	v_add_lshl_u32 v130, v206, 11, 12
	v_lshl_add_u64 v[134:135], v[130:131], 0, v[132:133]
	global_load_dword a14, v[134:135], off
	global_load_dword a15, v[134:135], off offset:128
	v_add_lshl_u32 v130, v206, 16, 12
	v_lshl_add_u64 v[134:135], v[130:131], 0, v[132:133]
	global_load_dword a16, v[134:135], off
	global_load_dword a17, v[134:135], off offset:128
	v_add_lshl_u32 v130, v206, 17, 12
	v_lshl_add_u64 v[134:135], v[130:131], 0, v[132:133]
	global_load_dword a18, v[134:135], off
	global_load_dword a19, v[134:135], off offset:128
	v_add_lshl_u32 v130, v206, 18, 12
	v_lshl_add_u64 v[134:135], v[130:131], 0, v[132:133]
	global_load_dword a20, v[134:135], off
	global_load_dword a21, v[134:135], off offset:128
	v_add_lshl_u32 v130, v206, 19, 12
	v_lshl_add_u64 v[134:135], v[130:131], 0, v[132:133]
	global_load_dword a22, v[134:135], off
	global_load_dword a23, v[134:135], off offset:128
	v_add_lshl_u32 v130, v206, 24, 12
	v_lshl_add_u64 v[134:135], v[130:131], 0, v[132:133]
	global_load_dword a24, v[134:135], off
	global_load_dword a25, v[134:135], off offset:128
	v_add_lshl_u32 v130, v206, 25, 12
	v_lshl_add_u64 v[134:135], v[130:131], 0, v[132:133]
	global_load_dword a26, v[134:135], off
	global_load_dword a27, v[134:135], off offset:128
	v_add_lshl_u32 v130, v206, 26, 12
	v_lshl_add_u64 v[134:135], v[130:131], 0, v[132:133]
	global_load_dword a28, v[134:135], off
	global_load_dword a29, v[134:135], off offset:128
	v_add_lshl_u32 v130, v206, 27, 12
	v_lshl_add_u64 v[134:135], v[130:131], 0, v[132:133]
	global_load_dword a30, v[134:135], off
	global_load_dword a31, v[134:135], off offset:128
	v_add_lshl_u32 v130, v206, 32, 12
	v_lshl_add_u64 v[134:135], v[130:131], 0, v[132:133]
	global_load_dword a32, v[134:135], off
; __device__ __forceinline__ float bflo(unsigned u) { return __uint_as_float(u << 16); }
; __device__ __forceinline__ float bfhi(unsigned u) { return __uint_as_float(u & 0xffff0000u); }
; __device__ __forceinline__ float sigmoidf_(float x) { return __builtin_amdgcn_rcpf(1.f + __expf(-x)); }
; __device__ __forceinline__ int rowmap(int e, int lane) { return (e & 3) + 8 * (e >> 2) + 4 * (lane >> 5); }
; __device__ __forceinline__ void phase6(const Params& p, char* smem) {
;     ...
; #pragma unroll
;     for (int i = 0; i < 2; i++)
; #pragma unroll
;       for (int e = 0; e < 16; e++) {
;         const int row = m0 + wm * 64 + i * 32 + rowmap(e, lane);
;         float sq = 0.f;
; #pragma unroll
;         for (int j = 0; j < 2; j++) {
;           const int col = n0 + wn * 64 + j * 32 + (lane & 31);
;           float* xp = X + (size_t)row * 1024 + col;
;           float v = *xp + ((e & 1) ? bfhi(pe[i][j][e >> 1]) : bflo(pe[i][j][e >> 1])) * sigmoidf_(acc1[i][j][e]);
	global_load_dword a33, v[134:135], off offset:128
	v_add_lshl_u32 v130, v206, 33, 12
	v_lshl_add_u64 v[134:135], v[130:131], 0, v[132:133]
	global_load_dword a34, v[134:135], off
	global_load_dword a35, v[134:135], off offset:128
	v_add_lshl_u32 v130, v206, 34, 12
	v_lshl_add_u64 v[134:135], v[130:131], 0, v[132:133]
	global_load_dword a36, v[134:135], off
	global_load_dword a37, v[134:135], off offset:128
	v_add_lshl_u32 v130, v206, 35, 12
	v_lshl_add_u64 v[134:135], v[130:131], 0, v[132:133]
	global_load_dword a38, v[134:135], off
	global_load_dword a39, v[134:135], off offset:128
	v_add_lshl_u32 v130, v206, 40, 12
	v_lshl_add_u64 v[134:135], v[130:131], 0, v[132:133]
	global_load_dword a40, v[134:135], off
	global_load_dword a41, v[134:135], off offset:128
	v_add_lshl_u32 v130, v206, 41, 12
	v_lshl_add_u64 v[134:135], v[130:131], 0, v[132:133]
	global_load_dword a42, v[134:135], off
	global_load_dword a43, v[134:135], off offset:128
	v_add_lshl_u32 v130, v206, 42, 12
	v_lshl_add_u64 v[134:135], v[130:131], 0, v[132:133]
	global_load_dword a44, v[134:135], off
	global_load_dword a45, v[134:135], off offset:128
	v_add_lshl_u32 v130, v206, 43, 12
	v_lshl_add_u64 v[134:135], v[130:131], 0, v[132:133]
	global_load_dword a46, v[134:135], off
	global_load_dword a47, v[134:135], off offset:128
	v_add_lshl_u32 v130, v206, 48, 12
	v_lshl_add_u64 v[134:135], v[130:131], 0, v[132:133]
	global_load_dword a48, v[134:135], off
	global_load_dword a49, v[134:135], off offset:128
	v_add_lshl_u32 v130, v206, 49, 12
	v_lshl_add_u64 v[134:135], v[130:131], 0, v[132:133]
	global_load_dword a50, v[134:135], off
	global_load_dword a51, v[134:135], off offset:128
	v_add_lshl_u32 v130, v206, 50, 12
	v_lshl_add_u64 v[134:135], v[130:131], 0, v[132:133]
	global_load_dword a52, v[134:135], off
	global_load_dword a53, v[134:135], off offset:128
	v_add_lshl_u32 v130, v206, 51, 12
	v_lshl_add_u64 v[134:135], v[130:131], 0, v[132:133]
	global_load_dword a54, v[134:135], off
	global_load_dword a55, v[134:135], off offset:128
	v_add_lshl_u32 v130, v206, 56, 12
	v_lshl_add_u64 v[134:135], v[130:131], 0, v[132:133]
	global_load_dword a56, v[134:135], off
	global_load_dword a57, v[134:135], off offset:128
	v_add_lshl_u32 v130, v206, 57, 12
	v_lshl_add_u64 v[134:135], v[130:131], 0, v[132:133]
	global_load_dword a58, v[134:135], off
	global_load_dword a59, v[134:135], off offset:128
	v_add_lshl_u32 v130, v206, 58, 12
	v_lshl_add_u64 v[134:135], v[130:131], 0, v[132:133]
	global_load_dword a60, v[134:135], off
	global_load_dword a61, v[134:135], off offset:128
	v_add_lshl_u32 v130, v206, 59, 12
	v_lshl_add_u64 v[134:135], v[130:131], 0, v[132:133]
	global_load_dword a62, v[134:135], off
	global_load_dword a63, v[134:135], off offset:128
	s_waitcnt vmcnt(0)
	v_mul_f32_e32 v154, 0x3a800000, v238
	v_add_f32_e32 v154, 0x358637bd, v154
	v_rsq_f32_e32 v154, v154
	s_nop 0
	v_mul_f32_e32 v154, 0xbfb8aa3b, v154
	v_accvgpr_write_b32 a192, v154
	v_mul_f32_e32 v155, 0x3a800000, v239
	v_add_f32_e32 v155, 0x358637bd, v155
	v_rsq_f32_e32 v155, v155
	s_nop 0
	v_mul_f32_e32 v155, 0xbfb8aa3b, v155
	v_accvgpr_write_b32 a193, v155
	v_mul_f32_e32 v154, 0x3a800000, v240
	v_add_f32_e32 v154, 0x358637bd, v154
	v_rsq_f32_e32 v154, v154
	s_nop 0
	v_mul_f32_e32 v154, 0xbfb8aa3b, v154
	v_accvgpr_write_b32 a194, v154
	v_mul_f32_e32 v155, 0x3a800000, v241
	v_add_f32_e32 v155, 0x358637bd, v155
	v_rsq_f32_e32 v155, v155
	s_nop 0
	v_mul_f32_e32 v155, 0xbfb8aa3b, v155
	v_accvgpr_write_b32 a195, v155
	v_mul_f32_e32 v154, 0x3a800000, v242
	v_add_f32_e32 v154, 0x358637bd, v154
	v_rsq_f32_e32 v154, v154
	s_nop 0
	v_mul_f32_e32 v154, 0xbfb8aa3b, v154
	v_accvgpr_write_b32 a196, v154
	v_mul_f32_e32 v155, 0x3a800000, v243
	v_add_f32_e32 v155, 0x358637bd, v155
	v_rsq_f32_e32 v155, v155
	s_nop 0
	v_mul_f32_e32 v155, 0xbfb8aa3b, v155
	v_accvgpr_write_b32 a197, v155
	v_mul_f32_e32 v154, 0x3a800000, v244
	v_add_f32_e32 v154, 0x358637bd, v154
	v_rsq_f32_e32 v154, v154
	s_nop 0
	v_mul_f32_e32 v154, 0xbfb8aa3b, v154
	v_accvgpr_write_b32 a198, v154
	v_mul_f32_e32 v155, 0x3a800000, v245
	v_add_f32_e32 v155, 0x358637bd, v155
	v_rsq_f32_e32 v155, v155
	s_nop 0
	v_mul_f32_e32 v155, 0xbfb8aa3b, v155
	v_accvgpr_write_b32 a199, v155
	v_mul_f32_e32 v154, 0x3a800000, v246
	v_add_f32_e32 v154, 0x358637bd, v154
	v_rsq_f32_e32 v154, v154
	s_nop 0
	v_mul_f32_e32 v154, 0xbfb8aa3b, v154
	v_accvgpr_write_b32 a200, v154
	v_mul_f32_e32 v155, 0x3a800000, v247
	v_add_f32_e32 v155, 0x358637bd, v155
	v_rsq_f32_e32 v155, v155
	s_nop 0
	v_mul_f32_e32 v155, 0xbfb8aa3b, v155
	v_accvgpr_write_b32 a201, v155
	v_mul_f32_e32 v154, 0x3a800000, v248
	v_add_f32_e32 v154, 0x358637bd, v154
	v_rsq_f32_e32 v154, v154
	s_nop 0
	v_mul_f32_e32 v154, 0xbfb8aa3b, v154
	v_accvgpr_write_b32 a202, v154
	v_mul_f32_e32 v155, 0x3a800000, v249
	v_add_f32_e32 v155, 0x358637bd, v155
	v_rsq_f32_e32 v155, v155
	s_nop 0
	v_mul_f32_e32 v155, 0xbfb8aa3b, v155
	v_accvgpr_write_b32 a203, v155
	v_mul_f32_e32 v154, 0x3a800000, v250
	v_add_f32_e32 v154, 0x358637bd, v154
	v_rsq_f32_e32 v154, v154
	s_nop 0
	v_mul_f32_e32 v154, 0xbfb8aa3b, v154
	v_accvgpr_write_b32 a204, v154
	v_mul_f32_e32 v155, 0x3a800000, v251
	v_add_f32_e32 v155, 0x358637bd, v155
	v_rsq_f32_e32 v155, v155
	s_nop 0
	v_mul_f32_e32 v155, 0xbfb8aa3b, v155
	v_accvgpr_write_b32 a205, v155
	v_mul_f32_e32 v154, 0x3a800000, v252
	v_add_f32_e32 v154, 0x358637bd, v154
	v_rsq_f32_e32 v154, v154
	s_nop 0
	v_mul_f32_e32 v154, 0xbfb8aa3b, v154
	v_accvgpr_write_b32 a206, v154
	v_mul_f32_e32 v155, 0x3a800000, v253
	v_add_f32_e32 v155, 0x358637bd, v155
	v_rsq_f32_e32 v155, v155
	s_nop 0
	v_mul_f32_e32 v155, 0xbfb8aa3b, v155
; __device__ __forceinline__ float bflo(unsigned u) { return __uint_as_float(u << 16); }
; __device__ __forceinline__ float bfhi(unsigned u) { return __uint_as_float(u & 0xffff0000u); }
; __device__ __forceinline__ float sum32(float v) { v = dpp_row_sum16(v); v += __shfl_xor(v, 16); return v; }
; __device__ __forceinline__ float sigmoidf_(float x) { return __builtin_amdgcn_rcpf(1.f + __expf(-x)); }
; __device__ __forceinline__ int rowmap(int e, int lane) { return (e & 3) + 8 * (e >> 2) + 4 * (lane >> 5); }
; __device__ __forceinline__ void phase6(const Params& p, char* smem) {
;     ...
; #pragma unroll
;     for (int i = 0; i < 2; i++)
; #pragma unroll
;       for (int e = 0; e < 16; e++) {
;         const int row = m0 + wm * 64 + i * 32 + rowmap(e, lane);
;         float sq = 0.f;
; #pragma unroll
;         for (int j = 0; j < 2; j++) {
;           const int col = n0 + wn * 64 + j * 32 + (lane & 31);
;           float* xp = X + (size_t)row * 1024 + col;
;           float v = *xp + ((e & 1) ? bfhi(pe[i][j][e >> 1]) : bflo(pe[i][j][e >> 1])) * sigmoidf_(acc1[i][j][e]);
;           *xp = v;
;           sq += v * v;
;         }
;         sq = sum32(sq);
;         if ((lane & 31) == 0) atomicAdd(&SSQ3[row], sq);
	v_accvgpr_write_b32 a207, v155
	v_accvgpr_read_b32 v154, a224
	v_mul_f32_e32 v154, 0x3a800000, v154
	v_add_f32_e32 v154, 0x358637bd, v154
	v_rsq_f32_e32 v154, v154
	s_nop 0
	v_mul_f32_e32 v154, 0xbfb8aa3b, v154
	v_accvgpr_write_b32 a208, v154
	v_accvgpr_read_b32 v155, a225
	v_mul_f32_e32 v155, 0x3a800000, v155
	v_add_f32_e32 v155, 0x358637bd, v155
	v_rsq_f32_e32 v155, v155
	s_nop 0
	v_mul_f32_e32 v155, 0xbfb8aa3b, v155
	v_accvgpr_write_b32 a209, v155
	v_accvgpr_read_b32 v154, a226
	v_mul_f32_e32 v154, 0x3a800000, v154
	v_add_f32_e32 v154, 0x358637bd, v154
	v_rsq_f32_e32 v154, v154
	s_nop 0
	v_mul_f32_e32 v154, 0xbfb8aa3b, v154
	v_accvgpr_write_b32 a210, v154
	v_accvgpr_read_b32 v155, a227
	v_mul_f32_e32 v155, 0x3a800000, v155
	v_add_f32_e32 v155, 0x358637bd, v155
	v_rsq_f32_e32 v155, v155
	s_nop 0
	v_mul_f32_e32 v155, 0xbfb8aa3b, v155
	v_accvgpr_write_b32 a211, v155
	v_accvgpr_read_b32 v154, a228
	v_mul_f32_e32 v154, 0x3a800000, v154
	v_add_f32_e32 v154, 0x358637bd, v154
	v_rsq_f32_e32 v154, v154
	s_nop 0
	v_mul_f32_e32 v154, 0xbfb8aa3b, v154
	v_accvgpr_write_b32 a212, v154
	v_accvgpr_read_b32 v155, a229
	v_mul_f32_e32 v155, 0x3a800000, v155
	v_add_f32_e32 v155, 0x358637bd, v155
	v_rsq_f32_e32 v155, v155
	s_nop 0
	v_mul_f32_e32 v155, 0xbfb8aa3b, v155
	v_accvgpr_write_b32 a213, v155
	v_accvgpr_read_b32 v154, a230
	v_mul_f32_e32 v154, 0x3a800000, v154
	v_add_f32_e32 v154, 0x358637bd, v154
	v_rsq_f32_e32 v154, v154
	s_nop 0
	v_mul_f32_e32 v154, 0xbfb8aa3b, v154
	v_accvgpr_write_b32 a214, v154
	v_accvgpr_read_b32 v155, a231
	v_mul_f32_e32 v155, 0x3a800000, v155
	v_add_f32_e32 v155, 0x358637bd, v155
	v_rsq_f32_e32 v155, v155
	s_nop 0
	v_mul_f32_e32 v155, 0xbfb8aa3b, v155
	v_accvgpr_write_b32 a215, v155
	v_accvgpr_read_b32 v154, a232
	v_mul_f32_e32 v154, 0x3a800000, v154
	v_add_f32_e32 v154, 0x358637bd, v154
	v_rsq_f32_e32 v154, v154
	s_nop 0
	v_mul_f32_e32 v154, 0xbfb8aa3b, v154
	v_accvgpr_write_b32 a216, v154
	v_accvgpr_read_b32 v155, a233
	v_mul_f32_e32 v155, 0x3a800000, v155
	v_add_f32_e32 v155, 0x358637bd, v155
	v_rsq_f32_e32 v155, v155
	s_nop 0
	v_mul_f32_e32 v155, 0xbfb8aa3b, v155
	v_accvgpr_write_b32 a217, v155
	v_accvgpr_read_b32 v154, a234
	v_mul_f32_e32 v154, 0x3a800000, v154
	v_add_f32_e32 v154, 0x358637bd, v154
	v_rsq_f32_e32 v154, v154
	s_nop 0
	v_mul_f32_e32 v154, 0xbfb8aa3b, v154
	v_accvgpr_write_b32 a218, v154
	v_accvgpr_read_b32 v155, a235
	v_mul_f32_e32 v155, 0x3a800000, v155
	v_add_f32_e32 v155, 0x358637bd, v155
	v_rsq_f32_e32 v155, v155
	s_nop 0
	v_mul_f32_e32 v155, 0xbfb8aa3b, v155
	v_accvgpr_write_b32 a219, v155
	v_accvgpr_read_b32 v154, a236
	v_mul_f32_e32 v154, 0x3a800000, v154
	v_add_f32_e32 v154, 0x358637bd, v154
	v_rsq_f32_e32 v154, v154
	s_nop 0
	v_mul_f32_e32 v154, 0xbfb8aa3b, v154
	v_accvgpr_write_b32 a220, v154
	v_accvgpr_read_b32 v155, a237
	v_mul_f32_e32 v155, 0x3a800000, v155
	v_add_f32_e32 v155, 0x358637bd, v155
	v_rsq_f32_e32 v155, v155
	s_nop 0
	v_mul_f32_e32 v155, 0xbfb8aa3b, v155
	v_accvgpr_write_b32 a221, v155
	v_accvgpr_read_b32 v154, a238
	v_mul_f32_e32 v154, 0x3a800000, v154
	v_add_f32_e32 v154, 0x358637bd, v154
	v_rsq_f32_e32 v154, v154
	s_nop 0
	v_mul_f32_e32 v154, 0xbfb8aa3b, v154
	v_accvgpr_write_b32 a222, v154
	v_accvgpr_read_b32 v155, a239
	v_mul_f32_e32 v155, 0x3a800000, v155
	v_add_f32_e32 v155, 0x358637bd, v155
	v_rsq_f32_e32 v155, v155
	s_nop 0
	v_mul_f32_e32 v155, 0xbfb8aa3b, v155
	v_accvgpr_write_b32 a223, v155
	v_cvt_pk_bf16_f32 v49, v48, v49
	v_add_u32_e32 v48, s8, v215
	v_cvt_pk_bf16_f32 v206, v32, v33
	v_or_b32_e32 v32, v48, v236
	v_ashrrev_i32_e32 v33, 31, v32
	v_or_b32_e32 v130, s38, v217
	v_lshlrev_b64 v[132:133], 12, v[32:33]
	v_lshl_add_u64 v[132:133], s[78:79], 0, v[132:133]
	v_lshlrev_b32_e32 v130, 2, v130
	v_lshl_add_u64 v[132:133], v[132:133], 0, v[130:131]
	v_accvgpr_read_b32 v134, a0
	v_accvgpr_read_b32 v155, a192
	v_mul_f32_e32 v112, v155, v112
	v_exp_f32_e32 v112, v112
	v_lshlrev_b32_e32 v135, 16, v206
	v_add_f32_e32 v112, 1.0, v112
	v_rcp_f32_e32 v112, v112
	v_accvgpr_read_b32 v155, a192
	v_mul_f32_e32 v96, v155, v96
	v_exp_f32_e32 v96, v96
	s_nop 0
	v_add_f32_e32 v96, 1.0, v96
	v_rcp_f32_e32 v96, v96
	v_fmac_f32_e32 v134, v112, v135
	v_accvgpr_read_b32 v112, a1
	v_lshlrev_b32_e32 v135, 16, v49
	global_store_dword v[132:133], v134, off
	v_fmac_f32_e32 v112, v96, v135
	v_mul_f32_e32 v96, v112, v112
	v_fmac_f32_e32 v96, v134, v134
	global_store_dword v[132:133], v112, off offset:128
	s_nop 0
	v_add_f32_dpp v96, v96, v96 quad_perm:[1,0,3,2] row_mask:0xf bank_mask:0xf bound_ctrl:1
	s_nop 1
	v_add_f32_dpp v96, v96, v96 quad_perm:[2,3,0,1] row_mask:0xf bank_mask:0xf bound_ctrl:1
	s_nop 1
	v_add_f32_dpp v96, v96, v96 row_half_mirror row_mask:0xf bank_mask:0xf bound_ctrl:1
	s_nop 1
	v_add_f32_dpp v96, v96, v96 row_mirror row_mask:0xf bank_mask:0xf bound_ctrl:1
	v_mov_b32_e32 v112, v96
	s_nop 1
	v_permlane16_swap_b32_e32 v112, v112
	s_and_saveexec_b64 s[8:9], s[4:5]
	s_cbranch_execz .LBB0_1590
	v_add_f32_e32 v96, v96, v112
	v_lshl_add_u64 v[32:33], v[32:33], 2, s[92:93]
	global_atomic_add_f32 v[32:33], v96, off
; __device__ __forceinline__ float bflo(unsigned u) { return __uint_as_float(u << 16); }
; __device__ __forceinline__ float bfhi(unsigned u) { return __uint_as_float(u & 0xffff0000u); }
; __device__ __forceinline__ float sum32(float v) { v = dpp_row_sum16(v); v += __shfl_xor(v, 16); return v; }
; __device__ __forceinline__ float sigmoidf_(float x) { return __builtin_amdgcn_rcpf(1.f + __expf(-x)); }
; __device__ __forceinline__ int rowmap(int e, int lane) { return (e & 3) + 8 * (e >> 2) + 4 * (lane >> 5); }
; __device__ __forceinline__ void phase6(const Params& p, char* smem) {
;     ...
;       for (int e = 0; e < 16; e++) {
;         const int row = m0 + wm * 64 + i * 32 + rowmap(e, lane);
;         float sq = 0.f;
; #pragma unroll
;         for (int j = 0; j < 2; j++) {
;           const int col = n0 + wn * 64 + j * 32 + (lane & 31);
;           float* xp = X + (size_t)row * 1024 + col;
;           float v = *xp + ((e & 1) ? bfhi(pe[i][j][e >> 1]) : bflo(pe[i][j][e >> 1])) * sigmoidf_(acc1[i][j][e]);
;           *xp = v;
;           sq += v * v;
;         }
;         sq = sum32(sq);
;         if ((lane & 31) == 0) atomicAdd(&SSQ3[row], sq);
.LBB0_1590:
	s_or_b64 exec, exec, s[8:9]
	v_accvgpr_read_b32 v135, a84
	v_or_b32_e32 v32, v48, v135
	v_ashrrev_i32_e32 v33, 31, v32
	v_lshlrev_b64 v[132:133], 12, v[32:33]
	v_lshl_add_u64 v[132:133], s[78:79], 0, v[132:133]
	v_lshl_add_u64 v[132:133], v[132:133], 0, v[130:131]
	v_accvgpr_read_b32 v112, a2
	v_accvgpr_read_b32 v134, a3
	v_accvgpr_read_b32 v155, a193
	v_mul_f32_e32 v97, v155, v97
	v_accvgpr_read_b32 v155, a193
	v_mul_f32_e32 v96, v155, v113
	v_exp_f32_e32 v97, v97
	v_exp_f32_e32 v96, v96
	v_and_b32_e32 v49, 0xffff0000, v49
	v_and_b32_e32 v113, 0xffff0000, v206
	v_add_f32_e32 v97, 1.0, v97
	v_add_f32_e32 v96, 1.0, v96
	v_rcp_f32_e32 v97, v97
	v_rcp_f32_e32 v96, v96
	v_fmac_f32_e32 v134, v97, v49
	v_fmac_f32_e32 v112, v96, v113
	v_mul_f32_e32 v49, v134, v134
	v_fmac_f32_e32 v49, v112, v112
	global_store_dword v[132:133], v112, off
	global_store_dword v[132:133], v134, off offset:128
	v_add_f32_dpp v49, v49, v49 quad_perm:[1,0,3,2] row_mask:0xf bank_mask:0xf bound_ctrl:1
	s_nop 1
	v_add_f32_dpp v49, v49, v49 quad_perm:[2,3,0,1] row_mask:0xf bank_mask:0xf bound_ctrl:1
	s_nop 1
	v_add_f32_dpp v49, v49, v49 row_half_mirror row_mask:0xf bank_mask:0xf bound_ctrl:1
	s_nop 1
	v_add_f32_dpp v49, v49, v49 row_mirror row_mask:0xf bank_mask:0xf bound_ctrl:1
	v_mov_b32_e32 v96, v49
	s_nop 1
	v_permlane16_swap_b32_e32 v96, v96
	s_mov_b64 s[8:9], exec
	s_and_b64 s[10:11], s[8:9], s[4:5]
	v_accvgpr_read_b32 v132, a85
	v_accvgpr_read_b32 v133, a86
	v_accvgpr_read_b32 v134, a87
	v_accvgpr_read_b32 v148, a88
	v_accvgpr_read_b32 v149, a89
	v_accvgpr_read_b32 v150, a90
	v_accvgpr_read_b32 v151, a91
	v_accvgpr_read_b32 v152, a92
	s_mov_b64 exec, s[10:11]
	s_cbranch_execz .LBB0_1592
	v_add_f32_e32 v49, v49, v96
	v_lshl_add_u64 v[32:33], v[32:33], 2, s[92:93]
	global_atomic_add_f32 v[32:33], v49, off
.LBB0_1592:
	s_or_b64 exec, exec, s[8:9]
	v_or_b32_e32 v32, v48, v132
	v_ashrrev_i32_e32 v33, 31, v32
	v_lshlrev_b64 v[96:97], 12, v[32:33]
	v_lshl_add_u64 v[96:97], s[78:79], 0, v[96:97]
	v_lshl_add_u64 v[96:97], v[96:97], 0, v[130:131]
	v_accvgpr_read_b32 v112, a4
	v_accvgpr_read_b32 v113, a5
	v_accvgpr_read_b32 v155, a194
	v_mul_f32_e32 v98, v155, v98
	v_accvgpr_read_b32 v155, a194
	v_mul_f32_e32 v49, v155, v114
	v_exp_f32_e32 v98, v98
	v_exp_f32_e32 v49, v49
	v_cvt_pk_bf16_f32 v34, v34, v35
	v_cvt_pk_bf16_f32 v35, v50, v51
	v_add_f32_e32 v50, 1.0, v98
	v_add_f32_e32 v49, 1.0, v49
	v_rcp_f32_e32 v50, v50
	v_rcp_f32_e32 v49, v49
	v_lshlrev_b32_e32 v98, 16, v35
	v_lshlrev_b32_e32 v51, 16, v34
	v_fmac_f32_e32 v112, v49, v51
	v_fmac_f32_e32 v113, v50, v98
	v_mul_f32_e32 v49, v113, v113
	v_fmac_f32_e32 v49, v112, v112
	global_store_dword v[96:97], v112, off
	global_store_dword v[96:97], v113, off offset:128
	v_add_f32_dpp v49, v49, v49 quad_perm:[1,0,3,2] row_mask:0xf bank_mask:0xf bound_ctrl:1
	s_nop 1
	v_add_f32_dpp v49, v49, v49 quad_perm:[2,3,0,1] row_mask:0xf bank_mask:0xf bound_ctrl:1
	s_nop 1
	v_add_f32_dpp v49, v49, v49 row_half_mirror row_mask:0xf bank_mask:0xf bound_ctrl:1
	s_nop 1
	v_add_f32_dpp v49, v49, v49 row_mirror row_mask:0xf bank_mask:0xf bound_ctrl:1
	v_mov_b32_e32 v50, v49
	s_nop 1
	v_permlane16_swap_b32_e32 v50, v50
	s_and_saveexec_b64 s[8:9], s[4:5]
	s_cbranch_execz .LBB0_1594
	v_add_f32_e32 v49, v49, v50
	v_lshl_add_u64 v[32:33], v[32:33], 2, s[92:93]
	global_atomic_add_f32 v[32:33], v49, off
.LBB0_1594:
	s_or_b64 exec, exec, s[8:9]
	v_or_b32_e32 v32, v48, v133
	v_ashrrev_i32_e32 v33, 31, v32
	v_lshlrev_b64 v[50:51], 12, v[32:33]
	v_lshl_add_u64 v[50:51], s[78:79], 0, v[50:51]
	v_lshl_add_u64 v[50:51], v[50:51], 0, v[130:131]
	v_accvgpr_read_b32 v49, a6
	v_accvgpr_read_b32 v96, a7
	v_accvgpr_read_b32 v155, a195
	v_mul_f32_e32 v98, v155, v99
	v_accvgpr_read_b32 v155, a195
	v_mul_f32_e32 v97, v155, v115
	v_exp_f32_e32 v98, v98
	v_exp_f32_e32 v97, v97
	v_and_b32_e32 v35, 0xffff0000, v35
	v_and_b32_e32 v34, 0xffff0000, v34
	v_add_f32_e32 v98, 1.0, v98
	v_add_f32_e32 v97, 1.0, v97
	v_rcp_f32_e32 v98, v98
	v_rcp_f32_e32 v97, v97
	v_fmac_f32_e32 v96, v98, v35
	v_fmac_f32_e32 v49, v97, v34
	v_mul_f32_e32 v34, v96, v96
	v_fmac_f32_e32 v34, v49, v49
	global_store_dword v[50:51], v49, off
	global_store_dword v[50:51], v96, off offset:128
	v_add_f32_dpp v34, v34, v34 quad_perm:[1,0,3,2] row_mask:0xf bank_mask:0xf bound_ctrl:1
	s_nop 1
	v_add_f32_dpp v34, v34, v34 quad_perm:[2,3,0,1] row_mask:0xf bank_mask:0xf bound_ctrl:1
	s_nop 1
	v_add_f32_dpp v34, v34, v34 row_half_mirror row_mask:0xf bank_mask:0xf bound_ctrl:1
	s_nop 1
	v_add_f32_dpp v34, v34, v34 row_mirror row_mask:0xf bank_mask:0xf bound_ctrl:1
	v_mov_b32_e32 v35, v34
	s_nop 1
	v_permlane16_swap_b32_e32 v35, v35
	s_mov_b64 s[8:9], exec
	s_and_b64 s[10:11], s[8:9], s[4:5]
	v_accvgpr_read_b32 v99, a93
	v_accvgpr_read_b32 v112, a94
	v_accvgpr_read_b32 v113, a95
	v_accvgpr_read_b32 v114, a96
	v_accvgpr_read_b32 v115, a97
	v_accvgpr_read_b32 v153, a98
	s_mov_b64 exec, s[10:11]
	s_cbranch_execz .LBB0_1596
	v_add_f32_e32 v34, v34, v35
	v_lshl_add_u64 v[32:33], v[32:33], 2, s[92:93]
	global_atomic_add_f32 v[32:33], v34, off
; __device__ __forceinline__ float bflo(unsigned u) { return __uint_as_float(u << 16); }
; __device__ __forceinline__ float bfhi(unsigned u) { return __uint_as_float(u & 0xffff0000u); }
; __device__ __forceinline__ float sum32(float v) { v = dpp_row_sum16(v); v += __shfl_xor(v, 16); return v; }
; __device__ __forceinline__ float sigmoidf_(float x) { return __builtin_amdgcn_rcpf(1.f + __expf(-x)); }
; __device__ __forceinline__ int rowmap(int e, int lane) { return (e & 3) + 8 * (e >> 2) + 4 * (lane >> 5); }
; __device__ __forceinline__ void phase6(const Params& p, char* smem) {
;     ...
;       for (int e = 0; e < 16; e++) {
;         const int row = m0 + wm * 64 + i * 32 + rowmap(e, lane);
;         float sq = 0.f;
; #pragma unroll
;         for (int j = 0; j < 2; j++) {
;           const int col = n0 + wn * 64 + j * 32 + (lane & 31);
;           float* xp = X + (size_t)row * 1024 + col;
;           float v = *xp + ((e & 1) ? bfhi(pe[i][j][e >> 1]) : bflo(pe[i][j][e >> 1])) * sigmoidf_(acc1[i][j][e]);
;           *xp = v;
;           sq += v * v;
;         }
;         sq = sum32(sq);
;         if ((lane & 31) == 0) atomicAdd(&SSQ3[row], sq);
.LBB0_1596:
	s_or_b64 exec, exec, s[8:9]
	v_or_b32_e32 v32, v48, v134
	v_ashrrev_i32_e32 v33, 31, v32
	v_lshlrev_b64 v[34:35], 12, v[32:33]
	v_lshl_add_u64 v[34:35], s[78:79], 0, v[34:35]
	v_lshl_add_u64 v[50:51], v[34:35], 0, v[130:131]
	v_accvgpr_read_b32 v49, a8
	v_accvgpr_read_b32 v96, a9
	v_accvgpr_read_b32 v155, a196
	v_mul_f32_e32 v35, v155, v100
	v_accvgpr_read_b32 v155, a196
	v_mul_f32_e32 v34, v155, v116
	v_exp_f32_e32 v98, v35
	v_exp_f32_e32 v97, v34
	v_cvt_pk_bf16_f32 v34, v36, v37
	v_cvt_pk_bf16_f32 v35, v52, v53
	v_add_f32_e32 v37, 1.0, v98
	v_add_f32_e32 v36, 1.0, v97
	v_rcp_f32_e32 v37, v37
	v_rcp_f32_e32 v36, v36
	v_lshlrev_b32_e32 v53, 16, v35
	v_lshlrev_b32_e32 v52, 16, v34
	v_fmac_f32_e32 v49, v36, v52
	v_fmac_f32_e32 v96, v37, v53
	v_mul_f32_e32 v36, v96, v96
	v_fmac_f32_e32 v36, v49, v49
	global_store_dword v[50:51], v49, off
	global_store_dword v[50:51], v96, off offset:128
	v_add_f32_dpp v36, v36, v36 quad_perm:[1,0,3,2] row_mask:0xf bank_mask:0xf bound_ctrl:1
	s_nop 1
	v_add_f32_dpp v36, v36, v36 quad_perm:[2,3,0,1] row_mask:0xf bank_mask:0xf bound_ctrl:1
	s_nop 1
	v_add_f32_dpp v36, v36, v36 row_half_mirror row_mask:0xf bank_mask:0xf bound_ctrl:1
	s_nop 1
	v_add_f32_dpp v36, v36, v36 row_mirror row_mask:0xf bank_mask:0xf bound_ctrl:1
	v_mov_b32_e32 v37, v36
	s_nop 1
	v_permlane16_swap_b32_e32 v37, v37
	s_and_saveexec_b64 s[8:9], s[4:5]
	s_cbranch_execz .LBB0_1598
	v_add_f32_e32 v36, v36, v37
	v_lshl_add_u64 v[32:33], v[32:33], 2, s[92:93]
	global_atomic_add_f32 v[32:33], v36, off
.LBB0_1598:
	s_or_b64 exec, exec, s[8:9]
	v_or_b32_e32 v32, v48, v148
	v_ashrrev_i32_e32 v33, 31, v32
	v_lshlrev_b64 v[36:37], 12, v[32:33]
	v_lshl_add_u64 v[36:37], s[78:79], 0, v[36:37]
	v_lshl_add_u64 v[36:37], v[36:37], 0, v[130:131]
	v_accvgpr_read_b32 v49, a10
	v_accvgpr_read_b32 v50, a11
	v_accvgpr_read_b32 v155, a197
	v_mul_f32_e32 v52, v155, v101
	v_accvgpr_read_b32 v155, a197
	v_mul_f32_e32 v51, v155, v117
	v_exp_f32_e32 v52, v52
	v_exp_f32_e32 v51, v51
	v_and_b32_e32 v35, 0xffff0000, v35
	v_and_b32_e32 v34, 0xffff0000, v34
	v_add_f32_e32 v52, 1.0, v52
	v_add_f32_e32 v51, 1.0, v51
	v_rcp_f32_e32 v52, v52
	v_rcp_f32_e32 v51, v51
	v_fmac_f32_e32 v50, v52, v35
	v_fmac_f32_e32 v49, v51, v34
	v_mul_f32_e32 v34, v50, v50
	v_fmac_f32_e32 v34, v49, v49
	global_store_dword v[36:37], v49, off
	global_store_dword v[36:37], v50, off offset:128
	v_add_f32_dpp v34, v34, v34 quad_perm:[1,0,3,2] row_mask:0xf bank_mask:0xf bound_ctrl:1
	s_nop 1
	v_add_f32_dpp v34, v34, v34 quad_perm:[2,3,0,1] row_mask:0xf bank_mask:0xf bound_ctrl:1
	s_nop 1
	v_add_f32_dpp v34, v34, v34 row_half_mirror row_mask:0xf bank_mask:0xf bound_ctrl:1
	s_nop 1
	v_add_f32_dpp v34, v34, v34 row_mirror row_mask:0xf bank_mask:0xf bound_ctrl:1
	v_mov_b32_e32 v35, v34
	s_nop 1
	v_permlane16_swap_b32_e32 v35, v35
	s_and_saveexec_b64 s[8:9], s[4:5]
	s_cbranch_execz .LBB0_1600
	v_add_f32_e32 v34, v34, v35
	v_lshl_add_u64 v[32:33], v[32:33], 2, s[92:93]
	global_atomic_add_f32 v[32:33], v34, off
.LBB0_1600:
	s_or_b64 exec, exec, s[8:9]
	v_or_b32_e32 v32, v48, v149
	v_ashrrev_i32_e32 v33, 31, v32
	v_lshlrev_b64 v[34:35], 12, v[32:33]
	v_lshl_add_u64 v[34:35], s[78:79], 0, v[34:35]
	v_lshl_add_u64 v[50:51], v[34:35], 0, v[130:131]
	v_accvgpr_read_b32 v49, a12
	v_accvgpr_read_b32 v52, a13
	v_accvgpr_read_b32 v155, a198
	v_mul_f32_e32 v35, v155, v102
	v_accvgpr_read_b32 v155, a198
	v_mul_f32_e32 v34, v155, v118
	v_exp_f32_e32 v37, v35
	v_exp_f32_e32 v36, v34
	v_cvt_pk_bf16_f32 v35, v54, v55
	v_cvt_pk_bf16_f32 v34, v38, v39
	v_add_f32_e32 v37, 1.0, v37
	v_add_f32_e32 v36, 1.0, v36
	v_rcp_f32_e32 v37, v37
	v_rcp_f32_e32 v36, v36
	v_lshlrev_b32_e32 v39, 16, v35
	v_lshlrev_b32_e32 v38, 16, v34
	v_fmac_f32_e32 v49, v36, v38
	v_fmac_f32_e32 v52, v37, v39
	v_mul_f32_e32 v36, v52, v52
	v_fmac_f32_e32 v36, v49, v49
	global_store_dword v[50:51], v49, off
	global_store_dword v[50:51], v52, off offset:128
	v_add_f32_dpp v36, v36, v36 quad_perm:[1,0,3,2] row_mask:0xf bank_mask:0xf bound_ctrl:1
	s_nop 1
	v_add_f32_dpp v36, v36, v36 quad_perm:[2,3,0,1] row_mask:0xf bank_mask:0xf bound_ctrl:1
	s_nop 1
	v_add_f32_dpp v36, v36, v36 row_half_mirror row_mask:0xf bank_mask:0xf bound_ctrl:1
	s_nop 1
	v_add_f32_dpp v36, v36, v36 row_mirror row_mask:0xf bank_mask:0xf bound_ctrl:1
	v_mov_b32_e32 v37, v36
	s_nop 1
	v_permlane16_swap_b32_e32 v37, v37
	s_and_saveexec_b64 s[8:9], s[4:5]
	s_cbranch_execz .LBB0_1602
	v_add_f32_e32 v36, v36, v37
	v_lshl_add_u64 v[32:33], v[32:33], 2, s[92:93]
	global_atomic_add_f32 v[32:33], v36, off
.LBB0_1602:
	s_or_b64 exec, exec, s[8:9]
	v_or_b32_e32 v32, v48, v150
	v_ashrrev_i32_e32 v33, 31, v32
	v_lshlrev_b64 v[36:37], 12, v[32:33]
	v_lshl_add_u64 v[36:37], s[78:79], 0, v[36:37]
	v_lshl_add_u64 v[36:37], v[36:37], 0, v[130:131]
	v_accvgpr_read_b32 v38, a14
	v_accvgpr_read_b32 v39, a15
	v_accvgpr_read_b32 v155, a199
	v_mul_f32_e32 v50, v155, v103
	v_accvgpr_read_b32 v155, a199
	v_mul_f32_e32 v49, v155, v119
	v_exp_f32_e32 v50, v50
	v_exp_f32_e32 v49, v49
	v_and_b32_e32 v35, 0xffff0000, v35
	v_and_b32_e32 v34, 0xffff0000, v34
	v_add_f32_e32 v50, 1.0, v50
	v_add_f32_e32 v49, 1.0, v49
	v_rcp_f32_e32 v50, v50
	v_rcp_f32_e32 v49, v49
	v_fmac_f32_e32 v39, v50, v35
	v_fmac_f32_e32 v38, v49, v34
	v_mul_f32_e32 v34, v39, v39
	v_fmac_f32_e32 v34, v38, v38
	global_store_dword v[36:37], v38, off
	global_store_dword v[36:37], v39, off offset:128
	v_add_f32_dpp v34, v34, v34 quad_perm:[1,0,3,2] row_mask:0xf bank_mask:0xf bound_ctrl:1
	s_nop 1
	v_add_f32_dpp v34, v34, v34 quad_perm:[2,3,0,1] row_mask:0xf bank_mask:0xf bound_ctrl:1
	s_nop 1
	v_add_f32_dpp v34, v34, v34 row_half_mirror row_mask:0xf bank_mask:0xf bound_ctrl:1
	s_nop 1
	v_add_f32_dpp v34, v34, v34 row_mirror row_mask:0xf bank_mask:0xf bound_ctrl:1
	v_mov_b32_e32 v35, v34
	s_nop 1
	v_permlane16_swap_b32_e32 v35, v35
	s_and_saveexec_b64 s[8:9], s[4:5]
	s_cbranch_execz .LBB0_1604
	v_add_f32_e32 v34, v34, v35
	v_lshl_add_u64 v[32:33], v[32:33], 2, s[92:93]
	global_atomic_add_f32 v[32:33], v34, off
; __device__ __forceinline__ float bflo(unsigned u) { return __uint_as_float(u << 16); }
; __device__ __forceinline__ float bfhi(unsigned u) { return __uint_as_float(u & 0xffff0000u); }
; __device__ __forceinline__ float sum32(float v) { v = dpp_row_sum16(v); v += __shfl_xor(v, 16); return v; }
; __device__ __forceinline__ float sigmoidf_(float x) { return __builtin_amdgcn_rcpf(1.f + __expf(-x)); }
; __device__ __forceinline__ int rowmap(int e, int lane) { return (e & 3) + 8 * (e >> 2) + 4 * (lane >> 5); }
; __device__ __forceinline__ void phase6(const Params& p, char* smem) {
;     ...
;       for (int e = 0; e < 16; e++) {
;         const int row = m0 + wm * 64 + i * 32 + rowmap(e, lane);
;         float sq = 0.f;
; #pragma unroll
;         for (int j = 0; j < 2; j++) {
;           const int col = n0 + wn * 64 + j * 32 + (lane & 31);
;           float* xp = X + (size_t)row * 1024 + col;
;           float v = *xp + ((e & 1) ? bfhi(pe[i][j][e >> 1]) : bflo(pe[i][j][e >> 1])) * sigmoidf_(acc1[i][j][e]);
;           *xp = v;
;           sq += v * v;
;         }
;         sq = sum32(sq);
;         if ((lane & 31) == 0) atomicAdd(&SSQ3[row], sq);
.LBB0_1604:
	s_or_b64 exec, exec, s[8:9]
	v_or_b32_e32 v32, v48, v151
	v_ashrrev_i32_e32 v33, 31, v32
	v_lshlrev_b64 v[34:35], 12, v[32:33]
	v_lshl_add_u64 v[34:35], s[78:79], 0, v[34:35]
	v_lshl_add_u64 v[38:39], v[34:35], 0, v[130:131]
	v_accvgpr_read_b32 v49, a16
	v_accvgpr_read_b32 v50, a17
	v_accvgpr_read_b32 v155, a200
	v_mul_f32_e32 v35, v155, v104
	v_accvgpr_read_b32 v155, a200
	v_mul_f32_e32 v34, v155, v120
	v_exp_f32_e32 v37, v35
	v_exp_f32_e32 v36, v34
	v_cvt_pk_bf16_f32 v35, v56, v57
	v_cvt_pk_bf16_f32 v34, v40, v41
	v_add_f32_e32 v37, 1.0, v37
	v_add_f32_e32 v36, 1.0, v36
	v_rcp_f32_e32 v37, v37
	v_rcp_f32_e32 v36, v36
	v_lshlrev_b32_e32 v41, 16, v35
	v_lshlrev_b32_e32 v40, 16, v34
	v_fmac_f32_e32 v49, v36, v40
	v_fmac_f32_e32 v50, v37, v41
	v_mul_f32_e32 v36, v50, v50
	v_fmac_f32_e32 v36, v49, v49
	global_store_dword v[38:39], v49, off
	global_store_dword v[38:39], v50, off offset:128
	v_add_f32_dpp v36, v36, v36 quad_perm:[1,0,3,2] row_mask:0xf bank_mask:0xf bound_ctrl:1
	s_nop 1
	v_add_f32_dpp v36, v36, v36 quad_perm:[2,3,0,1] row_mask:0xf bank_mask:0xf bound_ctrl:1
	s_nop 1
	v_add_f32_dpp v36, v36, v36 row_half_mirror row_mask:0xf bank_mask:0xf bound_ctrl:1
	s_nop 1
	v_add_f32_dpp v36, v36, v36 row_mirror row_mask:0xf bank_mask:0xf bound_ctrl:1
	v_mov_b32_e32 v37, v36
	s_nop 1
	v_permlane16_swap_b32_e32 v37, v37
	s_and_saveexec_b64 s[8:9], s[4:5]
	s_cbranch_execz .LBB0_1606
	v_add_f32_e32 v36, v36, v37
	v_lshl_add_u64 v[32:33], v[32:33], 2, s[92:93]
	global_atomic_add_f32 v[32:33], v36, off
.LBB0_1606:
	s_or_b64 exec, exec, s[8:9]
	v_or_b32_e32 v32, v48, v152
	v_ashrrev_i32_e32 v33, 31, v32
	v_lshlrev_b64 v[36:37], 12, v[32:33]
	v_lshl_add_u64 v[36:37], s[78:79], 0, v[36:37]
	v_lshl_add_u64 v[36:37], v[36:37], 0, v[130:131]
	v_accvgpr_read_b32 v38, a18
	v_accvgpr_read_b32 v39, a19
	v_accvgpr_read_b32 v155, a201
	v_mul_f32_e32 v41, v155, v105
	v_accvgpr_read_b32 v155, a201
	v_mul_f32_e32 v40, v155, v121
	v_exp_f32_e32 v41, v41
	v_exp_f32_e32 v40, v40
	v_and_b32_e32 v35, 0xffff0000, v35
	v_and_b32_e32 v34, 0xffff0000, v34
	v_add_f32_e32 v41, 1.0, v41
	v_add_f32_e32 v40, 1.0, v40
	v_rcp_f32_e32 v41, v41
	v_rcp_f32_e32 v40, v40
	v_fmac_f32_e32 v39, v41, v35
	v_fmac_f32_e32 v38, v40, v34
	v_mul_f32_e32 v34, v39, v39
	v_fmac_f32_e32 v34, v38, v38
	global_store_dword v[36:37], v38, off
	global_store_dword v[36:37], v39, off offset:128
	v_add_f32_dpp v34, v34, v34 quad_perm:[1,0,3,2] row_mask:0xf bank_mask:0xf bound_ctrl:1
	s_nop 1
	v_add_f32_dpp v34, v34, v34 quad_perm:[2,3,0,1] row_mask:0xf bank_mask:0xf bound_ctrl:1
	s_nop 1
	v_add_f32_dpp v34, v34, v34 row_half_mirror row_mask:0xf bank_mask:0xf bound_ctrl:1
	s_nop 1
	v_add_f32_dpp v34, v34, v34 row_mirror row_mask:0xf bank_mask:0xf bound_ctrl:1
	v_mov_b32_e32 v35, v34
	s_nop 1
	v_permlane16_swap_b32_e32 v35, v35
	s_and_saveexec_b64 s[8:9], s[4:5]
	s_cbranch_execz .LBB0_1608
	v_add_f32_e32 v34, v34, v35
	v_lshl_add_u64 v[32:33], v[32:33], 2, s[92:93]
	global_atomic_add_f32 v[32:33], v34, off
.LBB0_1608:
	s_or_b64 exec, exec, s[8:9]
	v_or_b32_e32 v32, v48, v99
	v_ashrrev_i32_e32 v33, 31, v32
	v_lshlrev_b64 v[34:35], 12, v[32:33]
	v_lshl_add_u64 v[34:35], s[78:79], 0, v[34:35]
	v_lshl_add_u64 v[38:39], v[34:35], 0, v[130:131]
	v_accvgpr_read_b32 v40, a20
	v_accvgpr_read_b32 v41, a21
	v_accvgpr_read_b32 v155, a202
	v_mul_f32_e32 v35, v155, v106
	v_accvgpr_read_b32 v155, a202
	v_mul_f32_e32 v34, v155, v122
	v_exp_f32_e32 v37, v35
	v_exp_f32_e32 v36, v34
	v_cvt_pk_bf16_f32 v35, v58, v59
	v_cvt_pk_bf16_f32 v34, v42, v43
	v_add_f32_e32 v37, 1.0, v37
	v_add_f32_e32 v36, 1.0, v36
	v_rcp_f32_e32 v37, v37
	v_rcp_f32_e32 v36, v36
	v_lshlrev_b32_e32 v43, 16, v35
	v_lshlrev_b32_e32 v42, 16, v34
	v_fmac_f32_e32 v40, v36, v42
	v_fmac_f32_e32 v41, v37, v43
	v_mul_f32_e32 v36, v41, v41
	v_fmac_f32_e32 v36, v40, v40
	global_store_dword v[38:39], v40, off
	global_store_dword v[38:39], v41, off offset:128
	v_add_f32_dpp v36, v36, v36 quad_perm:[1,0,3,2] row_mask:0xf bank_mask:0xf bound_ctrl:1
	s_nop 1
	v_add_f32_dpp v36, v36, v36 quad_perm:[2,3,0,1] row_mask:0xf bank_mask:0xf bound_ctrl:1
	s_nop 1
	v_add_f32_dpp v36, v36, v36 row_half_mirror row_mask:0xf bank_mask:0xf bound_ctrl:1
	s_nop 1
	v_add_f32_dpp v36, v36, v36 row_mirror row_mask:0xf bank_mask:0xf bound_ctrl:1
	v_mov_b32_e32 v37, v36
	s_nop 1
	v_permlane16_swap_b32_e32 v37, v37
	s_and_saveexec_b64 s[8:9], s[4:5]
	s_cbranch_execz .LBB0_1610
	v_add_f32_e32 v36, v36, v37
	v_lshl_add_u64 v[32:33], v[32:33], 2, s[92:93]
	global_atomic_add_f32 v[32:33], v36, off
.LBB0_1610:
	s_or_b64 exec, exec, s[8:9]
	v_or_b32_e32 v32, v48, v112
	v_ashrrev_i32_e32 v33, 31, v32
	v_lshlrev_b64 v[36:37], 12, v[32:33]
	v_lshl_add_u64 v[36:37], s[78:79], 0, v[36:37]
	v_lshl_add_u64 v[36:37], v[36:37], 0, v[130:131]
	v_accvgpr_read_b32 v38, a22
	v_accvgpr_read_b32 v39, a23
	v_accvgpr_read_b32 v155, a203
	v_mul_f32_e32 v41, v155, v107
	v_accvgpr_read_b32 v155, a203
	v_mul_f32_e32 v40, v155, v123
	v_exp_f32_e32 v41, v41
	v_exp_f32_e32 v40, v40
	v_and_b32_e32 v35, 0xffff0000, v35
	v_and_b32_e32 v34, 0xffff0000, v34
	v_add_f32_e32 v41, 1.0, v41
	v_add_f32_e32 v40, 1.0, v40
	v_rcp_f32_e32 v41, v41
	v_rcp_f32_e32 v40, v40
	v_fmac_f32_e32 v39, v41, v35
	v_fmac_f32_e32 v38, v40, v34
	v_mul_f32_e32 v34, v39, v39
	v_fmac_f32_e32 v34, v38, v38
	global_store_dword v[36:37], v38, off
	global_store_dword v[36:37], v39, off offset:128
	v_add_f32_dpp v34, v34, v34 quad_perm:[1,0,3,2] row_mask:0xf bank_mask:0xf bound_ctrl:1
	s_nop 1
	v_add_f32_dpp v34, v34, v34 quad_perm:[2,3,0,1] row_mask:0xf bank_mask:0xf bound_ctrl:1
	s_nop 1
	v_add_f32_dpp v34, v34, v34 row_half_mirror row_mask:0xf bank_mask:0xf bound_ctrl:1
	s_nop 1
	v_add_f32_dpp v34, v34, v34 row_mirror row_mask:0xf bank_mask:0xf bound_ctrl:1
	v_mov_b32_e32 v35, v34
	s_nop 1
	v_permlane16_swap_b32_e32 v35, v35
	s_and_saveexec_b64 s[8:9], s[4:5]
	s_cbranch_execz .LBB0_1612
	v_add_f32_e32 v34, v34, v35
	v_lshl_add_u64 v[32:33], v[32:33], 2, s[92:93]
	global_atomic_add_f32 v[32:33], v34, off
; __device__ __forceinline__ float bflo(unsigned u) { return __uint_as_float(u << 16); }
; __device__ __forceinline__ float bfhi(unsigned u) { return __uint_as_float(u & 0xffff0000u); }
; __device__ __forceinline__ float sum32(float v) { v = dpp_row_sum16(v); v += __shfl_xor(v, 16); return v; }
; __device__ __forceinline__ float sigmoidf_(float x) { return __builtin_amdgcn_rcpf(1.f + __expf(-x)); }
; __device__ __forceinline__ int rowmap(int e, int lane) { return (e & 3) + 8 * (e >> 2) + 4 * (lane >> 5); }
; __device__ __forceinline__ void phase6(const Params& p, char* smem) {
;     ...
;       for (int e = 0; e < 16; e++) {
;         const int row = m0 + wm * 64 + i * 32 + rowmap(e, lane);
;         float sq = 0.f;
; #pragma unroll
;         for (int j = 0; j < 2; j++) {
;           const int col = n0 + wn * 64 + j * 32 + (lane & 31);
;           float* xp = X + (size_t)row * 1024 + col;
;           float v = *xp + ((e & 1) ? bfhi(pe[i][j][e >> 1]) : bflo(pe[i][j][e >> 1])) * sigmoidf_(acc1[i][j][e]);
;           *xp = v;
;           sq += v * v;
;         }
;         sq = sum32(sq);
;         if ((lane & 31) == 0) atomicAdd(&SSQ3[row], sq);
.LBB0_1612:
	s_or_b64 exec, exec, s[8:9]
	v_or_b32_e32 v32, v48, v113
	v_ashrrev_i32_e32 v33, 31, v32
	v_lshlrev_b64 v[34:35], 12, v[32:33]
	v_lshl_add_u64 v[34:35], s[78:79], 0, v[34:35]
	v_lshl_add_u64 v[38:39], v[34:35], 0, v[130:131]
	v_accvgpr_read_b32 v40, a24
	v_accvgpr_read_b32 v41, a25
	v_accvgpr_read_b32 v155, a204
	v_mul_f32_e32 v35, v155, v108
	v_accvgpr_read_b32 v155, a204
	v_mul_f32_e32 v34, v155, v124
	v_exp_f32_e32 v37, v35
	v_exp_f32_e32 v36, v34
	v_cvt_pk_bf16_f32 v35, v60, v61
	v_cvt_pk_bf16_f32 v34, v44, v45
	v_add_f32_e32 v37, 1.0, v37
	v_add_f32_e32 v36, 1.0, v36
	v_rcp_f32_e32 v37, v37
	v_rcp_f32_e32 v36, v36
	v_lshlrev_b32_e32 v43, 16, v35
	v_lshlrev_b32_e32 v42, 16, v34
	v_fmac_f32_e32 v40, v36, v42
	v_fmac_f32_e32 v41, v37, v43
	v_mul_f32_e32 v36, v41, v41
	v_fmac_f32_e32 v36, v40, v40
	global_store_dword v[38:39], v40, off
	global_store_dword v[38:39], v41, off offset:128
	v_add_f32_dpp v36, v36, v36 quad_perm:[1,0,3,2] row_mask:0xf bank_mask:0xf bound_ctrl:1
	s_nop 1
	v_add_f32_dpp v36, v36, v36 quad_perm:[2,3,0,1] row_mask:0xf bank_mask:0xf bound_ctrl:1
	s_nop 1
	v_add_f32_dpp v36, v36, v36 row_half_mirror row_mask:0xf bank_mask:0xf bound_ctrl:1
	s_nop 1
	v_add_f32_dpp v36, v36, v36 row_mirror row_mask:0xf bank_mask:0xf bound_ctrl:1
	v_mov_b32_e32 v37, v36
	s_nop 1
	v_permlane16_swap_b32_e32 v37, v37
	s_and_saveexec_b64 s[8:9], s[4:5]
	s_cbranch_execz .LBB0_1614
	v_add_f32_e32 v36, v36, v37
	v_lshl_add_u64 v[32:33], v[32:33], 2, s[92:93]
	global_atomic_add_f32 v[32:33], v36, off
.LBB0_1614:
	s_or_b64 exec, exec, s[8:9]
	v_or_b32_e32 v32, v48, v114
	v_ashrrev_i32_e32 v33, 31, v32
	v_lshlrev_b64 v[36:37], 12, v[32:33]
	v_lshl_add_u64 v[36:37], s[78:79], 0, v[36:37]
	v_lshl_add_u64 v[36:37], v[36:37], 0, v[130:131]
	v_accvgpr_read_b32 v38, a26
	v_accvgpr_read_b32 v39, a27
	v_accvgpr_read_b32 v155, a205
	v_mul_f32_e32 v41, v155, v109
	v_accvgpr_read_b32 v155, a205
	v_mul_f32_e32 v40, v155, v125
	v_exp_f32_e32 v41, v41
	v_exp_f32_e32 v40, v40
	v_and_b32_e32 v35, 0xffff0000, v35
	v_and_b32_e32 v34, 0xffff0000, v34
	v_add_f32_e32 v41, 1.0, v41
	v_add_f32_e32 v40, 1.0, v40
	v_rcp_f32_e32 v41, v41
	v_rcp_f32_e32 v40, v40
	v_fmac_f32_e32 v39, v41, v35
	v_fmac_f32_e32 v38, v40, v34
	v_mul_f32_e32 v34, v39, v39
	v_fmac_f32_e32 v34, v38, v38
	global_store_dword v[36:37], v38, off
	global_store_dword v[36:37], v39, off offset:128
	v_add_f32_dpp v34, v34, v34 quad_perm:[1,0,3,2] row_mask:0xf bank_mask:0xf bound_ctrl:1
	s_nop 1
	v_add_f32_dpp v34, v34, v34 quad_perm:[2,3,0,1] row_mask:0xf bank_mask:0xf bound_ctrl:1
	s_nop 1
	v_add_f32_dpp v34, v34, v34 row_half_mirror row_mask:0xf bank_mask:0xf bound_ctrl:1
	s_nop 1
	v_add_f32_dpp v34, v34, v34 row_mirror row_mask:0xf bank_mask:0xf bound_ctrl:1
	v_mov_b32_e32 v35, v34
	s_nop 1
	v_permlane16_swap_b32_e32 v35, v35
	s_and_saveexec_b64 s[8:9], s[4:5]
	s_cbranch_execz .LBB0_1616
	v_add_f32_e32 v34, v34, v35
	v_lshl_add_u64 v[32:33], v[32:33], 2, s[92:93]
	global_atomic_add_f32 v[32:33], v34, off
.LBB0_1616:
	s_or_b64 exec, exec, s[8:9]
	v_or_b32_e32 v32, v48, v115
	v_ashrrev_i32_e32 v33, 31, v32
	v_lshlrev_b64 v[34:35], 12, v[32:33]
	v_lshl_add_u64 v[34:35], s[78:79], 0, v[34:35]
	v_lshl_add_u64 v[38:39], v[34:35], 0, v[130:131]
	v_accvgpr_read_b32 v40, a28
	v_accvgpr_read_b32 v41, a29
	v_accvgpr_read_b32 v155, a206
	v_mul_f32_e32 v35, v155, v110
	v_accvgpr_read_b32 v155, a206
	v_mul_f32_e32 v34, v155, v126
	v_exp_f32_e32 v37, v35
	v_exp_f32_e32 v36, v34
	v_cvt_pk_bf16_f32 v35, v62, v63
	v_cvt_pk_bf16_f32 v34, v46, v47
	v_add_f32_e32 v37, 1.0, v37
	v_add_f32_e32 v36, 1.0, v36
	v_rcp_f32_e32 v37, v37
	v_rcp_f32_e32 v36, v36
	v_lshlrev_b32_e32 v43, 16, v35
	v_lshlrev_b32_e32 v42, 16, v34
	v_fmac_f32_e32 v40, v36, v42
	v_fmac_f32_e32 v41, v37, v43
	v_mul_f32_e32 v36, v41, v41
	v_fmac_f32_e32 v36, v40, v40
	global_store_dword v[38:39], v40, off
	global_store_dword v[38:39], v41, off offset:128
	v_add_f32_dpp v36, v36, v36 quad_perm:[1,0,3,2] row_mask:0xf bank_mask:0xf bound_ctrl:1
	s_nop 1
	v_add_f32_dpp v36, v36, v36 quad_perm:[2,3,0,1] row_mask:0xf bank_mask:0xf bound_ctrl:1
	s_nop 1
	v_add_f32_dpp v36, v36, v36 row_half_mirror row_mask:0xf bank_mask:0xf bound_ctrl:1
	s_nop 1
	v_add_f32_dpp v36, v36, v36 row_mirror row_mask:0xf bank_mask:0xf bound_ctrl:1
	v_mov_b32_e32 v37, v36
	s_nop 1
	v_permlane16_swap_b32_e32 v37, v37
	s_and_saveexec_b64 s[8:9], s[4:5]
	s_cbranch_execz .LBB0_1618
	v_add_f32_e32 v36, v36, v37
	v_lshl_add_u64 v[32:33], v[32:33], 2, s[92:93]
	global_atomic_add_f32 v[32:33], v36, off
.LBB0_1618:
	s_or_b64 exec, exec, s[8:9]
	v_or_b32_e32 v32, v48, v153
	v_ashrrev_i32_e32 v33, 31, v32
	v_lshlrev_b64 v[36:37], 12, v[32:33]
	v_lshl_add_u64 v[36:37], s[78:79], 0, v[36:37]
	v_lshl_add_u64 v[36:37], v[36:37], 0, v[130:131]
	v_accvgpr_read_b32 v38, a30
	v_accvgpr_read_b32 v39, a31
	v_accvgpr_read_b32 v155, a207
	v_mul_f32_e32 v41, v155, v111
	v_accvgpr_read_b32 v155, a207
	v_mul_f32_e32 v40, v155, v127
	v_exp_f32_e32 v41, v41
	v_exp_f32_e32 v40, v40
	v_and_b32_e32 v35, 0xffff0000, v35
	v_and_b32_e32 v34, 0xffff0000, v34
	v_add_f32_e32 v41, 1.0, v41
	v_add_f32_e32 v40, 1.0, v40
	v_rcp_f32_e32 v41, v41
	v_rcp_f32_e32 v40, v40
	v_fmac_f32_e32 v39, v41, v35
	v_fmac_f32_e32 v38, v40, v34
	v_mul_f32_e32 v34, v39, v39
	v_fmac_f32_e32 v34, v38, v38
	global_store_dword v[36:37], v38, off
	global_store_dword v[36:37], v39, off offset:128
	v_add_f32_dpp v34, v34, v34 quad_perm:[1,0,3,2] row_mask:0xf bank_mask:0xf bound_ctrl:1
	s_nop 1
	v_add_f32_dpp v34, v34, v34 quad_perm:[2,3,0,1] row_mask:0xf bank_mask:0xf bound_ctrl:1
	s_nop 1
	v_add_f32_dpp v34, v34, v34 row_half_mirror row_mask:0xf bank_mask:0xf bound_ctrl:1
	s_nop 1
	v_add_f32_dpp v34, v34, v34 row_mirror row_mask:0xf bank_mask:0xf bound_ctrl:1
	v_mov_b32_e32 v35, v34
	s_nop 1
	v_permlane16_swap_b32_e32 v35, v35
	s_and_saveexec_b64 s[8:9], s[4:5]
	s_cbranch_execz .LBB0_1620
	v_add_f32_e32 v34, v34, v35
	v_lshl_add_u64 v[32:33], v[32:33], 2, s[92:93]
	global_atomic_add_f32 v[32:33], v34, off
; __device__ __forceinline__ float bflo(unsigned u) { return __uint_as_float(u << 16); }
; __device__ __forceinline__ float bfhi(unsigned u) { return __uint_as_float(u & 0xffff0000u); }
; __device__ __forceinline__ float sum32(float v) { v = dpp_row_sum16(v); v += __shfl_xor(v, 16); return v; }
; __device__ __forceinline__ float sigmoidf_(float x) { return __builtin_amdgcn_rcpf(1.f + __expf(-x)); }
; __device__ __forceinline__ int rowmap(int e, int lane) { return (e & 3) + 8 * (e >> 2) + 4 * (lane >> 5); }
; __device__ __forceinline__ void phase6(const Params& p, char* smem) {
;     ...
;       for (int e = 0; e < 16; e++) {
;         const int row = m0 + wm * 64 + i * 32 + rowmap(e, lane);
;         float sq = 0.f;
; #pragma unroll
;         for (int j = 0; j < 2; j++) {
;           const int col = n0 + wn * 64 + j * 32 + (lane & 31);
;           float* xp = X + (size_t)row * 1024 + col;
;           float v = *xp + ((e & 1) ? bfhi(pe[i][j][e >> 1]) : bflo(pe[i][j][e >> 1])) * sigmoidf_(acc1[i][j][e]);
;           *xp = v;
;           sq += v * v;
;         }
;         sq = sum32(sq);
;         if ((lane & 31) == 0) atomicAdd(&SSQ3[row], sq);
.LBB0_1620:
	s_or_b64 exec, exec, s[8:9]
	v_or_b32_e32 v34, 32, v48
	v_or_b32_e32 v32, v34, v236
	v_ashrrev_i32_e32 v33, 31, v32
	v_lshlrev_b64 v[36:37], 12, v[32:33]
	v_lshl_add_u64 v[36:37], s[78:79], 0, v[36:37]
	v_lshl_add_u64 v[36:37], v[36:37], 0, v[130:131]
	v_accvgpr_read_b32 v38, a32
	v_accvgpr_read_b32 v39, a33
	v_accvgpr_read_b32 v155, a208
	v_mul_f32_e32 v40, v155, v64
	v_accvgpr_read_b32 v155, a208
	v_mul_f32_e32 v35, v155, v80
	v_exp_f32_e32 v40, v40
	v_exp_f32_e32 v41, v35
	v_cvt_pk_bf16_f32 v35, v0, v1
	v_cvt_pk_bf16_f32 v16, v16, v17
	v_add_f32_e32 v1, 1.0, v40
	v_add_f32_e32 v0, 1.0, v41
	v_rcp_f32_e32 v1, v1
	v_rcp_f32_e32 v0, v0
	v_lshlrev_b32_e32 v40, 16, v16
	v_lshlrev_b32_e32 v17, 16, v35
	v_fmac_f32_e32 v38, v0, v17
	v_fmac_f32_e32 v39, v1, v40
	v_mul_f32_e32 v0, v39, v39
	v_fmac_f32_e32 v0, v38, v38
	global_store_dword v[36:37], v38, off
	global_store_dword v[36:37], v39, off offset:128
	v_add_f32_dpp v0, v0, v0 quad_perm:[1,0,3,2] row_mask:0xf bank_mask:0xf bound_ctrl:1
	s_nop 1
	v_add_f32_dpp v0, v0, v0 quad_perm:[2,3,0,1] row_mask:0xf bank_mask:0xf bound_ctrl:1
	s_nop 1
	v_add_f32_dpp v0, v0, v0 row_half_mirror row_mask:0xf bank_mask:0xf bound_ctrl:1
	s_nop 1
	v_add_f32_dpp v0, v0, v0 row_mirror row_mask:0xf bank_mask:0xf bound_ctrl:1
	v_mov_b32_e32 v1, v0
	s_nop 1
	v_permlane16_swap_b32_e32 v1, v1
	s_and_saveexec_b64 s[8:9], s[4:5]
	s_cbranch_execz .LBB0_1622
	v_add_f32_e32 v17, v0, v1
	v_lshl_add_u64 v[0:1], v[32:33], 2, s[92:93]
	global_atomic_add_f32 v[0:1], v17, off
.LBB0_1622:
	s_or_b64 exec, exec, s[8:9]
	v_or_b32_e32 v0, v34, v135
	v_ashrrev_i32_e32 v1, 31, v0
	v_lshlrev_b64 v[32:33], 12, v[0:1]
	v_lshl_add_u64 v[32:33], s[78:79], 0, v[32:33]
	v_lshl_add_u64 v[32:33], v[32:33], 0, v[130:131]
	v_accvgpr_read_b32 v36, a34
	v_accvgpr_read_b32 v37, a35
	v_accvgpr_read_b32 v155, a209
	v_mul_f32_e32 v38, v155, v65
	v_accvgpr_read_b32 v155, a209
	v_mul_f32_e32 v17, v155, v81
	v_exp_f32_e32 v38, v38
	v_exp_f32_e32 v17, v17
	v_and_b32_e32 v16, 0xffff0000, v16
	v_and_b32_e32 v35, 0xffff0000, v35
	v_add_f32_e32 v38, 1.0, v38
	v_add_f32_e32 v17, 1.0, v17
	v_rcp_f32_e32 v38, v38
	v_rcp_f32_e32 v17, v17
	v_fmac_f32_e32 v37, v38, v16
	v_fmac_f32_e32 v36, v17, v35
	v_mul_f32_e32 v16, v37, v37
	v_fmac_f32_e32 v16, v36, v36
	global_store_dword v[32:33], v36, off
	global_store_dword v[32:33], v37, off offset:128
	v_add_f32_dpp v16, v16, v16 quad_perm:[1,0,3,2] row_mask:0xf bank_mask:0xf bound_ctrl:1
	s_nop 1
	v_add_f32_dpp v16, v16, v16 quad_perm:[2,3,0,1] row_mask:0xf bank_mask:0xf bound_ctrl:1
	s_nop 1
	v_add_f32_dpp v16, v16, v16 row_half_mirror row_mask:0xf bank_mask:0xf bound_ctrl:1
	s_nop 1
	v_add_f32_dpp v16, v16, v16 row_mirror row_mask:0xf bank_mask:0xf bound_ctrl:1
	v_mov_b32_e32 v17, v16
	s_nop 1
	v_permlane16_swap_b32_e32 v17, v17
	s_and_saveexec_b64 s[8:9], s[4:5]
	s_cbranch_execz .LBB0_1624
	v_add_f32_e32 v16, v16, v17
	v_lshl_add_u64 v[0:1], v[0:1], 2, s[92:93]
	global_atomic_add_f32 v[0:1], v16, off
.LBB0_1624:
	s_or_b64 exec, exec, s[8:9]
	v_or_b32_e32 v0, v34, v132
	v_ashrrev_i32_e32 v1, 31, v0
	v_lshlrev_b64 v[16:17], 12, v[0:1]
	v_lshl_add_u64 v[16:17], s[78:79], 0, v[16:17]
	v_lshl_add_u64 v[32:33], v[16:17], 0, v[130:131]
	v_accvgpr_read_b32 v35, a36
	v_accvgpr_read_b32 v36, a37
	v_accvgpr_read_b32 v155, a210
	v_mul_f32_e32 v17, v155, v66
	v_accvgpr_read_b32 v155, a210
	v_mul_f32_e32 v16, v155, v82
	v_exp_f32_e32 v17, v17
	v_exp_f32_e32 v16, v16
	v_cvt_pk_bf16_f32 v2, v2, v3
	v_cvt_pk_bf16_f32 v3, v18, v19
	v_add_f32_e32 v17, 1.0, v17
	v_add_f32_e32 v16, 1.0, v16
	v_rcp_f32_e32 v17, v17
	v_rcp_f32_e32 v16, v16
	v_lshlrev_b32_e32 v19, 16, v3
	v_lshlrev_b32_e32 v18, 16, v2
	v_fmac_f32_e32 v35, v16, v18
	v_fmac_f32_e32 v36, v17, v19
	v_mul_f32_e32 v16, v36, v36
	v_fmac_f32_e32 v16, v35, v35
	global_store_dword v[32:33], v35, off
	global_store_dword v[32:33], v36, off offset:128
	v_add_f32_dpp v16, v16, v16 quad_perm:[1,0,3,2] row_mask:0xf bank_mask:0xf bound_ctrl:1
	s_nop 1
	v_add_f32_dpp v16, v16, v16 quad_perm:[2,3,0,1] row_mask:0xf bank_mask:0xf bound_ctrl:1
	s_nop 1
	v_add_f32_dpp v16, v16, v16 row_half_mirror row_mask:0xf bank_mask:0xf bound_ctrl:1
	s_nop 1
	v_add_f32_dpp v16, v16, v16 row_mirror row_mask:0xf bank_mask:0xf bound_ctrl:1
	v_mov_b32_e32 v17, v16
	s_nop 1
	v_permlane16_swap_b32_e32 v17, v17
	s_and_saveexec_b64 s[8:9], s[4:5]
	s_cbranch_execz .LBB0_1626
	v_add_f32_e32 v16, v16, v17
	v_lshl_add_u64 v[0:1], v[0:1], 2, s[92:93]
	global_atomic_add_f32 v[0:1], v16, off
.LBB0_1626:
	s_or_b64 exec, exec, s[8:9]
	v_or_b32_e32 v0, v34, v133
	v_ashrrev_i32_e32 v1, 31, v0
	v_lshlrev_b64 v[16:17], 12, v[0:1]
	v_lshl_add_u64 v[16:17], s[78:79], 0, v[16:17]
	v_lshl_add_u64 v[16:17], v[16:17], 0, v[130:131]
	v_accvgpr_read_b32 v18, a38
	v_accvgpr_read_b32 v19, a39
	v_accvgpr_read_b32 v155, a211
	v_mul_f32_e32 v33, v155, v67
	v_accvgpr_read_b32 v155, a211
	v_mul_f32_e32 v32, v155, v83
	v_exp_f32_e32 v33, v33
	v_exp_f32_e32 v32, v32
	v_and_b32_e32 v3, 0xffff0000, v3
	v_and_b32_e32 v2, 0xffff0000, v2
	v_add_f32_e32 v33, 1.0, v33
	v_add_f32_e32 v32, 1.0, v32
	v_rcp_f32_e32 v33, v33
	v_rcp_f32_e32 v32, v32
	v_fmac_f32_e32 v19, v33, v3
	v_fmac_f32_e32 v18, v32, v2
	v_mul_f32_e32 v2, v19, v19
	v_fmac_f32_e32 v2, v18, v18
	global_store_dword v[16:17], v18, off
	global_store_dword v[16:17], v19, off offset:128
	v_add_f32_dpp v2, v2, v2 quad_perm:[1,0,3,2] row_mask:0xf bank_mask:0xf bound_ctrl:1
	s_nop 1
	v_add_f32_dpp v2, v2, v2 quad_perm:[2,3,0,1] row_mask:0xf bank_mask:0xf bound_ctrl:1
	s_nop 1
	v_add_f32_dpp v2, v2, v2 row_half_mirror row_mask:0xf bank_mask:0xf bound_ctrl:1
	s_nop 1
	v_add_f32_dpp v2, v2, v2 row_mirror row_mask:0xf bank_mask:0xf bound_ctrl:1
	v_mov_b32_e32 v3, v2
	s_nop 1
	v_permlane16_swap_b32_e32 v3, v3
	s_and_saveexec_b64 s[8:9], s[4:5]
	s_cbranch_execz .LBB0_1628
	v_add_f32_e32 v2, v2, v3
	v_lshl_add_u64 v[0:1], v[0:1], 2, s[92:93]
	global_atomic_add_f32 v[0:1], v2, off
; __device__ __forceinline__ float bflo(unsigned u) { return __uint_as_float(u << 16); }
; __device__ __forceinline__ float bfhi(unsigned u) { return __uint_as_float(u & 0xffff0000u); }
; __device__ __forceinline__ float sum32(float v) { v = dpp_row_sum16(v); v += __shfl_xor(v, 16); return v; }
; __device__ __forceinline__ float sigmoidf_(float x) { return __builtin_amdgcn_rcpf(1.f + __expf(-x)); }
; __device__ __forceinline__ int rowmap(int e, int lane) { return (e & 3) + 8 * (e >> 2) + 4 * (lane >> 5); }
; __device__ __forceinline__ void phase6(const Params& p, char* smem) {
;     ...
;       for (int e = 0; e < 16; e++) {
;         const int row = m0 + wm * 64 + i * 32 + rowmap(e, lane);
;         float sq = 0.f;
; #pragma unroll
;         for (int j = 0; j < 2; j++) {
;           const int col = n0 + wn * 64 + j * 32 + (lane & 31);
;           float* xp = X + (size_t)row * 1024 + col;
;           float v = *xp + ((e & 1) ? bfhi(pe[i][j][e >> 1]) : bflo(pe[i][j][e >> 1])) * sigmoidf_(acc1[i][j][e]);
;           *xp = v;
;           sq += v * v;
;         }
;         sq = sum32(sq);
;         if ((lane & 31) == 0) atomicAdd(&SSQ3[row], sq);
.LBB0_1628:
	s_or_b64 exec, exec, s[8:9]
	v_or_b32_e32 v0, v34, v134
	v_ashrrev_i32_e32 v1, 31, v0
	v_lshlrev_b64 v[2:3], 12, v[0:1]
	v_lshl_add_u64 v[2:3], s[78:79], 0, v[2:3]
	v_lshl_add_u64 v[16:17], v[2:3], 0, v[130:131]
	v_accvgpr_read_b32 v18, a40
	v_accvgpr_read_b32 v19, a41
	v_accvgpr_read_b32 v155, a212
	v_mul_f32_e32 v3, v155, v68
	v_accvgpr_read_b32 v155, a212
	v_mul_f32_e32 v2, v155, v84
	v_exp_f32_e32 v33, v3
	v_exp_f32_e32 v32, v2
	v_cvt_pk_bf16_f32 v2, v4, v5
	v_cvt_pk_bf16_f32 v3, v20, v21
	v_add_f32_e32 v5, 1.0, v33
	v_add_f32_e32 v4, 1.0, v32
	v_rcp_f32_e32 v5, v5
	v_rcp_f32_e32 v4, v4
	v_lshlrev_b32_e32 v21, 16, v3
	v_lshlrev_b32_e32 v20, 16, v2
	v_fmac_f32_e32 v18, v4, v20
	v_fmac_f32_e32 v19, v5, v21
	v_mul_f32_e32 v4, v19, v19
	v_fmac_f32_e32 v4, v18, v18
	global_store_dword v[16:17], v18, off
	global_store_dword v[16:17], v19, off offset:128
	v_add_f32_dpp v4, v4, v4 quad_perm:[1,0,3,2] row_mask:0xf bank_mask:0xf bound_ctrl:1
	s_nop 1
	v_add_f32_dpp v4, v4, v4 quad_perm:[2,3,0,1] row_mask:0xf bank_mask:0xf bound_ctrl:1
	s_nop 1
	v_add_f32_dpp v4, v4, v4 row_half_mirror row_mask:0xf bank_mask:0xf bound_ctrl:1
	s_nop 1
	v_add_f32_dpp v4, v4, v4 row_mirror row_mask:0xf bank_mask:0xf bound_ctrl:1
	v_mov_b32_e32 v5, v4
	s_nop 1
	v_permlane16_swap_b32_e32 v5, v5
	s_and_saveexec_b64 s[8:9], s[4:5]
	s_cbranch_execz .LBB0_1630
	v_add_f32_e32 v4, v4, v5
	v_lshl_add_u64 v[0:1], v[0:1], 2, s[92:93]
	global_atomic_add_f32 v[0:1], v4, off
.LBB0_1630:
	s_or_b64 exec, exec, s[8:9]
	v_or_b32_e32 v0, v34, v148
	v_ashrrev_i32_e32 v1, 31, v0
	v_lshlrev_b64 v[4:5], 12, v[0:1]
	v_lshl_add_u64 v[4:5], s[78:79], 0, v[4:5]
	v_lshl_add_u64 v[4:5], v[4:5], 0, v[130:131]
	v_accvgpr_read_b32 v16, a42
	v_accvgpr_read_b32 v17, a43
	v_accvgpr_read_b32 v155, a213
	v_mul_f32_e32 v19, v155, v69
	v_accvgpr_read_b32 v155, a213
	v_mul_f32_e32 v18, v155, v85
	v_exp_f32_e32 v19, v19
	v_exp_f32_e32 v18, v18
	v_and_b32_e32 v3, 0xffff0000, v3
	v_and_b32_e32 v2, 0xffff0000, v2
	v_add_f32_e32 v19, 1.0, v19
	v_add_f32_e32 v18, 1.0, v18
	v_rcp_f32_e32 v19, v19
	v_rcp_f32_e32 v18, v18
	v_fmac_f32_e32 v17, v19, v3
	v_fmac_f32_e32 v16, v18, v2
	v_mul_f32_e32 v2, v17, v17
	v_fmac_f32_e32 v2, v16, v16
	global_store_dword v[4:5], v16, off
	global_store_dword v[4:5], v17, off offset:128
	v_add_f32_dpp v2, v2, v2 quad_perm:[1,0,3,2] row_mask:0xf bank_mask:0xf bound_ctrl:1
	s_nop 1
	v_add_f32_dpp v2, v2, v2 quad_perm:[2,3,0,1] row_mask:0xf bank_mask:0xf bound_ctrl:1
	s_nop 1
	v_add_f32_dpp v2, v2, v2 row_half_mirror row_mask:0xf bank_mask:0xf bound_ctrl:1
	s_nop 1
	v_add_f32_dpp v2, v2, v2 row_mirror row_mask:0xf bank_mask:0xf bound_ctrl:1
	v_mov_b32_e32 v3, v2
	s_nop 1
	v_permlane16_swap_b32_e32 v3, v3
	s_and_saveexec_b64 s[8:9], s[4:5]
	s_cbranch_execz .LBB0_1632
	v_add_f32_e32 v2, v2, v3
	v_lshl_add_u64 v[0:1], v[0:1], 2, s[92:93]
	global_atomic_add_f32 v[0:1], v2, off
.LBB0_1632:
	s_or_b64 exec, exec, s[8:9]
	v_or_b32_e32 v0, v34, v149
	v_ashrrev_i32_e32 v1, 31, v0
	v_lshlrev_b64 v[2:3], 12, v[0:1]
	v_lshl_add_u64 v[2:3], s[78:79], 0, v[2:3]
	v_lshl_add_u64 v[16:17], v[2:3], 0, v[130:131]
	v_accvgpr_read_b32 v18, a44
	v_accvgpr_read_b32 v19, a45
	v_accvgpr_read_b32 v155, a214
	v_mul_f32_e32 v3, v155, v70
	v_accvgpr_read_b32 v155, a214
	v_mul_f32_e32 v2, v155, v86
	v_exp_f32_e32 v5, v3
	v_exp_f32_e32 v4, v2
	v_cvt_pk_bf16_f32 v3, v22, v23
	v_cvt_pk_bf16_f32 v2, v6, v7
	v_add_f32_e32 v5, 1.0, v5
	v_add_f32_e32 v4, 1.0, v4
	v_rcp_f32_e32 v5, v5
	v_rcp_f32_e32 v4, v4
	v_lshlrev_b32_e32 v7, 16, v3
	v_lshlrev_b32_e32 v6, 16, v2
	v_fmac_f32_e32 v18, v4, v6
	v_fmac_f32_e32 v19, v5, v7
	v_mul_f32_e32 v4, v19, v19
	v_fmac_f32_e32 v4, v18, v18
	global_store_dword v[16:17], v18, off
	global_store_dword v[16:17], v19, off offset:128
	v_add_f32_dpp v4, v4, v4 quad_perm:[1,0,3,2] row_mask:0xf bank_mask:0xf bound_ctrl:1
	s_nop 1
	v_add_f32_dpp v4, v4, v4 quad_perm:[2,3,0,1] row_mask:0xf bank_mask:0xf bound_ctrl:1
	s_nop 1
	v_add_f32_dpp v4, v4, v4 row_half_mirror row_mask:0xf bank_mask:0xf bound_ctrl:1
	s_nop 1
	v_add_f32_dpp v4, v4, v4 row_mirror row_mask:0xf bank_mask:0xf bound_ctrl:1
	v_mov_b32_e32 v5, v4
	s_nop 1
	v_permlane16_swap_b32_e32 v5, v5
	s_and_saveexec_b64 s[8:9], s[4:5]
	s_cbranch_execz .LBB0_1634
	v_add_f32_e32 v4, v4, v5
	v_lshl_add_u64 v[0:1], v[0:1], 2, s[92:93]
	global_atomic_add_f32 v[0:1], v4, off
.LBB0_1634:
	s_or_b64 exec, exec, s[8:9]
	v_or_b32_e32 v0, v34, v150
	v_ashrrev_i32_e32 v1, 31, v0
	v_lshlrev_b64 v[4:5], 12, v[0:1]
	v_lshl_add_u64 v[4:5], s[78:79], 0, v[4:5]
	v_lshl_add_u64 v[4:5], v[4:5], 0, v[130:131]
	v_accvgpr_read_b32 v6, a46
	v_accvgpr_read_b32 v7, a47
	v_accvgpr_read_b32 v155, a215
	v_mul_f32_e32 v17, v155, v71
	v_accvgpr_read_b32 v155, a215
	v_mul_f32_e32 v16, v155, v87
	v_exp_f32_e32 v17, v17
	v_exp_f32_e32 v16, v16
	v_and_b32_e32 v3, 0xffff0000, v3
	v_and_b32_e32 v2, 0xffff0000, v2
	v_add_f32_e32 v17, 1.0, v17
	v_add_f32_e32 v16, 1.0, v16
	v_rcp_f32_e32 v17, v17
	v_rcp_f32_e32 v16, v16
	v_fmac_f32_e32 v7, v17, v3
	v_fmac_f32_e32 v6, v16, v2
	v_mul_f32_e32 v2, v7, v7
	v_fmac_f32_e32 v2, v6, v6
	global_store_dword v[4:5], v6, off
	global_store_dword v[4:5], v7, off offset:128
	v_add_f32_dpp v2, v2, v2 quad_perm:[1,0,3,2] row_mask:0xf bank_mask:0xf bound_ctrl:1
	s_nop 1
	v_add_f32_dpp v2, v2, v2 quad_perm:[2,3,0,1] row_mask:0xf bank_mask:0xf bound_ctrl:1
	s_nop 1
	v_add_f32_dpp v2, v2, v2 row_half_mirror row_mask:0xf bank_mask:0xf bound_ctrl:1
	s_nop 1
	v_add_f32_dpp v2, v2, v2 row_mirror row_mask:0xf bank_mask:0xf bound_ctrl:1
	v_mov_b32_e32 v3, v2
	s_nop 1
	v_permlane16_swap_b32_e32 v3, v3
	s_and_saveexec_b64 s[8:9], s[4:5]
	s_cbranch_execz .LBB0_1636
	v_add_f32_e32 v2, v2, v3
	v_lshl_add_u64 v[0:1], v[0:1], 2, s[92:93]
	global_atomic_add_f32 v[0:1], v2, off
; __device__ __forceinline__ float bflo(unsigned u) { return __uint_as_float(u << 16); }
; __device__ __forceinline__ float bfhi(unsigned u) { return __uint_as_float(u & 0xffff0000u); }
; __device__ __forceinline__ float sum32(float v) { v = dpp_row_sum16(v); v += __shfl_xor(v, 16); return v; }
; __device__ __forceinline__ float sigmoidf_(float x) { return __builtin_amdgcn_rcpf(1.f + __expf(-x)); }
; __device__ __forceinline__ int rowmap(int e, int lane) { return (e & 3) + 8 * (e >> 2) + 4 * (lane >> 5); }
; __device__ __forceinline__ void phase6(const Params& p, char* smem) {
;     ...
;       for (int e = 0; e < 16; e++) {
;         const int row = m0 + wm * 64 + i * 32 + rowmap(e, lane);
;         float sq = 0.f;
; #pragma unroll
;         for (int j = 0; j < 2; j++) {
;           const int col = n0 + wn * 64 + j * 32 + (lane & 31);
;           float* xp = X + (size_t)row * 1024 + col;
;           float v = *xp + ((e & 1) ? bfhi(pe[i][j][e >> 1]) : bflo(pe[i][j][e >> 1])) * sigmoidf_(acc1[i][j][e]);
;           *xp = v;
;           sq += v * v;
;         }
;         sq = sum32(sq);
;         if ((lane & 31) == 0) atomicAdd(&SSQ3[row], sq);
.LBB0_1636:
	s_or_b64 exec, exec, s[8:9]
	v_or_b32_e32 v0, v34, v151
	v_ashrrev_i32_e32 v1, 31, v0
	v_lshlrev_b64 v[2:3], 12, v[0:1]
	v_lshl_add_u64 v[2:3], s[78:79], 0, v[2:3]
	v_lshl_add_u64 v[6:7], v[2:3], 0, v[130:131]
	v_accvgpr_read_b32 v16, a48
	v_accvgpr_read_b32 v17, a49
	v_accvgpr_read_b32 v155, a216
	v_mul_f32_e32 v3, v155, v72
	v_accvgpr_read_b32 v155, a216
	v_mul_f32_e32 v2, v155, v88
	v_exp_f32_e32 v5, v3
	v_exp_f32_e32 v4, v2
	v_cvt_pk_bf16_f32 v3, v24, v25
	v_cvt_pk_bf16_f32 v2, v8, v9
	v_add_f32_e32 v5, 1.0, v5
	v_add_f32_e32 v4, 1.0, v4
	v_rcp_f32_e32 v5, v5
	v_rcp_f32_e32 v4, v4
	v_lshlrev_b32_e32 v9, 16, v3
	v_lshlrev_b32_e32 v8, 16, v2
	v_fmac_f32_e32 v16, v4, v8
	v_fmac_f32_e32 v17, v5, v9
	v_mul_f32_e32 v4, v17, v17
	v_fmac_f32_e32 v4, v16, v16
	global_store_dword v[6:7], v16, off
	global_store_dword v[6:7], v17, off offset:128
	v_add_f32_dpp v4, v4, v4 quad_perm:[1,0,3,2] row_mask:0xf bank_mask:0xf bound_ctrl:1
	s_nop 1
	v_add_f32_dpp v4, v4, v4 quad_perm:[2,3,0,1] row_mask:0xf bank_mask:0xf bound_ctrl:1
	s_nop 1
	v_add_f32_dpp v4, v4, v4 row_half_mirror row_mask:0xf bank_mask:0xf bound_ctrl:1
	s_nop 1
	v_add_f32_dpp v4, v4, v4 row_mirror row_mask:0xf bank_mask:0xf bound_ctrl:1
	v_mov_b32_e32 v5, v4
	s_nop 1
	v_permlane16_swap_b32_e32 v5, v5
	s_and_saveexec_b64 s[8:9], s[4:5]
	s_cbranch_execz .LBB0_1638
	v_add_f32_e32 v4, v4, v5
	v_lshl_add_u64 v[0:1], v[0:1], 2, s[92:93]
	global_atomic_add_f32 v[0:1], v4, off
.LBB0_1638:
	s_or_b64 exec, exec, s[8:9]
	v_or_b32_e32 v0, v34, v152
	v_ashrrev_i32_e32 v1, 31, v0
	v_lshlrev_b64 v[4:5], 12, v[0:1]
	v_lshl_add_u64 v[4:5], s[78:79], 0, v[4:5]
	v_lshl_add_u64 v[4:5], v[4:5], 0, v[130:131]
	v_accvgpr_read_b32 v6, a50
	v_accvgpr_read_b32 v7, a51
	v_accvgpr_read_b32 v155, a217
	v_mul_f32_e32 v9, v155, v73
	v_accvgpr_read_b32 v155, a217
	v_mul_f32_e32 v8, v155, v89
	v_exp_f32_e32 v9, v9
	v_exp_f32_e32 v8, v8
	v_and_b32_e32 v3, 0xffff0000, v3
	v_and_b32_e32 v2, 0xffff0000, v2
	v_add_f32_e32 v9, 1.0, v9
	v_add_f32_e32 v8, 1.0, v8
	v_rcp_f32_e32 v9, v9
	v_rcp_f32_e32 v8, v8
	v_fmac_f32_e32 v7, v9, v3
	v_fmac_f32_e32 v6, v8, v2
	v_mul_f32_e32 v2, v7, v7
	v_fmac_f32_e32 v2, v6, v6
	global_store_dword v[4:5], v6, off
	global_store_dword v[4:5], v7, off offset:128
	v_add_f32_dpp v2, v2, v2 quad_perm:[1,0,3,2] row_mask:0xf bank_mask:0xf bound_ctrl:1
	s_nop 1
	v_add_f32_dpp v2, v2, v2 quad_perm:[2,3,0,1] row_mask:0xf bank_mask:0xf bound_ctrl:1
	s_nop 1
	v_add_f32_dpp v2, v2, v2 row_half_mirror row_mask:0xf bank_mask:0xf bound_ctrl:1
	s_nop 1
	v_add_f32_dpp v2, v2, v2 row_mirror row_mask:0xf bank_mask:0xf bound_ctrl:1
	v_mov_b32_e32 v3, v2
	s_nop 1
	v_permlane16_swap_b32_e32 v3, v3
	s_and_saveexec_b64 s[8:9], s[4:5]
	s_cbranch_execz .LBB0_1640
	v_add_f32_e32 v2, v2, v3
	v_lshl_add_u64 v[0:1], v[0:1], 2, s[92:93]
	global_atomic_add_f32 v[0:1], v2, off
.LBB0_1640:
	s_or_b64 exec, exec, s[8:9]
	v_or_b32_e32 v0, v34, v99
	v_ashrrev_i32_e32 v1, 31, v0
	v_lshlrev_b64 v[2:3], 12, v[0:1]
	v_lshl_add_u64 v[2:3], s[78:79], 0, v[2:3]
	v_lshl_add_u64 v[6:7], v[2:3], 0, v[130:131]
	v_accvgpr_read_b32 v8, a52
	v_accvgpr_read_b32 v9, a53
	v_accvgpr_read_b32 v155, a218
	v_mul_f32_e32 v3, v155, v74
	v_accvgpr_read_b32 v155, a218
	v_mul_f32_e32 v2, v155, v90
	v_exp_f32_e32 v5, v3
	v_exp_f32_e32 v4, v2
	v_cvt_pk_bf16_f32 v3, v26, v27
	v_cvt_pk_bf16_f32 v2, v10, v11
	v_add_f32_e32 v5, 1.0, v5
	v_add_f32_e32 v4, 1.0, v4
	v_rcp_f32_e32 v5, v5
	v_rcp_f32_e32 v4, v4
	v_lshlrev_b32_e32 v11, 16, v3
	v_lshlrev_b32_e32 v10, 16, v2
	v_fmac_f32_e32 v8, v4, v10
	v_fmac_f32_e32 v9, v5, v11
	v_mul_f32_e32 v4, v9, v9
	v_fmac_f32_e32 v4, v8, v8
	global_store_dword v[6:7], v8, off
	global_store_dword v[6:7], v9, off offset:128
	v_add_f32_dpp v4, v4, v4 quad_perm:[1,0,3,2] row_mask:0xf bank_mask:0xf bound_ctrl:1
	s_nop 1
	v_add_f32_dpp v4, v4, v4 quad_perm:[2,3,0,1] row_mask:0xf bank_mask:0xf bound_ctrl:1
	s_nop 1
	v_add_f32_dpp v4, v4, v4 row_half_mirror row_mask:0xf bank_mask:0xf bound_ctrl:1
	s_nop 1
	v_add_f32_dpp v4, v4, v4 row_mirror row_mask:0xf bank_mask:0xf bound_ctrl:1
	v_mov_b32_e32 v5, v4
	s_nop 1
	v_permlane16_swap_b32_e32 v5, v5
	s_and_saveexec_b64 s[8:9], s[4:5]
	s_cbranch_execz .LBB0_1642
	v_add_f32_e32 v4, v4, v5
	v_lshl_add_u64 v[0:1], v[0:1], 2, s[92:93]
	global_atomic_add_f32 v[0:1], v4, off
.LBB0_1642:
	s_or_b64 exec, exec, s[8:9]
	v_or_b32_e32 v0, v34, v112
	v_ashrrev_i32_e32 v1, 31, v0
	v_lshlrev_b64 v[4:5], 12, v[0:1]
	v_lshl_add_u64 v[4:5], s[78:79], 0, v[4:5]
	v_lshl_add_u64 v[4:5], v[4:5], 0, v[130:131]
	v_accvgpr_read_b32 v6, a54
	v_accvgpr_read_b32 v7, a55
	v_accvgpr_read_b32 v155, a219
	v_mul_f32_e32 v9, v155, v75
	v_accvgpr_read_b32 v155, a219
	v_mul_f32_e32 v8, v155, v91
	v_exp_f32_e32 v9, v9
	v_exp_f32_e32 v8, v8
	v_and_b32_e32 v3, 0xffff0000, v3
	v_and_b32_e32 v2, 0xffff0000, v2
	v_add_f32_e32 v9, 1.0, v9
	v_add_f32_e32 v8, 1.0, v8
	v_rcp_f32_e32 v9, v9
	v_rcp_f32_e32 v8, v8
	v_fmac_f32_e32 v7, v9, v3
	v_fmac_f32_e32 v6, v8, v2
	v_mul_f32_e32 v2, v7, v7
	v_fmac_f32_e32 v2, v6, v6
	global_store_dword v[4:5], v6, off
	global_store_dword v[4:5], v7, off offset:128
	v_add_f32_dpp v2, v2, v2 quad_perm:[1,0,3,2] row_mask:0xf bank_mask:0xf bound_ctrl:1
	s_nop 1
	v_add_f32_dpp v2, v2, v2 quad_perm:[2,3,0,1] row_mask:0xf bank_mask:0xf bound_ctrl:1
	s_nop 1
	v_add_f32_dpp v2, v2, v2 row_half_mirror row_mask:0xf bank_mask:0xf bound_ctrl:1
	s_nop 1
	v_add_f32_dpp v2, v2, v2 row_mirror row_mask:0xf bank_mask:0xf bound_ctrl:1
	v_mov_b32_e32 v3, v2
	s_nop 1
	v_permlane16_swap_b32_e32 v3, v3
	s_and_saveexec_b64 s[8:9], s[4:5]
	s_cbranch_execz .LBB0_1644
	v_add_f32_e32 v2, v2, v3
	v_lshl_add_u64 v[0:1], v[0:1], 2, s[92:93]
	global_atomic_add_f32 v[0:1], v2, off
; __device__ __forceinline__ float bflo(unsigned u) { return __uint_as_float(u << 16); }
; __device__ __forceinline__ float bfhi(unsigned u) { return __uint_as_float(u & 0xffff0000u); }
; __device__ __forceinline__ float sum32(float v) { v = dpp_row_sum16(v); v += __shfl_xor(v, 16); return v; }
; __device__ __forceinline__ float sigmoidf_(float x) { return __builtin_amdgcn_rcpf(1.f + __expf(-x)); }
; __device__ __forceinline__ int rowmap(int e, int lane) { return (e & 3) + 8 * (e >> 2) + 4 * (lane >> 5); }
; __device__ __forceinline__ void phase6(const Params& p, char* smem) {
;     ...
;       for (int e = 0; e < 16; e++) {
;         const int row = m0 + wm * 64 + i * 32 + rowmap(e, lane);
;         float sq = 0.f;
; #pragma unroll
;         for (int j = 0; j < 2; j++) {
;           const int col = n0 + wn * 64 + j * 32 + (lane & 31);
;           float* xp = X + (size_t)row * 1024 + col;
;           float v = *xp + ((e & 1) ? bfhi(pe[i][j][e >> 1]) : bflo(pe[i][j][e >> 1])) * sigmoidf_(acc1[i][j][e]);
;           *xp = v;
;           sq += v * v;
;         }
;         sq = sum32(sq);
;         if ((lane & 31) == 0) atomicAdd(&SSQ3[row], sq);
.LBB0_1644:
	s_or_b64 exec, exec, s[8:9]
	v_or_b32_e32 v0, v34, v113
	v_ashrrev_i32_e32 v1, 31, v0
	v_lshlrev_b64 v[2:3], 12, v[0:1]
	v_lshl_add_u64 v[2:3], s[78:79], 0, v[2:3]
	v_lshl_add_u64 v[6:7], v[2:3], 0, v[130:131]
	v_accvgpr_read_b32 v8, a56
	v_accvgpr_read_b32 v9, a57
	v_accvgpr_read_b32 v155, a220
	v_mul_f32_e32 v3, v155, v76
	v_accvgpr_read_b32 v155, a220
	v_mul_f32_e32 v2, v155, v92
	v_exp_f32_e32 v5, v3
	v_exp_f32_e32 v4, v2
	v_cvt_pk_bf16_f32 v3, v28, v29
	v_cvt_pk_bf16_f32 v2, v12, v13
	v_add_f32_e32 v5, 1.0, v5
	v_add_f32_e32 v4, 1.0, v4
	v_rcp_f32_e32 v5, v5
	v_rcp_f32_e32 v4, v4
	v_lshlrev_b32_e32 v11, 16, v3
	v_lshlrev_b32_e32 v10, 16, v2
	v_fmac_f32_e32 v8, v4, v10
	v_fmac_f32_e32 v9, v5, v11
	v_mul_f32_e32 v4, v9, v9
	v_fmac_f32_e32 v4, v8, v8
	global_store_dword v[6:7], v8, off
	global_store_dword v[6:7], v9, off offset:128
	v_add_f32_dpp v4, v4, v4 quad_perm:[1,0,3,2] row_mask:0xf bank_mask:0xf bound_ctrl:1
	s_nop 1
	v_add_f32_dpp v4, v4, v4 quad_perm:[2,3,0,1] row_mask:0xf bank_mask:0xf bound_ctrl:1
	s_nop 1
	v_add_f32_dpp v4, v4, v4 row_half_mirror row_mask:0xf bank_mask:0xf bound_ctrl:1
	s_nop 1
	v_add_f32_dpp v4, v4, v4 row_mirror row_mask:0xf bank_mask:0xf bound_ctrl:1
	v_mov_b32_e32 v5, v4
	s_nop 1
	v_permlane16_swap_b32_e32 v5, v5
	s_and_saveexec_b64 s[8:9], s[4:5]
	s_cbranch_execz .LBB0_1646
	v_add_f32_e32 v4, v4, v5
	v_lshl_add_u64 v[0:1], v[0:1], 2, s[92:93]
	global_atomic_add_f32 v[0:1], v4, off
.LBB0_1646:
	s_or_b64 exec, exec, s[8:9]
	v_or_b32_e32 v0, v34, v114
	v_ashrrev_i32_e32 v1, 31, v0
	v_lshlrev_b64 v[4:5], 12, v[0:1]
	v_lshl_add_u64 v[4:5], s[78:79], 0, v[4:5]
	v_lshl_add_u64 v[4:5], v[4:5], 0, v[130:131]
	v_accvgpr_read_b32 v6, a58
	v_accvgpr_read_b32 v7, a59
	v_accvgpr_read_b32 v155, a221
	v_mul_f32_e32 v9, v155, v77
	v_accvgpr_read_b32 v155, a221
	v_mul_f32_e32 v8, v155, v93
	v_exp_f32_e32 v9, v9
	v_exp_f32_e32 v8, v8
	v_and_b32_e32 v3, 0xffff0000, v3
	v_and_b32_e32 v2, 0xffff0000, v2
	v_add_f32_e32 v9, 1.0, v9
	v_add_f32_e32 v8, 1.0, v8
	v_rcp_f32_e32 v9, v9
	v_rcp_f32_e32 v8, v8
	v_fmac_f32_e32 v7, v9, v3
	v_fmac_f32_e32 v6, v8, v2
	v_mul_f32_e32 v2, v7, v7
	v_fmac_f32_e32 v2, v6, v6
	global_store_dword v[4:5], v6, off
	global_store_dword v[4:5], v7, off offset:128
	v_add_f32_dpp v2, v2, v2 quad_perm:[1,0,3,2] row_mask:0xf bank_mask:0xf bound_ctrl:1
	s_nop 1
	v_add_f32_dpp v2, v2, v2 quad_perm:[2,3,0,1] row_mask:0xf bank_mask:0xf bound_ctrl:1
	s_nop 1
	v_add_f32_dpp v2, v2, v2 row_half_mirror row_mask:0xf bank_mask:0xf bound_ctrl:1
	s_nop 1
	v_add_f32_dpp v2, v2, v2 row_mirror row_mask:0xf bank_mask:0xf bound_ctrl:1
	v_mov_b32_e32 v3, v2
	s_nop 1
	v_permlane16_swap_b32_e32 v3, v3
	s_and_saveexec_b64 s[8:9], s[4:5]
	s_cbranch_execz .LBB0_1648
	v_add_f32_e32 v2, v2, v3
	v_lshl_add_u64 v[0:1], v[0:1], 2, s[92:93]
	global_atomic_add_f32 v[0:1], v2, off
.LBB0_1648:
	s_or_b64 exec, exec, s[8:9]
	v_or_b32_e32 v0, v34, v115
	v_ashrrev_i32_e32 v1, 31, v0
	v_lshlrev_b64 v[2:3], 12, v[0:1]
	v_lshl_add_u64 v[2:3], s[78:79], 0, v[2:3]
	v_lshl_add_u64 v[6:7], v[2:3], 0, v[130:131]
	v_accvgpr_read_b32 v8, a60
	v_accvgpr_read_b32 v9, a61
	v_accvgpr_read_b32 v155, a222
	v_mul_f32_e32 v3, v155, v78
	v_accvgpr_read_b32 v155, a222
	v_mul_f32_e32 v2, v155, v94
	v_exp_f32_e32 v5, v3
	v_exp_f32_e32 v4, v2
	v_cvt_pk_bf16_f32 v3, v30, v31
	v_cvt_pk_bf16_f32 v2, v14, v15
	v_add_f32_e32 v5, 1.0, v5
	v_add_f32_e32 v4, 1.0, v4
	v_rcp_f32_e32 v5, v5
	v_rcp_f32_e32 v4, v4
	v_lshlrev_b32_e32 v11, 16, v3
	v_lshlrev_b32_e32 v10, 16, v2
	v_fmac_f32_e32 v8, v4, v10
	v_fmac_f32_e32 v9, v5, v11
	v_mul_f32_e32 v4, v9, v9
	v_fmac_f32_e32 v4, v8, v8
	global_store_dword v[6:7], v8, off
	global_store_dword v[6:7], v9, off offset:128
	v_add_f32_dpp v4, v4, v4 quad_perm:[1,0,3,2] row_mask:0xf bank_mask:0xf bound_ctrl:1
	s_nop 1
	v_add_f32_dpp v4, v4, v4 quad_perm:[2,3,0,1] row_mask:0xf bank_mask:0xf bound_ctrl:1
	s_nop 1
	v_add_f32_dpp v4, v4, v4 row_half_mirror row_mask:0xf bank_mask:0xf bound_ctrl:1
	s_nop 1
	v_add_f32_dpp v4, v4, v4 row_mirror row_mask:0xf bank_mask:0xf bound_ctrl:1
	v_mov_b32_e32 v5, v4
	s_nop 1
	v_permlane16_swap_b32_e32 v5, v5
	s_and_saveexec_b64 s[8:9], s[4:5]
	s_cbranch_execz .LBB0_1650
	v_add_f32_e32 v4, v4, v5
	v_lshl_add_u64 v[0:1], v[0:1], 2, s[92:93]
	global_atomic_add_f32 v[0:1], v4, off
.LBB0_1650:
	s_or_b64 exec, exec, s[8:9]
	v_or_b32_e32 v0, v34, v153
	v_ashrrev_i32_e32 v1, 31, v0
	v_lshlrev_b64 v[4:5], 12, v[0:1]
	v_lshl_add_u64 v[4:5], s[78:79], 0, v[4:5]
	v_lshl_add_u64 v[4:5], v[4:5], 0, v[130:131]
	v_accvgpr_read_b32 v6, a62
	v_accvgpr_read_b32 v7, a63
	v_accvgpr_read_b32 v155, a223
	v_mul_f32_e32 v9, v155, v79
	v_accvgpr_read_b32 v155, a223
	v_mul_f32_e32 v8, v155, v95
	v_exp_f32_e32 v9, v9
	v_exp_f32_e32 v8, v8
	v_and_b32_e32 v3, 0xffff0000, v3
	v_and_b32_e32 v2, 0xffff0000, v2
	v_add_f32_e32 v9, 1.0, v9
	v_add_f32_e32 v8, 1.0, v8
	v_rcp_f32_e32 v9, v9
	v_rcp_f32_e32 v8, v8
	v_fmac_f32_e32 v7, v9, v3
	v_fmac_f32_e32 v6, v8, v2
	v_mul_f32_e32 v2, v7, v7
	v_fmac_f32_e32 v2, v6, v6
	global_store_dword v[4:5], v6, off
	global_store_dword v[4:5], v7, off offset:128
	v_add_f32_dpp v2, v2, v2 quad_perm:[1,0,3,2] row_mask:0xf bank_mask:0xf bound_ctrl:1
	s_nop 1
	v_add_f32_dpp v2, v2, v2 quad_perm:[2,3,0,1] row_mask:0xf bank_mask:0xf bound_ctrl:1
	s_nop 1
	v_add_f32_dpp v2, v2, v2 row_half_mirror row_mask:0xf bank_mask:0xf bound_ctrl:1
	s_nop 1
	v_add_f32_dpp v2, v2, v2 row_mirror row_mask:0xf bank_mask:0xf bound_ctrl:1
	v_mov_b32_e32 v3, v2
	s_nop 1
	v_permlane16_swap_b32_e32 v3, v3
	s_and_saveexec_b64 s[8:9], s[4:5]
	s_cbranch_execz .LBB0_1577
	v_add_f32_e32 v2, v2, v3
	v_lshl_add_u64 v[0:1], v[0:1], 2, s[92:93]
	global_atomic_add_f32 v[0:1], v2, off
	s_branch .LBB0_1577
